# merge: gate loads issued in K-step 1 of each group (was step 3)
# baseline (speedup 1.0000x reference)
.LBB0_1004:
	v_and_b32_e32 v2, 7, v192
	v_lshrrev_b32_e32 v3, 3, v192
	v_bfe_u32 v4, v192, 4, 3
	v_xor_b32_e32 v2, v2, v4
	v_lshlrev_b32_e32 v2, 4, v2
	v_mul_u32_u24_e32 v4, 0x3e00, v3
	v_add_u32_e32 v188, v4, v2
	v_add_u32_e32 v189, 0xf8000, v188
	v_add_u32_e32 v190, 0x1f0000, v188
	v_add_u32_e32 v191, 0x2e8000, v188
	v_and_b32_e32 v4, 35, v3
	v_bfe_u32 v5, v3, 4, 1
	v_lshl_or_b32 v4, v5, 2, v4
	v_bfe_u32 v5, v3, 2, 2
	v_lshl_or_b32 v4, v5, 3, v4
	v_lshl_or_b32 v205, v4, 10, v2
	v_add_u32_e32 v206, 0x10000, v205
	v_bfe_u32 v2, v192, 1, 3
	v_bfe_u32 v3, v192, 4, 2
	v_xor_b32_e32 v2, v2, v3
	v_lshlrev_b32_e32 v2, 4, v2
	v_and_b32_e32 v3, 15, v192
	v_lshrrev_b32_e32 v4, 7, v192
	v_lshl_or_b32 v4, v4, 6, v3
	v_lshl_or_b32 v207, v4, 7, v2
	v_xor_b32_e32 v119, 64, v207
	v_add_u32_e32 v0, 0x10000, v207
	v_add_u32_e32 v255, 0x10000, v119
	v_bfe_u32 v4, v192, 6, 1
	v_lshl_or_b32 v4, v4, 6, v3
	v_lshl_or_b32 v4, v4, 7, v2
	v_add_u32_e32 v90, 0x18000, v4
	v_xor_b32_e32 v91, 64, v90
	v_lshrrev_b32_e32 v5, 6, v192
	s_nop 0
	v_readfirstlane_b32 s67, v5
	s_lshl_b32 s67, s67, 10
	s_add_u32 s80, s46, 0xc00
	s_addc_u32 s81, s47, 0
	s_mov_b32 s96, s48
	s_mov_b32 s97, s49
	v_lshrrev_b32_e32 v2, 4, v192
	v_mul_u32_u24_e32 v2, 0x3e00, v2
	v_and_b32_e32 v3, 15, v192
	v_lshl_or_b32 v93, v3, 6, v2
	s_lshr_b32 s32, s13, 17
	s_mul_i32 s32, s32, 0x7c000
	s_add_u32 s86, s46, s32
	s_addc_u32 s87, s47, 0
	s_add_u32 s98, s86, 0x1000
	s_addc_u32 s99, s87, 0
	global_load_dword v92, v93, s[98:99]
	s_add_i32 m0, s67, 0x0
	s_nop 0
	global_load_lds_dwordx4 v188, s[80:81]
	s_add_i32 m0, s67, 0x2000
	s_nop 0
	global_load_lds_dwordx4 v189, s[80:81]
	s_add_i32 m0, s67, 0x4000
	s_nop 0
	global_load_lds_dwordx4 v190, s[80:81]
	s_add_i32 m0, s67, 0x6000
	s_nop 0
	global_load_lds_dwordx4 v191, s[80:81]
	s_add_i32 m0, s67, 0x18000
	s_nop 0
	global_load_lds_dwordx4 v205, s[96:97]
	s_add_i32 m0, s67, 0x1a000
	s_nop 0
	global_load_lds_dwordx4 v206, s[96:97]
	s_add_u32 s80, s80, 0x80
	s_addc_u32 s81, s81, 0
	s_add_u32 s96, s96, 0x80
	s_addc_u32 s97, s97, 0
	s_add_i32 m0, s67, 0x8000
	s_nop 0
	global_load_lds_dwordx4 v188, s[80:81]
	s_add_i32 m0, s67, 0xa000
	s_nop 0
	global_load_lds_dwordx4 v189, s[80:81]
	s_add_i32 m0, s67, 0xc000
	s_nop 0
	global_load_lds_dwordx4 v190, s[80:81]
	s_add_i32 m0, s67, 0xe000
	s_nop 0
	global_load_lds_dwordx4 v191, s[80:81]
	s_add_i32 m0, s67, 0x1c000
	s_nop 0
	global_load_lds_dwordx4 v205, s[96:97]
	s_add_i32 m0, s67, 0x1e000
	s_nop 0
	global_load_lds_dwordx4 v206, s[96:97]
	s_add_u32 s80, s80, 0x80
	s_addc_u32 s81, s81, 0
	s_add_u32 s96, s96, 0x80
	s_addc_u32 s97, s97, 0
	s_add_i32 m0, s67, 0x10000
	s_nop 0
	global_load_lds_dwordx4 v188, s[80:81]
	s_add_i32 m0, s67, 0x12000
	s_nop 0
	global_load_lds_dwordx4 v189, s[80:81]
	s_add_i32 m0, s67, 0x14000
	s_nop 0
	global_load_lds_dwordx4 v190, s[80:81]
	s_add_i32 m0, s67, 0x16000
	s_nop 0
	global_load_lds_dwordx4 v191, s[80:81]
	s_add_i32 m0, s67, 0x20400
	s_nop 0
	global_load_lds_dwordx4 v205, s[96:97]
	s_add_i32 m0, s67, 0x22400
	s_nop 0
	global_load_lds_dwordx4 v206, s[96:97]
	s_add_u32 s80, s80, 0x80
	s_addc_u32 s81, s81, 0
	s_add_u32 s96, s96, 0x80
	s_addc_u32 s97, s97, 0
	s_waitcnt vmcnt(12)
	s_barrier
	ds_read_b128 v[82:85], v90 offset:0
	ds_read_b128 v[86:89], v90 offset:2048
	ds_read_b128 v[208:211], v90 offset:4096
	ds_read_b128 v[212:215], v90 offset:6144
	ds_read_b128 v[66:69], v207 offset:0
	ds_read_b128 v[70:73], v207 offset:2048
	ds_read_b128 v[74:77], v207 offset:4096
	ds_read_b128 v[78:81], v207 offset:6144
	ds_read_b128 v[216:219], v91 offset:0
	ds_read_b128 v[220:223], v91 offset:2048
	ds_read_b128 v[224:227], v91 offset:4096
	ds_read_b128 v[228:231], v91 offset:6144
	s_waitcnt lgkmcnt(7)
	v_mfma_f32_16x16x32_bf16 v[6:9], v[82:85], v[66:69], 0
	v_mfma_f32_16x16x32_bf16 v[30:33], v[86:89], v[66:69], 0
	v_mfma_f32_16x16x32_bf16 v[38:41], v[208:211], v[66:69], 0
	v_mfma_f32_16x16x32_bf16 v[42:45], v[212:215], v[66:69], 0
	ds_read_b128 v[66:69], v119 offset:0
	s_waitcnt lgkmcnt(7)
	v_mfma_f32_16x16x32_bf16 v[46:49], v[82:85], v[70:73], 0
	v_mfma_f32_16x16x32_bf16 v[26:29], v[86:89], v[70:73], 0
	v_mfma_f32_16x16x32_bf16 v[14:17], v[208:211], v[70:73], 0
	v_mfma_f32_16x16x32_bf16 v[10:13], v[212:215], v[70:73], 0
	ds_read_b128 v[70:73], v119 offset:2048
	s_waitcnt lgkmcnt(7)
	v_mfma_f32_16x16x32_bf16 v[34:37], v[82:85], v[74:77], 0
	v_mfma_f32_16x16x32_bf16 v[22:25], v[86:89], v[74:77], 0
	v_mfma_f32_16x16x32_bf16 v[18:21], v[208:211], v[74:77], 0
	v_mfma_f32_16x16x32_bf16 v[62:65], v[212:215], v[74:77], 0
	ds_read_b128 v[74:77], v119 offset:4096
	s_waitcnt lgkmcnt(7)
	v_mfma_f32_16x16x32_bf16 v[58:61], v[82:85], v[78:81], 0
	v_mfma_f32_16x16x32_bf16 v[54:57], v[86:89], v[78:81], 0
	v_mfma_f32_16x16x32_bf16 v[50:53], v[208:211], v[78:81], 0
	v_mfma_f32_16x16x32_bf16 v[2:5], v[212:215], v[78:81], 0
	ds_read_b128 v[78:81], v119 offset:6144
	s_waitcnt lgkmcnt(3)
	v_mfma_f32_16x16x32_bf16 v[6:9], v[216:219], v[66:69], v[6:9]
	v_mfma_f32_16x16x32_bf16 v[30:33], v[220:223], v[66:69], v[30:33]
	v_mfma_f32_16x16x32_bf16 v[38:41], v[224:227], v[66:69], v[38:41]
	v_mfma_f32_16x16x32_bf16 v[42:45], v[228:231], v[66:69], v[42:45]
	s_waitcnt lgkmcnt(2)
	v_mfma_f32_16x16x32_bf16 v[46:49], v[216:219], v[70:73], v[46:49]
	v_mfma_f32_16x16x32_bf16 v[26:29], v[220:223], v[70:73], v[26:29]
	v_mfma_f32_16x16x32_bf16 v[14:17], v[224:227], v[70:73], v[14:17]
	v_mfma_f32_16x16x32_bf16 v[10:13], v[228:231], v[70:73], v[10:13]
	s_waitcnt vmcnt(6)
	s_waitcnt lgkmcnt(0)
	s_barrier
	s_add_i32 m0, s67, 0x0
	s_nop 0
	global_load_lds_dwordx4 v188, s[80:81]
	s_add_i32 m0, s67, 0x2000
	s_nop 0
	global_load_lds_dwordx4 v189, s[80:81]
	s_add_i32 m0, s67, 0x4000
	s_nop 0
	global_load_lds_dwordx4 v190, s[80:81]
	s_add_i32 m0, s67, 0x6000
	s_nop 0
	global_load_lds_dwordx4 v191, s[80:81]
	s_add_i32 m0, s67, 0x18000
	s_nop 0
	global_load_lds_dwordx4 v205, s[96:97]
	s_add_i32 m0, s67, 0x1a000
	s_nop 0
	global_load_lds_dwordx4 v206, s[96:97]
	s_add_u32 s80, s80, 0x80
	s_addc_u32 s81, s81, 0
	s_add_u32 s96, s96, 0x80
	s_addc_u32 s97, s97, 0
	ds_read_b128 v[82:85], v90 offset:16384
	ds_read_b128 v[86:89], v90 offset:18432
	ds_read_b128 v[208:211], v90 offset:20480
	ds_read_b128 v[212:215], v90 offset:22528
	ds_read_b128 v[66:69], v207 offset:32768
	ds_read_b128 v[70:73], v207 offset:34816
	v_mfma_f32_16x16x32_bf16 v[34:37], v[216:219], v[74:77], v[34:37]
	v_mfma_f32_16x16x32_bf16 v[22:25], v[220:223], v[74:77], v[22:25]
	v_mfma_f32_16x16x32_bf16 v[18:21], v[224:227], v[74:77], v[18:21]
	v_mfma_f32_16x16x32_bf16 v[62:65], v[228:231], v[74:77], v[62:65]
	ds_read_b128 v[74:77], v207 offset:36864
	v_mfma_f32_16x16x32_bf16 v[58:61], v[216:219], v[78:81], v[58:61]
	v_mfma_f32_16x16x32_bf16 v[54:57], v[220:223], v[78:81], v[54:57]
	v_mfma_f32_16x16x32_bf16 v[50:53], v[224:227], v[78:81], v[50:53]
	v_mfma_f32_16x16x32_bf16 v[2:5], v[228:231], v[78:81], v[2:5]
	ds_read_b128 v[78:81], v207 offset:38912
	ds_read_b128 v[216:219], v91 offset:16384
	ds_read_b128 v[220:223], v91 offset:18432
	ds_read_b128 v[224:227], v91 offset:20480
	ds_read_b128 v[228:231], v91 offset:22528
	s_waitcnt lgkmcnt(7)
	v_mfma_f32_16x16x32_bf16 v[6:9], v[82:85], v[66:69], v[6:9]
	v_mfma_f32_16x16x32_bf16 v[30:33], v[86:89], v[66:69], v[30:33]
	v_mfma_f32_16x16x32_bf16 v[38:41], v[208:211], v[66:69], v[38:41]
	v_mfma_f32_16x16x32_bf16 v[42:45], v[212:215], v[66:69], v[42:45]
	ds_read_b128 v[66:69], v119 offset:32768
	s_waitcnt lgkmcnt(7)
	v_mfma_f32_16x16x32_bf16 v[46:49], v[82:85], v[70:73], v[46:49]
	v_mfma_f32_16x16x32_bf16 v[26:29], v[86:89], v[70:73], v[26:29]
	v_mfma_f32_16x16x32_bf16 v[14:17], v[208:211], v[70:73], v[14:17]
	v_mfma_f32_16x16x32_bf16 v[10:13], v[212:215], v[70:73], v[10:13]
	ds_read_b128 v[70:73], v119 offset:34816
	s_waitcnt lgkmcnt(7)
	v_mfma_f32_16x16x32_bf16 v[34:37], v[82:85], v[74:77], v[34:37]
	v_mfma_f32_16x16x32_bf16 v[22:25], v[86:89], v[74:77], v[22:25]
	v_mfma_f32_16x16x32_bf16 v[18:21], v[208:211], v[74:77], v[18:21]
	v_mfma_f32_16x16x32_bf16 v[62:65], v[212:215], v[74:77], v[62:65]
	ds_read_b128 v[74:77], v119 offset:36864
	s_waitcnt lgkmcnt(7)
	v_mfma_f32_16x16x32_bf16 v[58:61], v[82:85], v[78:81], v[58:61]
	v_mfma_f32_16x16x32_bf16 v[54:57], v[86:89], v[78:81], v[54:57]
	v_mfma_f32_16x16x32_bf16 v[50:53], v[208:211], v[78:81], v[50:53]
	v_mfma_f32_16x16x32_bf16 v[2:5], v[212:215], v[78:81], v[2:5]
	ds_read_b128 v[78:81], v119 offset:38912
	s_waitcnt lgkmcnt(3)
	v_mfma_f32_16x16x32_bf16 v[6:9], v[216:219], v[66:69], v[6:9]
	v_mfma_f32_16x16x32_bf16 v[30:33], v[220:223], v[66:69], v[30:33]
	v_mfma_f32_16x16x32_bf16 v[38:41], v[224:227], v[66:69], v[38:41]
	v_mfma_f32_16x16x32_bf16 v[42:45], v[228:231], v[66:69], v[42:45]
	s_waitcnt lgkmcnt(2)
	v_mfma_f32_16x16x32_bf16 v[46:49], v[216:219], v[70:73], v[46:49]
	v_mfma_f32_16x16x32_bf16 v[26:29], v[220:223], v[70:73], v[26:29]
	v_mfma_f32_16x16x32_bf16 v[14:17], v[224:227], v[70:73], v[14:17]
	v_mfma_f32_16x16x32_bf16 v[10:13], v[228:231], v[70:73], v[10:13]
	s_waitcnt vmcnt(6)
	s_waitcnt lgkmcnt(0)
	s_barrier
	s_add_i32 m0, s67, 0x8000
	s_nop 0
	global_load_lds_dwordx4 v188, s[80:81]
	s_add_i32 m0, s67, 0xa000
	s_nop 0
	global_load_lds_dwordx4 v189, s[80:81]
	s_add_i32 m0, s67, 0xc000
	s_nop 0
	global_load_lds_dwordx4 v190, s[80:81]
	s_add_i32 m0, s67, 0xe000
	s_nop 0
	global_load_lds_dwordx4 v191, s[80:81]
	s_add_i32 m0, s67, 0x1c000
	s_nop 0
	global_load_lds_dwordx4 v205, s[96:97]
	s_add_i32 m0, s67, 0x1e000
	s_nop 0
	global_load_lds_dwordx4 v206, s[96:97]
	s_add_u32 s80, s80, 0x80
	s_addc_u32 s81, s81, 0
	s_add_u32 s96, s96, 0x80
	s_addc_u32 s97, s97, 0
	s_movk_i32 s10, 0x0
	s_mov_b32 s11, 0
	v_lshl_add_u64 v[248:249], v[128:129], 0, s[10:11]
	global_load_dwordx2 v[232:233], v[248:249], off
	global_load_dwordx2 v[234:235], v[248:249], off offset:32
	v_lshl_add_u64 v[248:249], v[132:133], 0, s[10:11]
	global_load_dwordx2 v[236:237], v[248:249], off
	global_load_dwordx2 v[238:239], v[248:249], off offset:32
	v_lshl_add_u64 v[248:249], v[152:153], 0, s[10:11]
	global_load_dwordx2 v[240:241], v[248:249], off
	global_load_dwordx2 v[242:243], v[248:249], off offset:32
	v_lshl_add_u64 v[248:249], v[154:155], 0, s[10:11]
	global_load_dwordx2 v[244:245], v[248:249], off
	global_load_dwordx2 v[246:247], v[248:249], off offset:32
	ds_read_b128 v[82:85], v90 offset:33792
	ds_read_b128 v[86:89], v90 offset:35840
	ds_read_b128 v[208:211], v90 offset:37888
	ds_read_b128 v[212:215], v90 offset:39936
	ds_read_b128 v[66:69], v0 offset:0
	ds_read_b128 v[70:73], v0 offset:2048
	v_mfma_f32_16x16x32_bf16 v[34:37], v[216:219], v[74:77], v[34:37]
	v_mfma_f32_16x16x32_bf16 v[22:25], v[220:223], v[74:77], v[22:25]
	v_mfma_f32_16x16x32_bf16 v[18:21], v[224:227], v[74:77], v[18:21]
	v_mfma_f32_16x16x32_bf16 v[62:65], v[228:231], v[74:77], v[62:65]
	ds_read_b128 v[74:77], v0 offset:4096
	v_mfma_f32_16x16x32_bf16 v[58:61], v[216:219], v[78:81], v[58:61]
	v_mfma_f32_16x16x32_bf16 v[54:57], v[220:223], v[78:81], v[54:57]
	v_mfma_f32_16x16x32_bf16 v[50:53], v[224:227], v[78:81], v[50:53]
	v_mfma_f32_16x16x32_bf16 v[2:5], v[228:231], v[78:81], v[2:5]
	ds_read_b128 v[78:81], v0 offset:6144
	ds_read_b128 v[216:219], v91 offset:33792
	ds_read_b128 v[220:223], v91 offset:35840
	ds_read_b128 v[224:227], v91 offset:37888
	ds_read_b128 v[228:231], v91 offset:39936
	s_waitcnt lgkmcnt(7)
	v_mfma_f32_16x16x32_bf16 v[6:9], v[82:85], v[66:69], v[6:9]
	v_mfma_f32_16x16x32_bf16 v[30:33], v[86:89], v[66:69], v[30:33]
	v_mfma_f32_16x16x32_bf16 v[38:41], v[208:211], v[66:69], v[38:41]
	v_mfma_f32_16x16x32_bf16 v[42:45], v[212:215], v[66:69], v[42:45]
	ds_read_b128 v[66:69], v255 offset:0
	s_waitcnt lgkmcnt(7)
	v_mfma_f32_16x16x32_bf16 v[46:49], v[82:85], v[70:73], v[46:49]
	v_mfma_f32_16x16x32_bf16 v[26:29], v[86:89], v[70:73], v[26:29]
	v_mfma_f32_16x16x32_bf16 v[14:17], v[208:211], v[70:73], v[14:17]
	v_mfma_f32_16x16x32_bf16 v[10:13], v[212:215], v[70:73], v[10:13]
	ds_read_b128 v[70:73], v255 offset:2048
	s_waitcnt lgkmcnt(7)
	v_mfma_f32_16x16x32_bf16 v[34:37], v[82:85], v[74:77], v[34:37]
	v_mfma_f32_16x16x32_bf16 v[22:25], v[86:89], v[74:77], v[22:25]
	v_mfma_f32_16x16x32_bf16 v[18:21], v[208:211], v[74:77], v[18:21]
	v_mfma_f32_16x16x32_bf16 v[62:65], v[212:215], v[74:77], v[62:65]
	ds_read_b128 v[74:77], v255 offset:4096
	s_waitcnt lgkmcnt(7)
	v_mfma_f32_16x16x32_bf16 v[58:61], v[82:85], v[78:81], v[58:61]
	v_mfma_f32_16x16x32_bf16 v[54:57], v[86:89], v[78:81], v[54:57]
	v_mfma_f32_16x16x32_bf16 v[50:53], v[208:211], v[78:81], v[50:53]
	v_mfma_f32_16x16x32_bf16 v[2:5], v[212:215], v[78:81], v[2:5]
	ds_read_b128 v[78:81], v255 offset:6144
	s_waitcnt lgkmcnt(3)
	v_mfma_f32_16x16x32_bf16 v[6:9], v[216:219], v[66:69], v[6:9]
	v_mfma_f32_16x16x32_bf16 v[30:33], v[220:223], v[66:69], v[30:33]
	v_mfma_f32_16x16x32_bf16 v[38:41], v[224:227], v[66:69], v[38:41]
	v_mfma_f32_16x16x32_bf16 v[42:45], v[228:231], v[66:69], v[42:45]
	s_waitcnt lgkmcnt(2)
	v_mfma_f32_16x16x32_bf16 v[46:49], v[216:219], v[70:73], v[46:49]
	v_mfma_f32_16x16x32_bf16 v[26:29], v[220:223], v[70:73], v[26:29]
	v_mfma_f32_16x16x32_bf16 v[14:17], v[224:227], v[70:73], v[14:17]
	v_mfma_f32_16x16x32_bf16 v[10:13], v[228:231], v[70:73], v[10:13]
	s_waitcnt vmcnt(14)
	s_waitcnt lgkmcnt(0)
	s_barrier
	s_add_i32 m0, s67, 0x10000
	s_nop 0
	global_load_lds_dwordx4 v188, s[80:81]
	s_add_i32 m0, s67, 0x12000
	s_nop 0
	global_load_lds_dwordx4 v189, s[80:81]
	s_add_i32 m0, s67, 0x14000
	s_nop 0
	global_load_lds_dwordx4 v190, s[80:81]
	s_add_i32 m0, s67, 0x16000
	s_nop 0
	global_load_lds_dwordx4 v191, s[80:81]
	s_add_i32 m0, s67, 0x20400
	s_nop 0
	global_load_lds_dwordx4 v205, s[96:97]
	s_add_i32 m0, s67, 0x22400
	s_nop 0
	global_load_lds_dwordx4 v206, s[96:97]
	s_add_u32 s80, s80, 0x80
	s_addc_u32 s81, s81, 0
	s_add_u32 s96, s96, 0x80
	s_addc_u32 s97, s97, 0
	ds_read_b128 v[82:85], v90 offset:0
	ds_read_b128 v[86:89], v90 offset:2048
	ds_read_b128 v[208:211], v90 offset:4096
	ds_read_b128 v[212:215], v90 offset:6144
	ds_read_b128 v[66:69], v207 offset:0
	ds_read_b128 v[70:73], v207 offset:2048
	v_mfma_f32_16x16x32_bf16 v[34:37], v[216:219], v[74:77], v[34:37]
	v_mfma_f32_16x16x32_bf16 v[22:25], v[220:223], v[74:77], v[22:25]
	v_mfma_f32_16x16x32_bf16 v[18:21], v[224:227], v[74:77], v[18:21]
	v_mfma_f32_16x16x32_bf16 v[62:65], v[228:231], v[74:77], v[62:65]
	ds_read_b128 v[74:77], v207 offset:4096
	v_mfma_f32_16x16x32_bf16 v[58:61], v[216:219], v[78:81], v[58:61]
	v_mfma_f32_16x16x32_bf16 v[54:57], v[220:223], v[78:81], v[54:57]
	v_mfma_f32_16x16x32_bf16 v[50:53], v[224:227], v[78:81], v[50:53]
	v_mfma_f32_16x16x32_bf16 v[2:5], v[228:231], v[78:81], v[2:5]
	ds_read_b128 v[78:81], v207 offset:6144
	ds_read_b128 v[216:219], v91 offset:0
	ds_read_b128 v[220:223], v91 offset:2048
	ds_read_b128 v[224:227], v91 offset:4096
	ds_read_b128 v[228:231], v91 offset:6144
	s_waitcnt lgkmcnt(7)
	v_mfma_f32_16x16x32_bf16 v[6:9], v[82:85], v[66:69], v[6:9]
	v_mfma_f32_16x16x32_bf16 v[30:33], v[86:89], v[66:69], v[30:33]
	v_mfma_f32_16x16x32_bf16 v[38:41], v[208:211], v[66:69], v[38:41]
	v_mfma_f32_16x16x32_bf16 v[42:45], v[212:215], v[66:69], v[42:45]
	ds_read_b128 v[66:69], v119 offset:0
	s_waitcnt lgkmcnt(7)
	v_mfma_f32_16x16x32_bf16 v[46:49], v[82:85], v[70:73], v[46:49]
	v_mfma_f32_16x16x32_bf16 v[26:29], v[86:89], v[70:73], v[26:29]
	v_mfma_f32_16x16x32_bf16 v[14:17], v[208:211], v[70:73], v[14:17]
	v_mfma_f32_16x16x32_bf16 v[10:13], v[212:215], v[70:73], v[10:13]
	ds_read_b128 v[70:73], v119 offset:2048
	s_waitcnt lgkmcnt(7)
	v_mfma_f32_16x16x32_bf16 v[34:37], v[82:85], v[74:77], v[34:37]
	v_mfma_f32_16x16x32_bf16 v[22:25], v[86:89], v[74:77], v[22:25]
	v_mfma_f32_16x16x32_bf16 v[18:21], v[208:211], v[74:77], v[18:21]
	v_mfma_f32_16x16x32_bf16 v[62:65], v[212:215], v[74:77], v[62:65]
	ds_read_b128 v[74:77], v119 offset:4096
	s_waitcnt lgkmcnt(7)
	v_mfma_f32_16x16x32_bf16 v[58:61], v[82:85], v[78:81], v[58:61]
	v_mfma_f32_16x16x32_bf16 v[54:57], v[86:89], v[78:81], v[54:57]
	v_mfma_f32_16x16x32_bf16 v[50:53], v[208:211], v[78:81], v[50:53]
	v_mfma_f32_16x16x32_bf16 v[2:5], v[212:215], v[78:81], v[2:5]
	ds_read_b128 v[78:81], v119 offset:6144
	s_waitcnt lgkmcnt(3)
	v_mfma_f32_16x16x32_bf16 v[6:9], v[216:219], v[66:69], v[6:9]
	v_mfma_f32_16x16x32_bf16 v[30:33], v[220:223], v[66:69], v[30:33]
	v_mfma_f32_16x16x32_bf16 v[38:41], v[224:227], v[66:69], v[38:41]
	v_mfma_f32_16x16x32_bf16 v[42:45], v[228:231], v[66:69], v[42:45]
	s_waitcnt lgkmcnt(2)
	v_mfma_f32_16x16x32_bf16 v[46:49], v[216:219], v[70:73], v[46:49]
	v_mfma_f32_16x16x32_bf16 v[26:29], v[220:223], v[70:73], v[26:29]
	v_mfma_f32_16x16x32_bf16 v[14:17], v[224:227], v[70:73], v[14:17]
	v_mfma_f32_16x16x32_bf16 v[10:13], v[228:231], v[70:73], v[10:13]
	s_waitcnt vmcnt(14)
	s_waitcnt lgkmcnt(0)
	s_barrier
	s_add_i32 m0, s67, 0x0
	s_nop 0
	global_load_lds_dwordx4 v188, s[80:81]
	s_add_i32 m0, s67, 0x2000
	s_nop 0
	global_load_lds_dwordx4 v189, s[80:81]
	s_add_i32 m0, s67, 0x4000
	s_nop 0
	global_load_lds_dwordx4 v190, s[80:81]
	s_add_i32 m0, s67, 0x6000
	s_nop 0
	global_load_lds_dwordx4 v191, s[80:81]
	s_add_i32 m0, s67, 0x18000
	s_nop 0
	global_load_lds_dwordx4 v205, s[96:97]
	s_add_i32 m0, s67, 0x1a000
	s_nop 0
	global_load_lds_dwordx4 v206, s[96:97]
	s_add_u32 s80, s80, 0x80
	s_addc_u32 s81, s81, 0
	s_add_u32 s96, s96, 0x80
	s_addc_u32 s97, s97, 0
	ds_read_b128 v[82:85], v90 offset:16384
	ds_read_b128 v[86:89], v90 offset:18432
	ds_read_b128 v[208:211], v90 offset:20480
	ds_read_b128 v[212:215], v90 offset:22528
	ds_read_b128 v[66:69], v207 offset:32768
	ds_read_b128 v[70:73], v207 offset:34816
	v_mfma_f32_16x16x32_bf16 v[34:37], v[216:219], v[74:77], v[34:37]
	v_mfma_f32_16x16x32_bf16 v[22:25], v[220:223], v[74:77], v[22:25]
	v_mfma_f32_16x16x32_bf16 v[18:21], v[224:227], v[74:77], v[18:21]
	v_mfma_f32_16x16x32_bf16 v[62:65], v[228:231], v[74:77], v[62:65]
	ds_read_b128 v[74:77], v207 offset:36864
	v_mfma_f32_16x16x32_bf16 v[58:61], v[216:219], v[78:81], v[58:61]
	v_mfma_f32_16x16x32_bf16 v[54:57], v[220:223], v[78:81], v[54:57]
	v_mfma_f32_16x16x32_bf16 v[50:53], v[224:227], v[78:81], v[50:53]
	v_mfma_f32_16x16x32_bf16 v[2:5], v[228:231], v[78:81], v[2:5]
	ds_read_b128 v[78:81], v207 offset:38912
	ds_read_b128 v[216:219], v91 offset:16384
	ds_read_b128 v[220:223], v91 offset:18432
	ds_read_b128 v[224:227], v91 offset:20480
	ds_read_b128 v[228:231], v91 offset:22528
	s_waitcnt lgkmcnt(7)
	v_mfma_f32_16x16x32_bf16 v[6:9], v[82:85], v[66:69], v[6:9]
	v_mfma_f32_16x16x32_bf16 v[30:33], v[86:89], v[66:69], v[30:33]
	v_mfma_f32_16x16x32_bf16 v[38:41], v[208:211], v[66:69], v[38:41]
	v_mfma_f32_16x16x32_bf16 v[42:45], v[212:215], v[66:69], v[42:45]
	ds_read_b128 v[66:69], v119 offset:32768
	s_waitcnt lgkmcnt(7)
	v_mfma_f32_16x16x32_bf16 v[46:49], v[82:85], v[70:73], v[46:49]
	v_mfma_f32_16x16x32_bf16 v[26:29], v[86:89], v[70:73], v[26:29]
	v_mfma_f32_16x16x32_bf16 v[14:17], v[208:211], v[70:73], v[14:17]
	v_mfma_f32_16x16x32_bf16 v[10:13], v[212:215], v[70:73], v[10:13]
	ds_read_b128 v[70:73], v119 offset:34816
	s_waitcnt lgkmcnt(7)
	v_mfma_f32_16x16x32_bf16 v[34:37], v[82:85], v[74:77], v[34:37]
	v_mfma_f32_16x16x32_bf16 v[22:25], v[86:89], v[74:77], v[22:25]
	v_mfma_f32_16x16x32_bf16 v[18:21], v[208:211], v[74:77], v[18:21]
	v_mfma_f32_16x16x32_bf16 v[62:65], v[212:215], v[74:77], v[62:65]
	ds_read_b128 v[74:77], v119 offset:36864
	s_waitcnt lgkmcnt(7)
	v_mfma_f32_16x16x32_bf16 v[58:61], v[82:85], v[78:81], v[58:61]
	v_mfma_f32_16x16x32_bf16 v[54:57], v[86:89], v[78:81], v[54:57]
	v_mfma_f32_16x16x32_bf16 v[50:53], v[208:211], v[78:81], v[50:53]
	v_mfma_f32_16x16x32_bf16 v[2:5], v[212:215], v[78:81], v[2:5]
	ds_read_b128 v[78:81], v119 offset:38912
	s_waitcnt lgkmcnt(3)
	v_mfma_f32_16x16x32_bf16 v[6:9], v[216:219], v[66:69], v[6:9]
	v_mfma_f32_16x16x32_bf16 v[30:33], v[220:223], v[66:69], v[30:33]
	v_mfma_f32_16x16x32_bf16 v[38:41], v[224:227], v[66:69], v[38:41]
	v_mfma_f32_16x16x32_bf16 v[42:45], v[228:231], v[66:69], v[42:45]
	s_waitcnt lgkmcnt(2)
	v_mfma_f32_16x16x32_bf16 v[46:49], v[216:219], v[70:73], v[46:49]
	v_mfma_f32_16x16x32_bf16 v[26:29], v[220:223], v[70:73], v[26:29]
	v_mfma_f32_16x16x32_bf16 v[14:17], v[224:227], v[70:73], v[14:17]
	v_mfma_f32_16x16x32_bf16 v[10:13], v[228:231], v[70:73], v[10:13]
	s_waitcnt vmcnt(6)
	s_waitcnt lgkmcnt(0)
	s_barrier
	s_add_i32 m0, s67, 0x8000
	s_nop 0
	global_load_lds_dwordx4 v188, s[80:81]
	s_add_i32 m0, s67, 0xa000
	s_nop 0
	global_load_lds_dwordx4 v189, s[80:81]
	s_add_i32 m0, s67, 0xc000
	s_nop 0
	global_load_lds_dwordx4 v190, s[80:81]
	s_add_i32 m0, s67, 0xe000
	s_nop 0
	global_load_lds_dwordx4 v191, s[80:81]
	s_add_i32 m0, s67, 0x1c000
	s_nop 0
	global_load_lds_dwordx4 v205, s[96:97]
	s_add_i32 m0, s67, 0x1e000
	s_nop 0
	global_load_lds_dwordx4 v206, s[96:97]
	s_add_u32 s80, s80, 0x80
	s_addc_u32 s81, s81, 0
	s_add_u32 s96, s96, 0xffc80
	s_addc_u32 s97, s97, 0
	ds_read_b128 v[82:85], v90 offset:33792
	ds_read_b128 v[86:89], v90 offset:35840
	ds_read_b128 v[208:211], v90 offset:37888
	ds_read_b128 v[212:215], v90 offset:39936
	ds_read_b128 v[66:69], v0 offset:0
	ds_read_b128 v[70:73], v0 offset:2048
	v_mfma_f32_16x16x32_bf16 v[34:37], v[216:219], v[74:77], v[34:37]
	v_mfma_f32_16x16x32_bf16 v[22:25], v[220:223], v[74:77], v[22:25]
	v_mfma_f32_16x16x32_bf16 v[18:21], v[224:227], v[74:77], v[18:21]
	v_mfma_f32_16x16x32_bf16 v[62:65], v[228:231], v[74:77], v[62:65]
	ds_read_b128 v[74:77], v0 offset:4096
	v_mfma_f32_16x16x32_bf16 v[58:61], v[216:219], v[78:81], v[58:61]
	v_mfma_f32_16x16x32_bf16 v[54:57], v[220:223], v[78:81], v[54:57]
	v_mfma_f32_16x16x32_bf16 v[50:53], v[224:227], v[78:81], v[50:53]
	v_mfma_f32_16x16x32_bf16 v[2:5], v[228:231], v[78:81], v[2:5]
	ds_read_b128 v[78:81], v0 offset:6144
	ds_read_b128 v[216:219], v91 offset:33792
	ds_read_b128 v[220:223], v91 offset:35840
	ds_read_b128 v[224:227], v91 offset:37888
	ds_read_b128 v[228:231], v91 offset:39936
	s_waitcnt lgkmcnt(7)
	v_mfma_f32_16x16x32_bf16 v[6:9], v[82:85], v[66:69], v[6:9]
	v_mfma_f32_16x16x32_bf16 v[30:33], v[86:89], v[66:69], v[30:33]
	v_mfma_f32_16x16x32_bf16 v[38:41], v[208:211], v[66:69], v[38:41]
	v_mfma_f32_16x16x32_bf16 v[42:45], v[212:215], v[66:69], v[42:45]
	ds_read_b128 v[66:69], v255 offset:0
	s_waitcnt lgkmcnt(7)
	v_mfma_f32_16x16x32_bf16 v[46:49], v[82:85], v[70:73], v[46:49]
	v_mfma_f32_16x16x32_bf16 v[26:29], v[86:89], v[70:73], v[26:29]
	v_mfma_f32_16x16x32_bf16 v[14:17], v[208:211], v[70:73], v[14:17]
	v_mfma_f32_16x16x32_bf16 v[10:13], v[212:215], v[70:73], v[10:13]
	ds_read_b128 v[70:73], v255 offset:2048
	s_waitcnt lgkmcnt(7)
	v_mfma_f32_16x16x32_bf16 v[34:37], v[82:85], v[74:77], v[34:37]
	v_mfma_f32_16x16x32_bf16 v[22:25], v[86:89], v[74:77], v[22:25]
	v_mfma_f32_16x16x32_bf16 v[18:21], v[208:211], v[74:77], v[18:21]
	v_mfma_f32_16x16x32_bf16 v[62:65], v[212:215], v[74:77], v[62:65]
	ds_read_b128 v[74:77], v255 offset:4096
	s_waitcnt lgkmcnt(7)
	v_mfma_f32_16x16x32_bf16 v[58:61], v[82:85], v[78:81], v[58:61]
	v_mfma_f32_16x16x32_bf16 v[54:57], v[86:89], v[78:81], v[54:57]
	v_mfma_f32_16x16x32_bf16 v[50:53], v[208:211], v[78:81], v[50:53]
	v_mfma_f32_16x16x32_bf16 v[2:5], v[212:215], v[78:81], v[2:5]
	ds_read_b128 v[78:81], v255 offset:6144
	s_waitcnt lgkmcnt(3)
	v_mfma_f32_16x16x32_bf16 v[6:9], v[216:219], v[66:69], v[6:9]
	v_mfma_f32_16x16x32_bf16 v[30:33], v[220:223], v[66:69], v[30:33]
	v_mfma_f32_16x16x32_bf16 v[38:41], v[224:227], v[66:69], v[38:41]
	v_mfma_f32_16x16x32_bf16 v[42:45], v[228:231], v[66:69], v[42:45]
	s_waitcnt lgkmcnt(2)
	v_mfma_f32_16x16x32_bf16 v[46:49], v[216:219], v[70:73], v[46:49]
	v_mfma_f32_16x16x32_bf16 v[26:29], v[220:223], v[70:73], v[26:29]
	v_mfma_f32_16x16x32_bf16 v[14:17], v[224:227], v[70:73], v[14:17]
	v_mfma_f32_16x16x32_bf16 v[10:13], v[228:231], v[70:73], v[10:13]
	s_waitcnt vmcnt(6)
	s_waitcnt lgkmcnt(0)
	s_barrier
	s_add_i32 m0, s67, 0x10000
	s_nop 0
	global_load_lds_dwordx4 v188, s[80:81]
	s_add_i32 m0, s67, 0x12000
	s_nop 0
	global_load_lds_dwordx4 v189, s[80:81]
	s_add_i32 m0, s67, 0x14000
	s_nop 0
	global_load_lds_dwordx4 v190, s[80:81]
	s_add_i32 m0, s67, 0x16000
	s_nop 0
	global_load_lds_dwordx4 v191, s[80:81]
	s_add_i32 m0, s67, 0x20400
	s_nop 0
	global_load_lds_dwordx4 v205, s[96:97]
	s_add_i32 m0, s67, 0x22400
	s_nop 0
	global_load_lds_dwordx4 v206, s[96:97]
	s_add_u32 s80, s80, 0x80
	s_addc_u32 s81, s81, 0
	s_add_u32 s96, s96, 0x80
	s_addc_u32 s97, s97, 0
	ds_read_b128 v[82:85], v90 offset:0
	ds_read_b128 v[86:89], v90 offset:2048
	ds_read_b128 v[208:211], v90 offset:4096
	ds_read_b128 v[212:215], v90 offset:6144
	ds_read_b128 v[66:69], v207 offset:0
	ds_read_b128 v[70:73], v207 offset:2048
	v_mfma_f32_16x16x32_bf16 v[34:37], v[216:219], v[74:77], v[34:37]
	v_mfma_f32_16x16x32_bf16 v[22:25], v[220:223], v[74:77], v[22:25]
	v_mfma_f32_16x16x32_bf16 v[18:21], v[224:227], v[74:77], v[18:21]
	v_mfma_f32_16x16x32_bf16 v[62:65], v[228:231], v[74:77], v[62:65]
	ds_read_b128 v[74:77], v207 offset:4096
	v_mfma_f32_16x16x32_bf16 v[58:61], v[216:219], v[78:81], v[58:61]
	v_mfma_f32_16x16x32_bf16 v[54:57], v[220:223], v[78:81], v[54:57]
	v_mfma_f32_16x16x32_bf16 v[50:53], v[224:227], v[78:81], v[50:53]
	v_mfma_f32_16x16x32_bf16 v[2:5], v[228:231], v[78:81], v[2:5]
	ds_read_b128 v[78:81], v207 offset:6144
	ds_read_b128 v[216:219], v91 offset:0
	ds_read_b128 v[220:223], v91 offset:2048
	ds_read_b128 v[224:227], v91 offset:4096
	ds_read_b128 v[228:231], v91 offset:6144
	s_waitcnt lgkmcnt(7)
	v_mfma_f32_16x16x32_bf16 v[6:9], v[82:85], v[66:69], v[6:9]
	v_mfma_f32_16x16x32_bf16 v[30:33], v[86:89], v[66:69], v[30:33]
	v_mfma_f32_16x16x32_bf16 v[38:41], v[208:211], v[66:69], v[38:41]
	v_mfma_f32_16x16x32_bf16 v[42:45], v[212:215], v[66:69], v[42:45]
	ds_read_b128 v[66:69], v119 offset:0
	s_waitcnt lgkmcnt(7)
	v_mfma_f32_16x16x32_bf16 v[46:49], v[82:85], v[70:73], v[46:49]
	v_mfma_f32_16x16x32_bf16 v[26:29], v[86:89], v[70:73], v[26:29]
	v_mfma_f32_16x16x32_bf16 v[14:17], v[208:211], v[70:73], v[14:17]
	v_mfma_f32_16x16x32_bf16 v[10:13], v[212:215], v[70:73], v[10:13]
	ds_read_b128 v[70:73], v119 offset:2048
	s_waitcnt lgkmcnt(7)
	v_mfma_f32_16x16x32_bf16 v[34:37], v[82:85], v[74:77], v[34:37]
	v_mfma_f32_16x16x32_bf16 v[22:25], v[86:89], v[74:77], v[22:25]
	v_mfma_f32_16x16x32_bf16 v[18:21], v[208:211], v[74:77], v[18:21]
	v_mfma_f32_16x16x32_bf16 v[62:65], v[212:215], v[74:77], v[62:65]
	ds_read_b128 v[74:77], v119 offset:4096
	s_waitcnt lgkmcnt(7)
	v_mfma_f32_16x16x32_bf16 v[58:61], v[82:85], v[78:81], v[58:61]
	v_mfma_f32_16x16x32_bf16 v[54:57], v[86:89], v[78:81], v[54:57]
	v_mfma_f32_16x16x32_bf16 v[50:53], v[208:211], v[78:81], v[50:53]
	v_mfma_f32_16x16x32_bf16 v[2:5], v[212:215], v[78:81], v[2:5]
	ds_read_b128 v[78:81], v119 offset:6144
	s_waitcnt lgkmcnt(3)
	v_mfma_f32_16x16x32_bf16 v[6:9], v[216:219], v[66:69], v[6:9]
	v_mfma_f32_16x16x32_bf16 v[30:33], v[220:223], v[66:69], v[30:33]
	v_mfma_f32_16x16x32_bf16 v[38:41], v[224:227], v[66:69], v[38:41]
	v_mfma_f32_16x16x32_bf16 v[42:45], v[228:231], v[66:69], v[42:45]
	s_waitcnt lgkmcnt(2)
	v_mfma_f32_16x16x32_bf16 v[46:49], v[216:219], v[70:73], v[46:49]
	v_mfma_f32_16x16x32_bf16 v[26:29], v[220:223], v[70:73], v[26:29]
	v_mfma_f32_16x16x32_bf16 v[14:17], v[224:227], v[70:73], v[14:17]
	v_mfma_f32_16x16x32_bf16 v[10:13], v[228:231], v[70:73], v[10:13]
	s_waitcnt vmcnt(6)
	s_waitcnt lgkmcnt(0)
	s_barrier
	s_add_i32 m0, s67, 0x0
	s_nop 0
	global_load_lds_dwordx4 v188, s[80:81]
	s_add_i32 m0, s67, 0x2000
	s_nop 0
	global_load_lds_dwordx4 v189, s[80:81]
	s_add_i32 m0, s67, 0x4000
	s_nop 0
	global_load_lds_dwordx4 v190, s[80:81]
	s_add_i32 m0, s67, 0x6000
	s_nop 0
	global_load_lds_dwordx4 v191, s[80:81]
	s_add_i32 m0, s67, 0x18000
	s_nop 0
	global_load_lds_dwordx4 v205, s[96:97]
	s_add_i32 m0, s67, 0x1a000
	s_nop 0
	global_load_lds_dwordx4 v206, s[96:97]
	s_add_u32 s80, s80, 0x80
	s_addc_u32 s81, s81, 0
	s_add_u32 s96, s96, 0x80
	s_addc_u32 s97, s97, 0
	ds_read_b128 v[82:85], v90 offset:16384
	ds_read_b128 v[86:89], v90 offset:18432
	ds_read_b128 v[208:211], v90 offset:20480
	ds_read_b128 v[212:215], v90 offset:22528
	ds_read_b128 v[66:69], v207 offset:32768
	ds_read_b128 v[70:73], v207 offset:34816
	v_mfma_f32_16x16x32_bf16 v[34:37], v[216:219], v[74:77], v[34:37]
	v_mfma_f32_16x16x32_bf16 v[22:25], v[220:223], v[74:77], v[22:25]
	v_mfma_f32_16x16x32_bf16 v[18:21], v[224:227], v[74:77], v[18:21]
	v_mfma_f32_16x16x32_bf16 v[62:65], v[228:231], v[74:77], v[62:65]
	ds_read_b128 v[74:77], v207 offset:36864
	v_mfma_f32_16x16x32_bf16 v[58:61], v[216:219], v[78:81], v[58:61]
	v_mfma_f32_16x16x32_bf16 v[54:57], v[220:223], v[78:81], v[54:57]
	v_mfma_f32_16x16x32_bf16 v[50:53], v[224:227], v[78:81], v[50:53]
	v_mfma_f32_16x16x32_bf16 v[2:5], v[228:231], v[78:81], v[2:5]
	ds_read_b128 v[78:81], v207 offset:38912
	ds_read_b128 v[216:219], v91 offset:16384
	ds_read_b128 v[220:223], v91 offset:18432
	ds_read_b128 v[224:227], v91 offset:20480
	ds_read_b128 v[228:231], v91 offset:22528
	s_waitcnt lgkmcnt(7)
	v_mfma_f32_16x16x32_bf16 v[6:9], v[82:85], v[66:69], v[6:9]
	v_mfma_f32_16x16x32_bf16 v[30:33], v[86:89], v[66:69], v[30:33]
	v_mfma_f32_16x16x32_bf16 v[38:41], v[208:211], v[66:69], v[38:41]
	v_mfma_f32_16x16x32_bf16 v[42:45], v[212:215], v[66:69], v[42:45]
	ds_read_b128 v[66:69], v119 offset:32768
	s_waitcnt lgkmcnt(7)
	v_mfma_f32_16x16x32_bf16 v[46:49], v[82:85], v[70:73], v[46:49]
	v_mfma_f32_16x16x32_bf16 v[26:29], v[86:89], v[70:73], v[26:29]
	v_mfma_f32_16x16x32_bf16 v[14:17], v[208:211], v[70:73], v[14:17]
	v_mfma_f32_16x16x32_bf16 v[10:13], v[212:215], v[70:73], v[10:13]
	ds_read_b128 v[70:73], v119 offset:34816
	s_waitcnt lgkmcnt(7)
	v_mfma_f32_16x16x32_bf16 v[34:37], v[82:85], v[74:77], v[34:37]
	v_mfma_f32_16x16x32_bf16 v[22:25], v[86:89], v[74:77], v[22:25]
	v_mfma_f32_16x16x32_bf16 v[18:21], v[208:211], v[74:77], v[18:21]
	v_mfma_f32_16x16x32_bf16 v[62:65], v[212:215], v[74:77], v[62:65]
	ds_read_b128 v[74:77], v119 offset:36864
	s_waitcnt lgkmcnt(7)
	v_mfma_f32_16x16x32_bf16 v[58:61], v[82:85], v[78:81], v[58:61]
	v_mfma_f32_16x16x32_bf16 v[54:57], v[86:89], v[78:81], v[54:57]
	v_mfma_f32_16x16x32_bf16 v[50:53], v[208:211], v[78:81], v[50:53]
	v_mfma_f32_16x16x32_bf16 v[2:5], v[212:215], v[78:81], v[2:5]
	ds_read_b128 v[78:81], v119 offset:38912
	s_waitcnt lgkmcnt(3)
	v_mfma_f32_16x16x32_bf16 v[6:9], v[216:219], v[66:69], v[6:9]
	s_waitcnt vmcnt(30)
	v_mfma_f32_16x16x32_bf16 v[30:33], v[220:223], v[66:69], v[30:33]
	v_mfma_f32_16x16x32_bf16 v[38:41], v[224:227], v[66:69], v[38:41]
	v_mfma_f32_16x16x32_bf16 v[42:45], v[228:231], v[66:69], v[42:45]
	v_cvt_f32_ubyte0_e32 v248, v232
	v_cvt_f32_ubyte1_e32 v249, v232
	v_cvt_f32_ubyte2_e32 v250, v232
	v_cvt_f32_ubyte3_e32 v251, v232
	v_mul_f32_e32 v248, s34, v248
	v_mul_f32_e32 v249, s34, v249
	v_mul_f32_e32 v250, s34, v250
	v_mul_f32_e32 v251, s34, v251
	v_fma_f32 v184, v6, v248, v184
	v_fma_f32 v185, v7, v249, v185
	v_fma_f32 v186, v8, v250, v186
	v_fma_f32 v187, v9, v251, v187
	s_waitcnt lgkmcnt(2)
	v_mfma_f32_16x16x32_bf16 v[46:49], v[216:219], v[70:73], v[46:49]
	v_cvt_f32_ubyte0_e32 v248, v233
	v_cvt_f32_ubyte1_e32 v249, v233
	v_cvt_f32_ubyte2_e32 v250, v233
	v_cvt_f32_ubyte3_e32 v251, v233
	v_mul_f32_e32 v248, s34, v248
	v_mul_f32_e32 v249, s34, v249
	v_mul_f32_e32 v250, s34, v250
	v_mul_f32_e32 v251, s34, v251
	v_fma_f32 v180, v30, v248, v180
	v_fma_f32 v181, v31, v249, v181
	v_fma_f32 v182, v32, v250, v182
	v_fma_f32 v183, v33, v251, v183
	v_mfma_f32_16x16x32_bf16 v[26:29], v[220:223], v[70:73], v[26:29]
	v_cvt_f32_ubyte0_e32 v248, v234
	v_cvt_f32_ubyte1_e32 v249, v234
	v_cvt_f32_ubyte2_e32 v250, v234
	v_cvt_f32_ubyte3_e32 v251, v234
	v_mul_f32_e32 v248, s34, v248
	v_mul_f32_e32 v249, s34, v249
	v_mul_f32_e32 v250, s34, v250
	v_mul_f32_e32 v251, s34, v251
	v_fma_f32 v176, v38, v248, v176
	v_fma_f32 v177, v39, v249, v177
	v_fma_f32 v178, v40, v250, v178
	v_fma_f32 v179, v41, v251, v179
	v_mfma_f32_16x16x32_bf16 v[14:17], v[224:227], v[70:73], v[14:17]
	v_cvt_f32_ubyte0_e32 v248, v235
	v_cvt_f32_ubyte1_e32 v249, v235
	v_cvt_f32_ubyte2_e32 v250, v235
	v_cvt_f32_ubyte3_e32 v251, v235
	v_mul_f32_e32 v248, s34, v248
	v_mul_f32_e32 v249, s34, v249
	v_mul_f32_e32 v250, s34, v250
	v_mul_f32_e32 v251, s34, v251
	v_fma_f32 v172, v42, v248, v172
	v_fma_f32 v173, v43, v249, v173
	v_fma_f32 v174, v44, v250, v174
	v_fma_f32 v175, v45, v251, v175
	v_mfma_f32_16x16x32_bf16 v[10:13], v[228:231], v[70:73], v[10:13]
	v_cvt_f32_ubyte0_e32 v248, v236
	v_cvt_f32_ubyte1_e32 v249, v236
	v_cvt_f32_ubyte2_e32 v250, v236
	v_cvt_f32_ubyte3_e32 v251, v236
	v_mul_f32_e32 v248, s34, v248
	v_mul_f32_e32 v249, s34, v249
	v_mul_f32_e32 v250, s34, v250
	v_mul_f32_e32 v251, s34, v251
	v_fma_f32 v168, v46, v248, v168
	v_fma_f32 v169, v47, v249, v169
	v_fma_f32 v170, v48, v250, v170
	v_fma_f32 v171, v49, v251, v171
	s_waitcnt vmcnt(6)
	s_waitcnt lgkmcnt(0)
	s_barrier
	s_add_i32 m0, s67, 0x8000
	s_nop 0
	global_load_lds_dwordx4 v188, s[80:81]
	s_add_i32 m0, s67, 0xa000
	s_nop 0
	global_load_lds_dwordx4 v189, s[80:81]
	s_add_i32 m0, s67, 0xc000
	s_nop 0
	global_load_lds_dwordx4 v190, s[80:81]
	s_add_i32 m0, s67, 0xe000
	s_nop 0
	global_load_lds_dwordx4 v191, s[80:81]
	s_add_i32 m0, s67, 0x1c000
	s_nop 0
	global_load_lds_dwordx4 v205, s[96:97]
	s_add_i32 m0, s67, 0x1e000
	s_nop 0
	global_load_lds_dwordx4 v206, s[96:97]
	s_add_u32 s80, s80, 0x80
	s_addc_u32 s81, s81, 0
	s_add_u32 s96, s96, 0x80
	s_addc_u32 s97, s97, 0
	ds_read_b128 v[82:85], v90 offset:33792
	ds_read_b128 v[86:89], v90 offset:35840
	ds_read_b128 v[208:211], v90 offset:37888
	ds_read_b128 v[212:215], v90 offset:39936
	ds_read_b128 v[66:69], v0 offset:0
	ds_read_b128 v[70:73], v0 offset:2048
	v_mfma_f32_16x16x32_bf16 v[34:37], v[216:219], v[74:77], v[34:37]
	v_cvt_f32_ubyte0_e32 v248, v237
	v_cvt_f32_ubyte1_e32 v249, v237
	v_cvt_f32_ubyte2_e32 v250, v237
	v_cvt_f32_ubyte3_e32 v251, v237
	v_mul_f32_e32 v248, s34, v248
	v_mul_f32_e32 v249, s34, v249
	v_mul_f32_e32 v250, s34, v250
	v_mul_f32_e32 v251, s34, v251
	v_fma_f32 v164, v26, v248, v164
	v_fma_f32 v165, v27, v249, v165
	v_fma_f32 v166, v28, v250, v166
	v_fma_f32 v167, v29, v251, v167
	v_mfma_f32_16x16x32_bf16 v[22:25], v[220:223], v[74:77], v[22:25]
	v_cvt_f32_ubyte0_e32 v248, v238
	v_cvt_f32_ubyte1_e32 v249, v238
	v_cvt_f32_ubyte2_e32 v250, v238
	v_cvt_f32_ubyte3_e32 v251, v238
	v_mul_f32_e32 v248, s34, v248
	v_mul_f32_e32 v249, s34, v249
	v_mul_f32_e32 v250, s34, v250
	v_mul_f32_e32 v251, s34, v251
	v_fma_f32 v160, v14, v248, v160
	v_fma_f32 v161, v15, v249, v161
	v_fma_f32 v162, v16, v250, v162
	v_fma_f32 v163, v17, v251, v163
	v_mfma_f32_16x16x32_bf16 v[18:21], v[224:227], v[74:77], v[18:21]
	v_cvt_f32_ubyte0_e32 v248, v239
	v_cvt_f32_ubyte1_e32 v249, v239
	v_cvt_f32_ubyte2_e32 v250, v239
	v_cvt_f32_ubyte3_e32 v251, v239
	v_mul_f32_e32 v248, s34, v248
	v_mul_f32_e32 v249, s34, v249
	v_mul_f32_e32 v250, s34, v250
	v_mul_f32_e32 v251, s34, v251
	v_fma_f32 v156, v10, v248, v156
	v_fma_f32 v157, v11, v249, v157
	v_fma_f32 v158, v12, v250, v158
	v_fma_f32 v159, v13, v251, v159
	v_mfma_f32_16x16x32_bf16 v[62:65], v[228:231], v[74:77], v[62:65]
	v_cvt_f32_ubyte0_e32 v248, v240
	v_cvt_f32_ubyte1_e32 v249, v240
	v_cvt_f32_ubyte2_e32 v250, v240
	v_cvt_f32_ubyte3_e32 v251, v240
	v_mul_f32_e32 v248, s34, v248
	v_mul_f32_e32 v249, s34, v249
	v_mul_f32_e32 v250, s34, v250
	v_mul_f32_e32 v251, s34, v251
	v_fma_f32 v136, v34, v248, v136
	v_fma_f32 v137, v35, v249, v137
	v_fma_f32 v150, v36, v250, v150
	v_fma_f32 v151, v37, v251, v151
	ds_read_b128 v[74:77], v0 offset:4096
	v_mfma_f32_16x16x32_bf16 v[58:61], v[216:219], v[78:81], v[58:61]
	v_cvt_f32_ubyte0_e32 v248, v241
	v_cvt_f32_ubyte1_e32 v249, v241
	v_cvt_f32_ubyte2_e32 v250, v241
	v_cvt_f32_ubyte3_e32 v251, v241
	v_mul_f32_e32 v248, s34, v248
	v_mul_f32_e32 v249, s34, v249
	v_mul_f32_e32 v250, s34, v250
	v_mul_f32_e32 v251, s34, v251
	v_fma_f32 v130, v22, v248, v130
	v_fma_f32 v131, v23, v249, v131
	v_fma_f32 v134, v24, v250, v134
	v_fma_f32 v135, v25, v251, v135
	v_mfma_f32_16x16x32_bf16 v[54:57], v[220:223], v[78:81], v[54:57]
	v_cvt_f32_ubyte0_e32 v248, v242
	v_cvt_f32_ubyte1_e32 v249, v242
	v_cvt_f32_ubyte2_e32 v250, v242
	v_cvt_f32_ubyte3_e32 v251, v242
	v_mul_f32_e32 v248, s34, v248
	v_mul_f32_e32 v249, s34, v249
	v_mul_f32_e32 v250, s34, v250
	v_mul_f32_e32 v251, s34, v251
	v_fma_f32 v124, v18, v248, v124
	v_fma_f32 v125, v19, v249, v125
	v_fma_f32 v126, v20, v250, v126
	v_fma_f32 v127, v21, v251, v127
	v_mfma_f32_16x16x32_bf16 v[50:53], v[224:227], v[78:81], v[50:53]
	v_cvt_f32_ubyte0_e32 v248, v243
	v_cvt_f32_ubyte1_e32 v249, v243
	v_cvt_f32_ubyte2_e32 v250, v243
	v_cvt_f32_ubyte3_e32 v251, v243
	v_mul_f32_e32 v248, s34, v248
	v_mul_f32_e32 v249, s34, v249
	v_mul_f32_e32 v250, s34, v250
	v_mul_f32_e32 v251, s34, v251
	v_fma_f32 v120, v62, v248, v120
	v_fma_f32 v121, v63, v249, v121
	v_fma_f32 v122, v64, v250, v122
	v_fma_f32 v123, v65, v251, v123
	v_mfma_f32_16x16x32_bf16 v[2:5], v[228:231], v[78:81], v[2:5]
	v_cvt_f32_ubyte0_e32 v248, v244
	v_cvt_f32_ubyte1_e32 v249, v244
	v_cvt_f32_ubyte2_e32 v250, v244
	v_cvt_f32_ubyte3_e32 v251, v244
	v_mul_f32_e32 v248, s34, v248
	v_mul_f32_e32 v249, s34, v249
	v_mul_f32_e32 v250, s34, v250
	v_mul_f32_e32 v251, s34, v251
	v_fma_f32 v114, v58, v248, v114
	v_fma_f32 v115, v59, v249, v115
	v_fma_f32 v116, v60, v250, v116
	v_fma_f32 v117, v61, v251, v117
	ds_read_b128 v[78:81], v0 offset:6144
	s_nop 7
	s_nop 3
	v_cvt_f32_ubyte0_e32 v248, v245
	v_cvt_f32_ubyte1_e32 v249, v245
	v_cvt_f32_ubyte2_e32 v250, v245
	v_cvt_f32_ubyte3_e32 v251, v245
	v_mul_f32_e32 v248, s34, v248
	v_mul_f32_e32 v249, s34, v249
	v_mul_f32_e32 v250, s34, v250
	v_mul_f32_e32 v251, s34, v251
	v_fma_f32 v106, v54, v248, v106
	v_fma_f32 v107, v55, v249, v107
	v_fma_f32 v108, v56, v250, v108
	v_fma_f32 v109, v57, v251, v109
	v_cvt_f32_ubyte0_e32 v248, v246
	v_cvt_f32_ubyte1_e32 v249, v246
	v_cvt_f32_ubyte2_e32 v250, v246
	v_cvt_f32_ubyte3_e32 v251, v246
	v_mul_f32_e32 v248, s34, v248
	v_mul_f32_e32 v249, s34, v249
	v_mul_f32_e32 v250, s34, v250
	v_mul_f32_e32 v251, s34, v251
	v_fma_f32 v100, v50, v248, v100
	v_fma_f32 v101, v51, v249, v101
	v_fma_f32 v102, v52, v250, v102
	v_fma_f32 v103, v53, v251, v103
	v_cvt_f32_ubyte0_e32 v248, v247
	v_cvt_f32_ubyte1_e32 v249, v247
	v_cvt_f32_ubyte2_e32 v250, v247
	v_cvt_f32_ubyte3_e32 v251, v247
	v_mul_f32_e32 v248, s34, v248
	v_mul_f32_e32 v249, s34, v249
	v_mul_f32_e32 v250, s34, v250
	v_mul_f32_e32 v251, s34, v251
	v_fma_f32 v96, v2, v248, v96
	v_fma_f32 v97, v3, v249, v97
	v_fma_f32 v98, v4, v250, v98
	v_fma_f32 v99, v5, v251, v99
	s_add_u32 s98, s86, 0x1600
	s_addc_u32 s99, s87, 0
	global_load_dword v92, v93, s[98:99]
	ds_read_b128 v[216:219], v91 offset:33792
	ds_read_b128 v[220:223], v91 offset:35840
	ds_read_b128 v[224:227], v91 offset:37888
	ds_read_b128 v[228:231], v91 offset:39936
	s_waitcnt lgkmcnt(7)
	v_mfma_f32_16x16x32_bf16 v[6:9], v[82:85], v[66:69], 0
	v_mfma_f32_16x16x32_bf16 v[30:33], v[86:89], v[66:69], 0
	v_mfma_f32_16x16x32_bf16 v[38:41], v[208:211], v[66:69], 0
	v_mfma_f32_16x16x32_bf16 v[42:45], v[212:215], v[66:69], 0
	ds_read_b128 v[66:69], v255 offset:0
	s_waitcnt lgkmcnt(7)
	v_mfma_f32_16x16x32_bf16 v[46:49], v[82:85], v[70:73], 0
	v_mfma_f32_16x16x32_bf16 v[26:29], v[86:89], v[70:73], 0
	v_mfma_f32_16x16x32_bf16 v[14:17], v[208:211], v[70:73], 0
	v_mfma_f32_16x16x32_bf16 v[10:13], v[212:215], v[70:73], 0
	ds_read_b128 v[70:73], v255 offset:2048
	s_waitcnt lgkmcnt(7)
	v_mfma_f32_16x16x32_bf16 v[34:37], v[82:85], v[74:77], 0
	v_mfma_f32_16x16x32_bf16 v[22:25], v[86:89], v[74:77], 0
	v_mfma_f32_16x16x32_bf16 v[18:21], v[208:211], v[74:77], 0
	v_mfma_f32_16x16x32_bf16 v[62:65], v[212:215], v[74:77], 0
	ds_read_b128 v[74:77], v255 offset:4096
	s_waitcnt lgkmcnt(7)
	v_mfma_f32_16x16x32_bf16 v[58:61], v[82:85], v[78:81], 0
	v_mfma_f32_16x16x32_bf16 v[54:57], v[86:89], v[78:81], 0
	v_mfma_f32_16x16x32_bf16 v[50:53], v[208:211], v[78:81], 0
	v_mfma_f32_16x16x32_bf16 v[2:5], v[212:215], v[78:81], 0
	ds_read_b128 v[78:81], v255 offset:6144
	s_waitcnt lgkmcnt(3)
	v_mfma_f32_16x16x32_bf16 v[6:9], v[216:219], v[66:69], v[6:9]
	v_mfma_f32_16x16x32_bf16 v[30:33], v[220:223], v[66:69], v[30:33]
	v_mfma_f32_16x16x32_bf16 v[38:41], v[224:227], v[66:69], v[38:41]
	v_mfma_f32_16x16x32_bf16 v[42:45], v[228:231], v[66:69], v[42:45]
	s_waitcnt lgkmcnt(2)
	v_mfma_f32_16x16x32_bf16 v[46:49], v[216:219], v[70:73], v[46:49]
	v_mfma_f32_16x16x32_bf16 v[26:29], v[220:223], v[70:73], v[26:29]
	v_mfma_f32_16x16x32_bf16 v[14:17], v[224:227], v[70:73], v[14:17]
	v_mfma_f32_16x16x32_bf16 v[10:13], v[228:231], v[70:73], v[10:13]
	s_waitcnt vmcnt(7)
	s_waitcnt lgkmcnt(0)
	s_barrier
	s_add_i32 m0, s67, 0x10000
	s_nop 0
	global_load_lds_dwordx4 v188, s[80:81]
	s_add_i32 m0, s67, 0x12000
	s_nop 0
	global_load_lds_dwordx4 v189, s[80:81]
	s_add_i32 m0, s67, 0x14000
	s_nop 0
	global_load_lds_dwordx4 v190, s[80:81]
	s_add_i32 m0, s67, 0x16000
	s_nop 0
	global_load_lds_dwordx4 v191, s[80:81]
	s_add_i32 m0, s67, 0x20400
	s_nop 0
	global_load_lds_dwordx4 v205, s[96:97]
	s_add_i32 m0, s67, 0x22400
	s_nop 0
	global_load_lds_dwordx4 v206, s[96:97]
	s_add_u32 s80, s80, 0x80
	s_addc_u32 s81, s81, 0
	s_add_u32 s96, s96, 0x80
	s_addc_u32 s97, s97, 0
	ds_read_b128 v[82:85], v90 offset:0
	ds_read_b128 v[86:89], v90 offset:2048
	ds_read_b128 v[208:211], v90 offset:4096
	ds_read_b128 v[212:215], v90 offset:6144
	ds_read_b128 v[66:69], v207 offset:0
	ds_read_b128 v[70:73], v207 offset:2048
	v_mfma_f32_16x16x32_bf16 v[34:37], v[216:219], v[74:77], v[34:37]
	v_mfma_f32_16x16x32_bf16 v[22:25], v[220:223], v[74:77], v[22:25]
	v_mfma_f32_16x16x32_bf16 v[18:21], v[224:227], v[74:77], v[18:21]
	v_mfma_f32_16x16x32_bf16 v[62:65], v[228:231], v[74:77], v[62:65]
	ds_read_b128 v[74:77], v207 offset:4096
	v_mfma_f32_16x16x32_bf16 v[58:61], v[216:219], v[78:81], v[58:61]
	v_mfma_f32_16x16x32_bf16 v[54:57], v[220:223], v[78:81], v[54:57]
	v_mfma_f32_16x16x32_bf16 v[50:53], v[224:227], v[78:81], v[50:53]
	v_mfma_f32_16x16x32_bf16 v[2:5], v[228:231], v[78:81], v[2:5]
	ds_read_b128 v[78:81], v207 offset:6144
	ds_read_b128 v[216:219], v91 offset:0
	ds_read_b128 v[220:223], v91 offset:2048
	ds_read_b128 v[224:227], v91 offset:4096
	ds_read_b128 v[228:231], v91 offset:6144
	s_waitcnt lgkmcnt(7)
	v_mfma_f32_16x16x32_bf16 v[6:9], v[82:85], v[66:69], v[6:9]
	v_mfma_f32_16x16x32_bf16 v[30:33], v[86:89], v[66:69], v[30:33]
	v_mfma_f32_16x16x32_bf16 v[38:41], v[208:211], v[66:69], v[38:41]
	v_mfma_f32_16x16x32_bf16 v[42:45], v[212:215], v[66:69], v[42:45]
	ds_read_b128 v[66:69], v119 offset:0
	s_waitcnt lgkmcnt(7)
	v_mfma_f32_16x16x32_bf16 v[46:49], v[82:85], v[70:73], v[46:49]
	v_mfma_f32_16x16x32_bf16 v[26:29], v[86:89], v[70:73], v[26:29]
	v_mfma_f32_16x16x32_bf16 v[14:17], v[208:211], v[70:73], v[14:17]
	v_mfma_f32_16x16x32_bf16 v[10:13], v[212:215], v[70:73], v[10:13]
	ds_read_b128 v[70:73], v119 offset:2048
	s_waitcnt lgkmcnt(7)
	v_mfma_f32_16x16x32_bf16 v[34:37], v[82:85], v[74:77], v[34:37]
	v_mfma_f32_16x16x32_bf16 v[22:25], v[86:89], v[74:77], v[22:25]
	v_mfma_f32_16x16x32_bf16 v[18:21], v[208:211], v[74:77], v[18:21]
	v_mfma_f32_16x16x32_bf16 v[62:65], v[212:215], v[74:77], v[62:65]
	ds_read_b128 v[74:77], v119 offset:4096
	s_waitcnt lgkmcnt(7)
	v_mfma_f32_16x16x32_bf16 v[58:61], v[82:85], v[78:81], v[58:61]
	v_mfma_f32_16x16x32_bf16 v[54:57], v[86:89], v[78:81], v[54:57]
	v_mfma_f32_16x16x32_bf16 v[50:53], v[208:211], v[78:81], v[50:53]
	v_mfma_f32_16x16x32_bf16 v[2:5], v[212:215], v[78:81], v[2:5]
	ds_read_b128 v[78:81], v119 offset:6144
	s_waitcnt lgkmcnt(3)
	v_mfma_f32_16x16x32_bf16 v[6:9], v[216:219], v[66:69], v[6:9]
	v_mfma_f32_16x16x32_bf16 v[30:33], v[220:223], v[66:69], v[30:33]
	v_mfma_f32_16x16x32_bf16 v[38:41], v[224:227], v[66:69], v[38:41]
	v_mfma_f32_16x16x32_bf16 v[42:45], v[228:231], v[66:69], v[42:45]
	s_waitcnt lgkmcnt(2)
	v_mfma_f32_16x16x32_bf16 v[46:49], v[216:219], v[70:73], v[46:49]
	v_mfma_f32_16x16x32_bf16 v[26:29], v[220:223], v[70:73], v[26:29]
	v_mfma_f32_16x16x32_bf16 v[14:17], v[224:227], v[70:73], v[14:17]
	v_mfma_f32_16x16x32_bf16 v[10:13], v[228:231], v[70:73], v[10:13]
	s_waitcnt vmcnt(7)
	s_waitcnt lgkmcnt(0)
	s_barrier
	s_add_i32 m0, s67, 0x0
	s_nop 0
	global_load_lds_dwordx4 v188, s[80:81]
	s_add_i32 m0, s67, 0x2000
	s_nop 0
	global_load_lds_dwordx4 v189, s[80:81]
	s_add_i32 m0, s67, 0x4000
	s_nop 0
	global_load_lds_dwordx4 v190, s[80:81]
	s_add_i32 m0, s67, 0x6000
	s_nop 0
	global_load_lds_dwordx4 v191, s[80:81]
	s_add_i32 m0, s67, 0x18000
	s_nop 0
	global_load_lds_dwordx4 v205, s[96:97]
	s_add_i32 m0, s67, 0x1a000
	s_nop 0
	global_load_lds_dwordx4 v206, s[96:97]
	s_add_u32 s80, s80, 0x80
	s_addc_u32 s81, s81, 0
	s_add_u32 s96, s96, 0x80
	s_addc_u32 s97, s97, 0
	s_movk_i32 s10, 0x400
	s_mov_b32 s11, 0
	v_lshl_add_u64 v[248:249], v[128:129], 0, s[10:11]
	global_load_dwordx2 v[232:233], v[248:249], off
	global_load_dwordx2 v[234:235], v[248:249], off offset:32
	v_lshl_add_u64 v[248:249], v[132:133], 0, s[10:11]
	global_load_dwordx2 v[236:237], v[248:249], off
	global_load_dwordx2 v[238:239], v[248:249], off offset:32
	v_lshl_add_u64 v[248:249], v[152:153], 0, s[10:11]
	global_load_dwordx2 v[240:241], v[248:249], off
	global_load_dwordx2 v[242:243], v[248:249], off offset:32
	v_lshl_add_u64 v[248:249], v[154:155], 0, s[10:11]
	global_load_dwordx2 v[244:245], v[248:249], off
	global_load_dwordx2 v[246:247], v[248:249], off offset:32
	ds_read_b128 v[82:85], v90 offset:16384
	ds_read_b128 v[86:89], v90 offset:18432
	ds_read_b128 v[208:211], v90 offset:20480
	ds_read_b128 v[212:215], v90 offset:22528
	ds_read_b128 v[66:69], v207 offset:32768
	ds_read_b128 v[70:73], v207 offset:34816
	v_mfma_f32_16x16x32_bf16 v[34:37], v[216:219], v[74:77], v[34:37]
	v_mfma_f32_16x16x32_bf16 v[22:25], v[220:223], v[74:77], v[22:25]
	v_mfma_f32_16x16x32_bf16 v[18:21], v[224:227], v[74:77], v[18:21]
	v_mfma_f32_16x16x32_bf16 v[62:65], v[228:231], v[74:77], v[62:65]
	ds_read_b128 v[74:77], v207 offset:36864
	v_mfma_f32_16x16x32_bf16 v[58:61], v[216:219], v[78:81], v[58:61]
	v_mfma_f32_16x16x32_bf16 v[54:57], v[220:223], v[78:81], v[54:57]
	v_mfma_f32_16x16x32_bf16 v[50:53], v[224:227], v[78:81], v[50:53]
	v_mfma_f32_16x16x32_bf16 v[2:5], v[228:231], v[78:81], v[2:5]
	ds_read_b128 v[78:81], v207 offset:38912
	ds_read_b128 v[216:219], v91 offset:16384
	ds_read_b128 v[220:223], v91 offset:18432
	ds_read_b128 v[224:227], v91 offset:20480
	ds_read_b128 v[228:231], v91 offset:22528
	s_waitcnt lgkmcnt(7)
	v_mfma_f32_16x16x32_bf16 v[6:9], v[82:85], v[66:69], v[6:9]
	v_mfma_f32_16x16x32_bf16 v[30:33], v[86:89], v[66:69], v[30:33]
	v_mfma_f32_16x16x32_bf16 v[38:41], v[208:211], v[66:69], v[38:41]
	v_mfma_f32_16x16x32_bf16 v[42:45], v[212:215], v[66:69], v[42:45]
	ds_read_b128 v[66:69], v119 offset:32768
	s_waitcnt lgkmcnt(7)
	v_mfma_f32_16x16x32_bf16 v[46:49], v[82:85], v[70:73], v[46:49]
	v_mfma_f32_16x16x32_bf16 v[26:29], v[86:89], v[70:73], v[26:29]
	v_mfma_f32_16x16x32_bf16 v[14:17], v[208:211], v[70:73], v[14:17]
	v_mfma_f32_16x16x32_bf16 v[10:13], v[212:215], v[70:73], v[10:13]
	ds_read_b128 v[70:73], v119 offset:34816
	s_waitcnt lgkmcnt(7)
	v_mfma_f32_16x16x32_bf16 v[34:37], v[82:85], v[74:77], v[34:37]
	v_mfma_f32_16x16x32_bf16 v[22:25], v[86:89], v[74:77], v[22:25]
	v_mfma_f32_16x16x32_bf16 v[18:21], v[208:211], v[74:77], v[18:21]
	v_mfma_f32_16x16x32_bf16 v[62:65], v[212:215], v[74:77], v[62:65]
	ds_read_b128 v[74:77], v119 offset:36864
	s_waitcnt lgkmcnt(7)
	v_mfma_f32_16x16x32_bf16 v[58:61], v[82:85], v[78:81], v[58:61]
	v_mfma_f32_16x16x32_bf16 v[54:57], v[86:89], v[78:81], v[54:57]
	v_mfma_f32_16x16x32_bf16 v[50:53], v[208:211], v[78:81], v[50:53]
	v_mfma_f32_16x16x32_bf16 v[2:5], v[212:215], v[78:81], v[2:5]
	ds_read_b128 v[78:81], v119 offset:38912
	s_waitcnt lgkmcnt(3)
	v_mfma_f32_16x16x32_bf16 v[6:9], v[216:219], v[66:69], v[6:9]
	v_mfma_f32_16x16x32_bf16 v[30:33], v[220:223], v[66:69], v[30:33]
	v_mfma_f32_16x16x32_bf16 v[38:41], v[224:227], v[66:69], v[38:41]
	v_mfma_f32_16x16x32_bf16 v[42:45], v[228:231], v[66:69], v[42:45]
	s_waitcnt lgkmcnt(2)
	v_mfma_f32_16x16x32_bf16 v[46:49], v[216:219], v[70:73], v[46:49]
	v_mfma_f32_16x16x32_bf16 v[26:29], v[220:223], v[70:73], v[26:29]
	v_mfma_f32_16x16x32_bf16 v[14:17], v[224:227], v[70:73], v[14:17]
	v_mfma_f32_16x16x32_bf16 v[10:13], v[228:231], v[70:73], v[10:13]
	s_waitcnt vmcnt(14)
	s_waitcnt lgkmcnt(0)
	s_barrier
	s_add_i32 m0, s67, 0x8000
	s_nop 0
	global_load_lds_dwordx4 v188, s[80:81]
	s_add_i32 m0, s67, 0xa000
	s_nop 0
	global_load_lds_dwordx4 v189, s[80:81]
	s_add_i32 m0, s67, 0xc000
	s_nop 0
	global_load_lds_dwordx4 v190, s[80:81]
	s_add_i32 m0, s67, 0xe000
	s_nop 0
	global_load_lds_dwordx4 v191, s[80:81]
	s_add_i32 m0, s67, 0x1c000
	s_nop 0
	global_load_lds_dwordx4 v205, s[96:97]
	s_add_i32 m0, s67, 0x1e000
	s_nop 0
	global_load_lds_dwordx4 v206, s[96:97]
	s_add_u32 s80, s80, 0x80
	s_addc_u32 s81, s81, 0
	s_add_u32 s96, s96, 0x80
	s_addc_u32 s97, s97, 0
	ds_read_b128 v[82:85], v90 offset:33792
	ds_read_b128 v[86:89], v90 offset:35840
	ds_read_b128 v[208:211], v90 offset:37888
	ds_read_b128 v[212:215], v90 offset:39936
	ds_read_b128 v[66:69], v0 offset:0
	ds_read_b128 v[70:73], v0 offset:2048
	v_mfma_f32_16x16x32_bf16 v[34:37], v[216:219], v[74:77], v[34:37]
	v_mfma_f32_16x16x32_bf16 v[22:25], v[220:223], v[74:77], v[22:25]
	v_mfma_f32_16x16x32_bf16 v[18:21], v[224:227], v[74:77], v[18:21]
	v_mfma_f32_16x16x32_bf16 v[62:65], v[228:231], v[74:77], v[62:65]
	ds_read_b128 v[74:77], v0 offset:4096
	v_mfma_f32_16x16x32_bf16 v[58:61], v[216:219], v[78:81], v[58:61]
	v_mfma_f32_16x16x32_bf16 v[54:57], v[220:223], v[78:81], v[54:57]
	v_mfma_f32_16x16x32_bf16 v[50:53], v[224:227], v[78:81], v[50:53]
	v_mfma_f32_16x16x32_bf16 v[2:5], v[228:231], v[78:81], v[2:5]
	ds_read_b128 v[78:81], v0 offset:6144
	ds_read_b128 v[216:219], v91 offset:33792
	ds_read_b128 v[220:223], v91 offset:35840
	ds_read_b128 v[224:227], v91 offset:37888
	ds_read_b128 v[228:231], v91 offset:39936
	s_waitcnt lgkmcnt(7)
	v_mfma_f32_16x16x32_bf16 v[6:9], v[82:85], v[66:69], v[6:9]
	v_mfma_f32_16x16x32_bf16 v[30:33], v[86:89], v[66:69], v[30:33]
	v_mfma_f32_16x16x32_bf16 v[38:41], v[208:211], v[66:69], v[38:41]
	v_mfma_f32_16x16x32_bf16 v[42:45], v[212:215], v[66:69], v[42:45]
	ds_read_b128 v[66:69], v255 offset:0
	s_waitcnt lgkmcnt(7)
	v_mfma_f32_16x16x32_bf16 v[46:49], v[82:85], v[70:73], v[46:49]
	v_mfma_f32_16x16x32_bf16 v[26:29], v[86:89], v[70:73], v[26:29]
	v_mfma_f32_16x16x32_bf16 v[14:17], v[208:211], v[70:73], v[14:17]
	v_mfma_f32_16x16x32_bf16 v[10:13], v[212:215], v[70:73], v[10:13]
	ds_read_b128 v[70:73], v255 offset:2048
	s_waitcnt lgkmcnt(7)
	v_mfma_f32_16x16x32_bf16 v[34:37], v[82:85], v[74:77], v[34:37]
	v_mfma_f32_16x16x32_bf16 v[22:25], v[86:89], v[74:77], v[22:25]
	v_mfma_f32_16x16x32_bf16 v[18:21], v[208:211], v[74:77], v[18:21]
	v_mfma_f32_16x16x32_bf16 v[62:65], v[212:215], v[74:77], v[62:65]
	ds_read_b128 v[74:77], v255 offset:4096
	s_waitcnt lgkmcnt(7)
	v_mfma_f32_16x16x32_bf16 v[58:61], v[82:85], v[78:81], v[58:61]
	v_mfma_f32_16x16x32_bf16 v[54:57], v[86:89], v[78:81], v[54:57]
	v_mfma_f32_16x16x32_bf16 v[50:53], v[208:211], v[78:81], v[50:53]
	v_mfma_f32_16x16x32_bf16 v[2:5], v[212:215], v[78:81], v[2:5]
	ds_read_b128 v[78:81], v255 offset:6144
	s_waitcnt lgkmcnt(3)
	v_mfma_f32_16x16x32_bf16 v[6:9], v[216:219], v[66:69], v[6:9]
	v_mfma_f32_16x16x32_bf16 v[30:33], v[220:223], v[66:69], v[30:33]
	v_mfma_f32_16x16x32_bf16 v[38:41], v[224:227], v[66:69], v[38:41]
	v_mfma_f32_16x16x32_bf16 v[42:45], v[228:231], v[66:69], v[42:45]
	s_waitcnt lgkmcnt(2)
	v_mfma_f32_16x16x32_bf16 v[46:49], v[216:219], v[70:73], v[46:49]
	v_mfma_f32_16x16x32_bf16 v[26:29], v[220:223], v[70:73], v[26:29]
	v_mfma_f32_16x16x32_bf16 v[14:17], v[224:227], v[70:73], v[14:17]
	v_mfma_f32_16x16x32_bf16 v[10:13], v[228:231], v[70:73], v[10:13]
	s_waitcnt vmcnt(14)
	s_waitcnt lgkmcnt(0)
	s_barrier
	s_add_i32 m0, s67, 0x10000
	s_nop 0
	global_load_lds_dwordx4 v188, s[80:81]
	s_add_i32 m0, s67, 0x12000
	s_nop 0
	global_load_lds_dwordx4 v189, s[80:81]
	s_add_i32 m0, s67, 0x14000
	s_nop 0
	global_load_lds_dwordx4 v190, s[80:81]
	s_add_i32 m0, s67, 0x16000
	s_nop 0
	global_load_lds_dwordx4 v191, s[80:81]
	s_add_i32 m0, s67, 0x20400
	s_nop 0
	global_load_lds_dwordx4 v205, s[96:97]
	s_add_i32 m0, s67, 0x22400
	s_nop 0
	global_load_lds_dwordx4 v206, s[96:97]
	s_add_u32 s80, s80, 0x80
	s_addc_u32 s81, s81, 0
	s_add_u32 s96, s96, 0x80
	s_addc_u32 s97, s97, 0
	ds_read_b128 v[82:85], v90 offset:0
	ds_read_b128 v[86:89], v90 offset:2048
	ds_read_b128 v[208:211], v90 offset:4096
	ds_read_b128 v[212:215], v90 offset:6144
	ds_read_b128 v[66:69], v207 offset:0
	ds_read_b128 v[70:73], v207 offset:2048
	v_mfma_f32_16x16x32_bf16 v[34:37], v[216:219], v[74:77], v[34:37]
	v_mfma_f32_16x16x32_bf16 v[22:25], v[220:223], v[74:77], v[22:25]
	v_mfma_f32_16x16x32_bf16 v[18:21], v[224:227], v[74:77], v[18:21]
	v_mfma_f32_16x16x32_bf16 v[62:65], v[228:231], v[74:77], v[62:65]
	ds_read_b128 v[74:77], v207 offset:4096
	v_mfma_f32_16x16x32_bf16 v[58:61], v[216:219], v[78:81], v[58:61]
	v_mfma_f32_16x16x32_bf16 v[54:57], v[220:223], v[78:81], v[54:57]
	v_mfma_f32_16x16x32_bf16 v[50:53], v[224:227], v[78:81], v[50:53]
	v_mfma_f32_16x16x32_bf16 v[2:5], v[228:231], v[78:81], v[2:5]
	ds_read_b128 v[78:81], v207 offset:6144
	ds_read_b128 v[216:219], v91 offset:0
	ds_read_b128 v[220:223], v91 offset:2048
	ds_read_b128 v[224:227], v91 offset:4096
	ds_read_b128 v[228:231], v91 offset:6144
	s_waitcnt lgkmcnt(7)
	v_mfma_f32_16x16x32_bf16 v[6:9], v[82:85], v[66:69], v[6:9]
	v_mfma_f32_16x16x32_bf16 v[30:33], v[86:89], v[66:69], v[30:33]
	v_mfma_f32_16x16x32_bf16 v[38:41], v[208:211], v[66:69], v[38:41]
	v_mfma_f32_16x16x32_bf16 v[42:45], v[212:215], v[66:69], v[42:45]
	ds_read_b128 v[66:69], v119 offset:0
	s_waitcnt lgkmcnt(7)
	v_mfma_f32_16x16x32_bf16 v[46:49], v[82:85], v[70:73], v[46:49]
	v_mfma_f32_16x16x32_bf16 v[26:29], v[86:89], v[70:73], v[26:29]
	v_mfma_f32_16x16x32_bf16 v[14:17], v[208:211], v[70:73], v[14:17]
	v_mfma_f32_16x16x32_bf16 v[10:13], v[212:215], v[70:73], v[10:13]
	ds_read_b128 v[70:73], v119 offset:2048
	s_waitcnt lgkmcnt(7)
	v_mfma_f32_16x16x32_bf16 v[34:37], v[82:85], v[74:77], v[34:37]
	v_mfma_f32_16x16x32_bf16 v[22:25], v[86:89], v[74:77], v[22:25]
	v_mfma_f32_16x16x32_bf16 v[18:21], v[208:211], v[74:77], v[18:21]
	v_mfma_f32_16x16x32_bf16 v[62:65], v[212:215], v[74:77], v[62:65]
	ds_read_b128 v[74:77], v119 offset:4096
	s_waitcnt lgkmcnt(7)
	v_mfma_f32_16x16x32_bf16 v[58:61], v[82:85], v[78:81], v[58:61]
	v_mfma_f32_16x16x32_bf16 v[54:57], v[86:89], v[78:81], v[54:57]
	v_mfma_f32_16x16x32_bf16 v[50:53], v[208:211], v[78:81], v[50:53]
	v_mfma_f32_16x16x32_bf16 v[2:5], v[212:215], v[78:81], v[2:5]
	ds_read_b128 v[78:81], v119 offset:6144
	s_waitcnt lgkmcnt(3)
	v_mfma_f32_16x16x32_bf16 v[6:9], v[216:219], v[66:69], v[6:9]
	v_mfma_f32_16x16x32_bf16 v[30:33], v[220:223], v[66:69], v[30:33]
	v_mfma_f32_16x16x32_bf16 v[38:41], v[224:227], v[66:69], v[38:41]
	v_mfma_f32_16x16x32_bf16 v[42:45], v[228:231], v[66:69], v[42:45]
	s_waitcnt lgkmcnt(2)
	v_mfma_f32_16x16x32_bf16 v[46:49], v[216:219], v[70:73], v[46:49]
	v_mfma_f32_16x16x32_bf16 v[26:29], v[220:223], v[70:73], v[26:29]
	v_mfma_f32_16x16x32_bf16 v[14:17], v[224:227], v[70:73], v[14:17]
	v_mfma_f32_16x16x32_bf16 v[10:13], v[228:231], v[70:73], v[10:13]
	s_waitcnt vmcnt(6)
	s_waitcnt lgkmcnt(0)
	s_barrier
	s_add_i32 m0, s67, 0x0
	s_nop 0
	global_load_lds_dwordx4 v188, s[80:81]
	s_add_i32 m0, s67, 0x2000
	s_nop 0
	global_load_lds_dwordx4 v189, s[80:81]
	s_add_i32 m0, s67, 0x4000
	s_nop 0
	global_load_lds_dwordx4 v190, s[80:81]
	s_add_i32 m0, s67, 0x6000
	s_nop 0
	global_load_lds_dwordx4 v191, s[80:81]
	s_add_i32 m0, s67, 0x18000
	s_nop 0
	global_load_lds_dwordx4 v205, s[96:97]
	s_add_i32 m0, s67, 0x1a000
	s_nop 0
	global_load_lds_dwordx4 v206, s[96:97]
	s_add_u32 s80, s80, 0x280
	s_addc_u32 s81, s81, 0
	s_add_u32 s96, s96, 0xffc80
	s_addc_u32 s97, s97, 0
	ds_read_b128 v[82:85], v90 offset:16384
	ds_read_b128 v[86:89], v90 offset:18432
	ds_read_b128 v[208:211], v90 offset:20480
	ds_read_b128 v[212:215], v90 offset:22528
	ds_read_b128 v[66:69], v207 offset:32768
	ds_read_b128 v[70:73], v207 offset:34816
	v_mfma_f32_16x16x32_bf16 v[34:37], v[216:219], v[74:77], v[34:37]
	v_mfma_f32_16x16x32_bf16 v[22:25], v[220:223], v[74:77], v[22:25]
	v_mfma_f32_16x16x32_bf16 v[18:21], v[224:227], v[74:77], v[18:21]
	v_mfma_f32_16x16x32_bf16 v[62:65], v[228:231], v[74:77], v[62:65]
	ds_read_b128 v[74:77], v207 offset:36864
	v_mfma_f32_16x16x32_bf16 v[58:61], v[216:219], v[78:81], v[58:61]
	v_mfma_f32_16x16x32_bf16 v[54:57], v[220:223], v[78:81], v[54:57]
	v_mfma_f32_16x16x32_bf16 v[50:53], v[224:227], v[78:81], v[50:53]
	v_mfma_f32_16x16x32_bf16 v[2:5], v[228:231], v[78:81], v[2:5]
	ds_read_b128 v[78:81], v207 offset:38912
	ds_read_b128 v[216:219], v91 offset:16384
	ds_read_b128 v[220:223], v91 offset:18432
	ds_read_b128 v[224:227], v91 offset:20480
	ds_read_b128 v[228:231], v91 offset:22528
	s_waitcnt lgkmcnt(7)
	v_mfma_f32_16x16x32_bf16 v[6:9], v[82:85], v[66:69], v[6:9]
	v_mfma_f32_16x16x32_bf16 v[30:33], v[86:89], v[66:69], v[30:33]
	v_mfma_f32_16x16x32_bf16 v[38:41], v[208:211], v[66:69], v[38:41]
	v_mfma_f32_16x16x32_bf16 v[42:45], v[212:215], v[66:69], v[42:45]
	ds_read_b128 v[66:69], v119 offset:32768
	s_waitcnt lgkmcnt(7)
	v_mfma_f32_16x16x32_bf16 v[46:49], v[82:85], v[70:73], v[46:49]
	v_mfma_f32_16x16x32_bf16 v[26:29], v[86:89], v[70:73], v[26:29]
	v_mfma_f32_16x16x32_bf16 v[14:17], v[208:211], v[70:73], v[14:17]
	v_mfma_f32_16x16x32_bf16 v[10:13], v[212:215], v[70:73], v[10:13]
	ds_read_b128 v[70:73], v119 offset:34816
	s_waitcnt lgkmcnt(7)
	v_mfma_f32_16x16x32_bf16 v[34:37], v[82:85], v[74:77], v[34:37]
	v_mfma_f32_16x16x32_bf16 v[22:25], v[86:89], v[74:77], v[22:25]
	v_mfma_f32_16x16x32_bf16 v[18:21], v[208:211], v[74:77], v[18:21]
	v_mfma_f32_16x16x32_bf16 v[62:65], v[212:215], v[74:77], v[62:65]
	ds_read_b128 v[74:77], v119 offset:36864
	s_waitcnt lgkmcnt(7)
	v_mfma_f32_16x16x32_bf16 v[58:61], v[82:85], v[78:81], v[58:61]
	v_mfma_f32_16x16x32_bf16 v[54:57], v[86:89], v[78:81], v[54:57]
	v_mfma_f32_16x16x32_bf16 v[50:53], v[208:211], v[78:81], v[50:53]
	v_mfma_f32_16x16x32_bf16 v[2:5], v[212:215], v[78:81], v[2:5]
	ds_read_b128 v[78:81], v119 offset:38912
	s_waitcnt lgkmcnt(3)
	v_mfma_f32_16x16x32_bf16 v[6:9], v[216:219], v[66:69], v[6:9]
	v_mfma_f32_16x16x32_bf16 v[30:33], v[220:223], v[66:69], v[30:33]
	v_mfma_f32_16x16x32_bf16 v[38:41], v[224:227], v[66:69], v[38:41]
	v_mfma_f32_16x16x32_bf16 v[42:45], v[228:231], v[66:69], v[42:45]
	s_waitcnt lgkmcnt(2)
	v_mfma_f32_16x16x32_bf16 v[46:49], v[216:219], v[70:73], v[46:49]
	v_mfma_f32_16x16x32_bf16 v[26:29], v[220:223], v[70:73], v[26:29]
	v_mfma_f32_16x16x32_bf16 v[14:17], v[224:227], v[70:73], v[14:17]
	v_mfma_f32_16x16x32_bf16 v[10:13], v[228:231], v[70:73], v[10:13]
	s_waitcnt vmcnt(6)
	s_waitcnt lgkmcnt(0)
	s_barrier
	s_add_i32 m0, s67, 0x8000
	s_nop 0
	global_load_lds_dwordx4 v188, s[80:81]
	s_add_i32 m0, s67, 0xa000
	s_nop 0
	global_load_lds_dwordx4 v189, s[80:81]
	s_add_i32 m0, s67, 0xc000
	s_nop 0
	global_load_lds_dwordx4 v190, s[80:81]
	s_add_i32 m0, s67, 0xe000
	s_nop 0
	global_load_lds_dwordx4 v191, s[80:81]
	s_add_i32 m0, s67, 0x1c000
	s_nop 0
	global_load_lds_dwordx4 v205, s[96:97]
	s_add_i32 m0, s67, 0x1e000
	s_nop 0
	global_load_lds_dwordx4 v206, s[96:97]
	s_add_u32 s80, s80, 0x80
	s_addc_u32 s81, s81, 0
	s_add_u32 s96, s96, 0x80
	s_addc_u32 s97, s97, 0
	ds_read_b128 v[82:85], v90 offset:33792
	ds_read_b128 v[86:89], v90 offset:35840
	ds_read_b128 v[208:211], v90 offset:37888
	ds_read_b128 v[212:215], v90 offset:39936
	ds_read_b128 v[66:69], v0 offset:0
	ds_read_b128 v[70:73], v0 offset:2048
	v_mfma_f32_16x16x32_bf16 v[34:37], v[216:219], v[74:77], v[34:37]
	v_mfma_f32_16x16x32_bf16 v[22:25], v[220:223], v[74:77], v[22:25]
	v_mfma_f32_16x16x32_bf16 v[18:21], v[224:227], v[74:77], v[18:21]
	v_mfma_f32_16x16x32_bf16 v[62:65], v[228:231], v[74:77], v[62:65]
	ds_read_b128 v[74:77], v0 offset:4096
	v_mfma_f32_16x16x32_bf16 v[58:61], v[216:219], v[78:81], v[58:61]
	v_mfma_f32_16x16x32_bf16 v[54:57], v[220:223], v[78:81], v[54:57]
	v_mfma_f32_16x16x32_bf16 v[50:53], v[224:227], v[78:81], v[50:53]
	v_mfma_f32_16x16x32_bf16 v[2:5], v[228:231], v[78:81], v[2:5]
	ds_read_b128 v[78:81], v0 offset:6144
	ds_read_b128 v[216:219], v91 offset:33792
	ds_read_b128 v[220:223], v91 offset:35840
	ds_read_b128 v[224:227], v91 offset:37888
	ds_read_b128 v[228:231], v91 offset:39936
	s_waitcnt lgkmcnt(7)
	v_mfma_f32_16x16x32_bf16 v[6:9], v[82:85], v[66:69], v[6:9]
	v_mfma_f32_16x16x32_bf16 v[30:33], v[86:89], v[66:69], v[30:33]
	v_mfma_f32_16x16x32_bf16 v[38:41], v[208:211], v[66:69], v[38:41]
	v_mfma_f32_16x16x32_bf16 v[42:45], v[212:215], v[66:69], v[42:45]
	ds_read_b128 v[66:69], v255 offset:0
	s_waitcnt lgkmcnt(7)
	v_mfma_f32_16x16x32_bf16 v[46:49], v[82:85], v[70:73], v[46:49]
	v_mfma_f32_16x16x32_bf16 v[26:29], v[86:89], v[70:73], v[26:29]
	v_mfma_f32_16x16x32_bf16 v[14:17], v[208:211], v[70:73], v[14:17]
	v_mfma_f32_16x16x32_bf16 v[10:13], v[212:215], v[70:73], v[10:13]
	ds_read_b128 v[70:73], v255 offset:2048
	s_waitcnt lgkmcnt(7)
	v_mfma_f32_16x16x32_bf16 v[34:37], v[82:85], v[74:77], v[34:37]
	v_mfma_f32_16x16x32_bf16 v[22:25], v[86:89], v[74:77], v[22:25]
	v_mfma_f32_16x16x32_bf16 v[18:21], v[208:211], v[74:77], v[18:21]
	v_mfma_f32_16x16x32_bf16 v[62:65], v[212:215], v[74:77], v[62:65]
	ds_read_b128 v[74:77], v255 offset:4096
	s_waitcnt lgkmcnt(7)
	v_mfma_f32_16x16x32_bf16 v[58:61], v[82:85], v[78:81], v[58:61]
	v_mfma_f32_16x16x32_bf16 v[54:57], v[86:89], v[78:81], v[54:57]
	v_mfma_f32_16x16x32_bf16 v[50:53], v[208:211], v[78:81], v[50:53]
	v_mfma_f32_16x16x32_bf16 v[2:5], v[212:215], v[78:81], v[2:5]
	ds_read_b128 v[78:81], v255 offset:6144
	s_waitcnt lgkmcnt(3)
	v_mfma_f32_16x16x32_bf16 v[6:9], v[216:219], v[66:69], v[6:9]
	v_mfma_f32_16x16x32_bf16 v[30:33], v[220:223], v[66:69], v[30:33]
	v_mfma_f32_16x16x32_bf16 v[38:41], v[224:227], v[66:69], v[38:41]
	v_mfma_f32_16x16x32_bf16 v[42:45], v[228:231], v[66:69], v[42:45]
	s_waitcnt lgkmcnt(2)
	v_mfma_f32_16x16x32_bf16 v[46:49], v[216:219], v[70:73], v[46:49]
	v_mfma_f32_16x16x32_bf16 v[26:29], v[220:223], v[70:73], v[26:29]
	v_mfma_f32_16x16x32_bf16 v[14:17], v[224:227], v[70:73], v[14:17]
	v_mfma_f32_16x16x32_bf16 v[10:13], v[228:231], v[70:73], v[10:13]
	s_waitcnt vmcnt(6)
	s_waitcnt lgkmcnt(0)
	s_barrier
	s_add_i32 m0, s67, 0x10000
	s_nop 0
	global_load_lds_dwordx4 v188, s[80:81]
	s_add_i32 m0, s67, 0x12000
	s_nop 0
	global_load_lds_dwordx4 v189, s[80:81]
	s_add_i32 m0, s67, 0x14000
	s_nop 0
	global_load_lds_dwordx4 v190, s[80:81]
	s_add_i32 m0, s67, 0x16000
	s_nop 0
	global_load_lds_dwordx4 v191, s[80:81]
	s_add_i32 m0, s67, 0x20400
	s_nop 0
	global_load_lds_dwordx4 v205, s[96:97]
	s_add_i32 m0, s67, 0x22400
	s_nop 0
	global_load_lds_dwordx4 v206, s[96:97]
	s_add_u32 s80, s80, 0x80
	s_addc_u32 s81, s81, 0
	s_add_u32 s96, s96, 0x80
	s_addc_u32 s97, s97, 0
	ds_read_b128 v[82:85], v90 offset:0
	ds_read_b128 v[86:89], v90 offset:2048
	ds_read_b128 v[208:211], v90 offset:4096
	ds_read_b128 v[212:215], v90 offset:6144
	ds_read_b128 v[66:69], v207 offset:0
	ds_read_b128 v[70:73], v207 offset:2048
	v_mfma_f32_16x16x32_bf16 v[34:37], v[216:219], v[74:77], v[34:37]
	v_mfma_f32_16x16x32_bf16 v[22:25], v[220:223], v[74:77], v[22:25]
	v_mfma_f32_16x16x32_bf16 v[18:21], v[224:227], v[74:77], v[18:21]
	v_mfma_f32_16x16x32_bf16 v[62:65], v[228:231], v[74:77], v[62:65]
	ds_read_b128 v[74:77], v207 offset:4096
	v_mfma_f32_16x16x32_bf16 v[58:61], v[216:219], v[78:81], v[58:61]
	v_mfma_f32_16x16x32_bf16 v[54:57], v[220:223], v[78:81], v[54:57]
	v_mfma_f32_16x16x32_bf16 v[50:53], v[224:227], v[78:81], v[50:53]
	v_mfma_f32_16x16x32_bf16 v[2:5], v[228:231], v[78:81], v[2:5]
	ds_read_b128 v[78:81], v207 offset:6144
	ds_read_b128 v[216:219], v91 offset:0
	ds_read_b128 v[220:223], v91 offset:2048
	ds_read_b128 v[224:227], v91 offset:4096
	ds_read_b128 v[228:231], v91 offset:6144
	s_waitcnt lgkmcnt(7)
	v_mfma_f32_16x16x32_bf16 v[6:9], v[82:85], v[66:69], v[6:9]
	v_mfma_f32_16x16x32_bf16 v[30:33], v[86:89], v[66:69], v[30:33]
	v_mfma_f32_16x16x32_bf16 v[38:41], v[208:211], v[66:69], v[38:41]
	v_mfma_f32_16x16x32_bf16 v[42:45], v[212:215], v[66:69], v[42:45]
	ds_read_b128 v[66:69], v119 offset:0
	s_waitcnt lgkmcnt(7)
	v_mfma_f32_16x16x32_bf16 v[46:49], v[82:85], v[70:73], v[46:49]
	v_mfma_f32_16x16x32_bf16 v[26:29], v[86:89], v[70:73], v[26:29]
	v_mfma_f32_16x16x32_bf16 v[14:17], v[208:211], v[70:73], v[14:17]
	v_mfma_f32_16x16x32_bf16 v[10:13], v[212:215], v[70:73], v[10:13]
	ds_read_b128 v[70:73], v119 offset:2048
	s_waitcnt lgkmcnt(7)
	v_mfma_f32_16x16x32_bf16 v[34:37], v[82:85], v[74:77], v[34:37]
	v_mfma_f32_16x16x32_bf16 v[22:25], v[86:89], v[74:77], v[22:25]
	v_mfma_f32_16x16x32_bf16 v[18:21], v[208:211], v[74:77], v[18:21]
	v_mfma_f32_16x16x32_bf16 v[62:65], v[212:215], v[74:77], v[62:65]
	ds_read_b128 v[74:77], v119 offset:4096
	s_waitcnt lgkmcnt(7)
	v_mfma_f32_16x16x32_bf16 v[58:61], v[82:85], v[78:81], v[58:61]
	v_mfma_f32_16x16x32_bf16 v[54:57], v[86:89], v[78:81], v[54:57]
	v_mfma_f32_16x16x32_bf16 v[50:53], v[208:211], v[78:81], v[50:53]
	v_mfma_f32_16x16x32_bf16 v[2:5], v[212:215], v[78:81], v[2:5]
	ds_read_b128 v[78:81], v119 offset:6144
	s_waitcnt lgkmcnt(3)
	v_mfma_f32_16x16x32_bf16 v[6:9], v[216:219], v[66:69], v[6:9]
	s_waitcnt vmcnt(30)
	v_mfma_f32_16x16x32_bf16 v[30:33], v[220:223], v[66:69], v[30:33]
	v_mfma_f32_16x16x32_bf16 v[38:41], v[224:227], v[66:69], v[38:41]
	v_mfma_f32_16x16x32_bf16 v[42:45], v[228:231], v[66:69], v[42:45]
	v_cvt_f32_ubyte0_e32 v248, v232
	v_cvt_f32_ubyte1_e32 v249, v232
	v_cvt_f32_ubyte2_e32 v250, v232
	v_cvt_f32_ubyte3_e32 v251, v232
	v_mul_f32_e32 v248, s34, v248
	v_mul_f32_e32 v249, s34, v249
	v_mul_f32_e32 v250, s34, v250
	v_mul_f32_e32 v251, s34, v251
	v_fma_f32 v184, v6, v248, v184
	v_fma_f32 v185, v7, v249, v185
	v_fma_f32 v186, v8, v250, v186
	v_fma_f32 v187, v9, v251, v187
	s_waitcnt lgkmcnt(2)
	v_mfma_f32_16x16x32_bf16 v[46:49], v[216:219], v[70:73], v[46:49]
	v_cvt_f32_ubyte0_e32 v248, v233
	v_cvt_f32_ubyte1_e32 v249, v233
	v_cvt_f32_ubyte2_e32 v250, v233
	v_cvt_f32_ubyte3_e32 v251, v233
	v_mul_f32_e32 v248, s34, v248
	v_mul_f32_e32 v249, s34, v249
	v_mul_f32_e32 v250, s34, v250
	v_mul_f32_e32 v251, s34, v251
	v_fma_f32 v180, v30, v248, v180
	v_fma_f32 v181, v31, v249, v181
	v_fma_f32 v182, v32, v250, v182
	v_fma_f32 v183, v33, v251, v183
	v_mfma_f32_16x16x32_bf16 v[26:29], v[220:223], v[70:73], v[26:29]
	v_cvt_f32_ubyte0_e32 v248, v234
	v_cvt_f32_ubyte1_e32 v249, v234
	v_cvt_f32_ubyte2_e32 v250, v234
	v_cvt_f32_ubyte3_e32 v251, v234
	v_mul_f32_e32 v248, s34, v248
	v_mul_f32_e32 v249, s34, v249
	v_mul_f32_e32 v250, s34, v250
	v_mul_f32_e32 v251, s34, v251
	v_fma_f32 v176, v38, v248, v176
	v_fma_f32 v177, v39, v249, v177
	v_fma_f32 v178, v40, v250, v178
	v_fma_f32 v179, v41, v251, v179
	v_mfma_f32_16x16x32_bf16 v[14:17], v[224:227], v[70:73], v[14:17]
	v_cvt_f32_ubyte0_e32 v248, v235
	v_cvt_f32_ubyte1_e32 v249, v235
	v_cvt_f32_ubyte2_e32 v250, v235
	v_cvt_f32_ubyte3_e32 v251, v235
	v_mul_f32_e32 v248, s34, v248
	v_mul_f32_e32 v249, s34, v249
	v_mul_f32_e32 v250, s34, v250
	v_mul_f32_e32 v251, s34, v251
	v_fma_f32 v172, v42, v248, v172
	v_fma_f32 v173, v43, v249, v173
	v_fma_f32 v174, v44, v250, v174
	v_fma_f32 v175, v45, v251, v175
	v_mfma_f32_16x16x32_bf16 v[10:13], v[228:231], v[70:73], v[10:13]
	v_cvt_f32_ubyte0_e32 v248, v236
	v_cvt_f32_ubyte1_e32 v249, v236
	v_cvt_f32_ubyte2_e32 v250, v236
	v_cvt_f32_ubyte3_e32 v251, v236
	v_mul_f32_e32 v248, s34, v248
	v_mul_f32_e32 v249, s34, v249
	v_mul_f32_e32 v250, s34, v250
	v_mul_f32_e32 v251, s34, v251
	v_fma_f32 v168, v46, v248, v168
	v_fma_f32 v169, v47, v249, v169
	v_fma_f32 v170, v48, v250, v170
	v_fma_f32 v171, v49, v251, v171
	s_waitcnt vmcnt(6)
	s_waitcnt lgkmcnt(0)
	s_barrier
	s_add_i32 m0, s67, 0x0
	s_nop 0
	global_load_lds_dwordx4 v188, s[80:81]
	s_add_i32 m0, s67, 0x2000
	s_nop 0
	global_load_lds_dwordx4 v189, s[80:81]
	s_add_i32 m0, s67, 0x4000
	s_nop 0
	global_load_lds_dwordx4 v190, s[80:81]
	s_add_i32 m0, s67, 0x6000
	s_nop 0
	global_load_lds_dwordx4 v191, s[80:81]
	s_add_i32 m0, s67, 0x18000
	s_nop 0
	global_load_lds_dwordx4 v205, s[96:97]
	s_add_i32 m0, s67, 0x1a000
	s_nop 0
	global_load_lds_dwordx4 v206, s[96:97]
	s_add_u32 s80, s80, 0x80
	s_addc_u32 s81, s81, 0
	s_add_u32 s96, s96, 0x80
	s_addc_u32 s97, s97, 0
	ds_read_b128 v[82:85], v90 offset:16384
	ds_read_b128 v[86:89], v90 offset:18432
	ds_read_b128 v[208:211], v90 offset:20480
	ds_read_b128 v[212:215], v90 offset:22528
	ds_read_b128 v[66:69], v207 offset:32768
	ds_read_b128 v[70:73], v207 offset:34816
	v_mfma_f32_16x16x32_bf16 v[34:37], v[216:219], v[74:77], v[34:37]
	v_cvt_f32_ubyte0_e32 v248, v237
	v_cvt_f32_ubyte1_e32 v249, v237
	v_cvt_f32_ubyte2_e32 v250, v237
	v_cvt_f32_ubyte3_e32 v251, v237
	v_mul_f32_e32 v248, s34, v248
	v_mul_f32_e32 v249, s34, v249
	v_mul_f32_e32 v250, s34, v250
	v_mul_f32_e32 v251, s34, v251
	v_fma_f32 v164, v26, v248, v164
	v_fma_f32 v165, v27, v249, v165
	v_fma_f32 v166, v28, v250, v166
	v_fma_f32 v167, v29, v251, v167
	v_mfma_f32_16x16x32_bf16 v[22:25], v[220:223], v[74:77], v[22:25]
	v_cvt_f32_ubyte0_e32 v248, v238
	v_cvt_f32_ubyte1_e32 v249, v238
	v_cvt_f32_ubyte2_e32 v250, v238
	v_cvt_f32_ubyte3_e32 v251, v238
	v_mul_f32_e32 v248, s34, v248
	v_mul_f32_e32 v249, s34, v249
	v_mul_f32_e32 v250, s34, v250
	v_mul_f32_e32 v251, s34, v251
	v_fma_f32 v160, v14, v248, v160
	v_fma_f32 v161, v15, v249, v161
	v_fma_f32 v162, v16, v250, v162
	v_fma_f32 v163, v17, v251, v163
	v_mfma_f32_16x16x32_bf16 v[18:21], v[224:227], v[74:77], v[18:21]
	v_cvt_f32_ubyte0_e32 v248, v239
	v_cvt_f32_ubyte1_e32 v249, v239
	v_cvt_f32_ubyte2_e32 v250, v239
	v_cvt_f32_ubyte3_e32 v251, v239
	v_mul_f32_e32 v248, s34, v248
	v_mul_f32_e32 v249, s34, v249
	v_mul_f32_e32 v250, s34, v250
	v_mul_f32_e32 v251, s34, v251
	v_fma_f32 v156, v10, v248, v156
	v_fma_f32 v157, v11, v249, v157
	v_fma_f32 v158, v12, v250, v158
	v_fma_f32 v159, v13, v251, v159
	v_mfma_f32_16x16x32_bf16 v[62:65], v[228:231], v[74:77], v[62:65]
	v_cvt_f32_ubyte0_e32 v248, v240
	v_cvt_f32_ubyte1_e32 v249, v240
	v_cvt_f32_ubyte2_e32 v250, v240
	v_cvt_f32_ubyte3_e32 v251, v240
	v_mul_f32_e32 v248, s34, v248
	v_mul_f32_e32 v249, s34, v249
	v_mul_f32_e32 v250, s34, v250
	v_mul_f32_e32 v251, s34, v251
	v_fma_f32 v136, v34, v248, v136
	v_fma_f32 v137, v35, v249, v137
	v_fma_f32 v150, v36, v250, v150
	v_fma_f32 v151, v37, v251, v151
	ds_read_b128 v[74:77], v207 offset:36864
	v_mfma_f32_16x16x32_bf16 v[58:61], v[216:219], v[78:81], v[58:61]
	v_cvt_f32_ubyte0_e32 v248, v241
	v_cvt_f32_ubyte1_e32 v249, v241
	v_cvt_f32_ubyte2_e32 v250, v241
	v_cvt_f32_ubyte3_e32 v251, v241
	v_mul_f32_e32 v248, s34, v248
	v_mul_f32_e32 v249, s34, v249
	v_mul_f32_e32 v250, s34, v250
	v_mul_f32_e32 v251, s34, v251
	v_fma_f32 v130, v22, v248, v130
	v_fma_f32 v131, v23, v249, v131
	v_fma_f32 v134, v24, v250, v134
	v_fma_f32 v135, v25, v251, v135
	v_mfma_f32_16x16x32_bf16 v[54:57], v[220:223], v[78:81], v[54:57]
	v_cvt_f32_ubyte0_e32 v248, v242
	v_cvt_f32_ubyte1_e32 v249, v242
	v_cvt_f32_ubyte2_e32 v250, v242
	v_cvt_f32_ubyte3_e32 v251, v242
	v_mul_f32_e32 v248, s34, v248
	v_mul_f32_e32 v249, s34, v249
	v_mul_f32_e32 v250, s34, v250
	v_mul_f32_e32 v251, s34, v251
	v_fma_f32 v124, v18, v248, v124
	v_fma_f32 v125, v19, v249, v125
	v_fma_f32 v126, v20, v250, v126
	v_fma_f32 v127, v21, v251, v127
	v_mfma_f32_16x16x32_bf16 v[50:53], v[224:227], v[78:81], v[50:53]
	v_cvt_f32_ubyte0_e32 v248, v243
	v_cvt_f32_ubyte1_e32 v249, v243
	v_cvt_f32_ubyte2_e32 v250, v243
	v_cvt_f32_ubyte3_e32 v251, v243
	v_mul_f32_e32 v248, s34, v248
	v_mul_f32_e32 v249, s34, v249
	v_mul_f32_e32 v250, s34, v250
	v_mul_f32_e32 v251, s34, v251
	v_fma_f32 v120, v62, v248, v120
	v_fma_f32 v121, v63, v249, v121
	v_fma_f32 v122, v64, v250, v122
	v_fma_f32 v123, v65, v251, v123
	v_mfma_f32_16x16x32_bf16 v[2:5], v[228:231], v[78:81], v[2:5]
	v_cvt_f32_ubyte0_e32 v248, v244
	v_cvt_f32_ubyte1_e32 v249, v244
	v_cvt_f32_ubyte2_e32 v250, v244
	v_cvt_f32_ubyte3_e32 v251, v244
	v_mul_f32_e32 v248, s34, v248
	v_mul_f32_e32 v249, s34, v249
	v_mul_f32_e32 v250, s34, v250
	v_mul_f32_e32 v251, s34, v251
	v_fma_f32 v114, v58, v248, v114
	v_fma_f32 v115, v59, v249, v115
	v_fma_f32 v116, v60, v250, v116
	v_fma_f32 v117, v61, v251, v117
	ds_read_b128 v[78:81], v207 offset:38912
	s_nop 7
	s_nop 3
	v_cvt_f32_ubyte0_e32 v248, v245
	v_cvt_f32_ubyte1_e32 v249, v245
	v_cvt_f32_ubyte2_e32 v250, v245
	v_cvt_f32_ubyte3_e32 v251, v245
	v_mul_f32_e32 v248, s34, v248
	v_mul_f32_e32 v249, s34, v249
	v_mul_f32_e32 v250, s34, v250
	v_mul_f32_e32 v251, s34, v251
	v_fma_f32 v106, v54, v248, v106
	v_fma_f32 v107, v55, v249, v107
	v_fma_f32 v108, v56, v250, v108
	v_fma_f32 v109, v57, v251, v109
	v_cvt_f32_ubyte0_e32 v248, v246
	v_cvt_f32_ubyte1_e32 v249, v246
	v_cvt_f32_ubyte2_e32 v250, v246
	v_cvt_f32_ubyte3_e32 v251, v246
	v_mul_f32_e32 v248, s34, v248
	v_mul_f32_e32 v249, s34, v249
	v_mul_f32_e32 v250, s34, v250
	v_mul_f32_e32 v251, s34, v251
	v_fma_f32 v100, v50, v248, v100
	v_fma_f32 v101, v51, v249, v101
	v_fma_f32 v102, v52, v250, v102
	v_fma_f32 v103, v53, v251, v103
	v_cvt_f32_ubyte0_e32 v248, v247
	v_cvt_f32_ubyte1_e32 v249, v247
	v_cvt_f32_ubyte2_e32 v250, v247
	v_cvt_f32_ubyte3_e32 v251, v247
	v_mul_f32_e32 v248, s34, v248
	v_mul_f32_e32 v249, s34, v249
	v_mul_f32_e32 v250, s34, v250
	v_mul_f32_e32 v251, s34, v251
	v_fma_f32 v96, v2, v248, v96
	v_fma_f32 v97, v3, v249, v97
	v_fma_f32 v98, v4, v250, v98
	v_fma_f32 v99, v5, v251, v99
	s_add_u32 s98, s86, 0x2200
	s_addc_u32 s99, s87, 0
	global_load_dword v92, v93, s[98:99]
	ds_read_b128 v[216:219], v91 offset:16384
	ds_read_b128 v[220:223], v91 offset:18432
	ds_read_b128 v[224:227], v91 offset:20480
	ds_read_b128 v[228:231], v91 offset:22528
	s_waitcnt lgkmcnt(7)
	v_mfma_f32_16x16x32_bf16 v[6:9], v[82:85], v[66:69], 0
	v_mfma_f32_16x16x32_bf16 v[30:33], v[86:89], v[66:69], 0
	v_mfma_f32_16x16x32_bf16 v[38:41], v[208:211], v[66:69], 0
	v_mfma_f32_16x16x32_bf16 v[42:45], v[212:215], v[66:69], 0
	ds_read_b128 v[66:69], v119 offset:32768
	s_waitcnt lgkmcnt(7)
	v_mfma_f32_16x16x32_bf16 v[46:49], v[82:85], v[70:73], 0
	v_mfma_f32_16x16x32_bf16 v[26:29], v[86:89], v[70:73], 0
	v_mfma_f32_16x16x32_bf16 v[14:17], v[208:211], v[70:73], 0
	v_mfma_f32_16x16x32_bf16 v[10:13], v[212:215], v[70:73], 0
	ds_read_b128 v[70:73], v119 offset:34816
	s_waitcnt lgkmcnt(7)
	v_mfma_f32_16x16x32_bf16 v[34:37], v[82:85], v[74:77], 0
	v_mfma_f32_16x16x32_bf16 v[22:25], v[86:89], v[74:77], 0
	v_mfma_f32_16x16x32_bf16 v[18:21], v[208:211], v[74:77], 0
	v_mfma_f32_16x16x32_bf16 v[62:65], v[212:215], v[74:77], 0
	ds_read_b128 v[74:77], v119 offset:36864
	s_waitcnt lgkmcnt(7)
	v_mfma_f32_16x16x32_bf16 v[58:61], v[82:85], v[78:81], 0
	v_mfma_f32_16x16x32_bf16 v[54:57], v[86:89], v[78:81], 0
	v_mfma_f32_16x16x32_bf16 v[50:53], v[208:211], v[78:81], 0
	v_mfma_f32_16x16x32_bf16 v[2:5], v[212:215], v[78:81], 0
	ds_read_b128 v[78:81], v119 offset:38912
	s_waitcnt lgkmcnt(3)
	v_mfma_f32_16x16x32_bf16 v[6:9], v[216:219], v[66:69], v[6:9]
	v_mfma_f32_16x16x32_bf16 v[30:33], v[220:223], v[66:69], v[30:33]
	v_mfma_f32_16x16x32_bf16 v[38:41], v[224:227], v[66:69], v[38:41]
	v_mfma_f32_16x16x32_bf16 v[42:45], v[228:231], v[66:69], v[42:45]
	s_waitcnt lgkmcnt(2)
	v_mfma_f32_16x16x32_bf16 v[46:49], v[216:219], v[70:73], v[46:49]
	v_mfma_f32_16x16x32_bf16 v[26:29], v[220:223], v[70:73], v[26:29]
	v_mfma_f32_16x16x32_bf16 v[14:17], v[224:227], v[70:73], v[14:17]
	v_mfma_f32_16x16x32_bf16 v[10:13], v[228:231], v[70:73], v[10:13]
	s_waitcnt vmcnt(7)
	s_waitcnt lgkmcnt(0)
	s_barrier
	s_add_i32 m0, s67, 0x8000
	s_nop 0
	global_load_lds_dwordx4 v188, s[80:81]
	s_add_i32 m0, s67, 0xa000
	s_nop 0
	global_load_lds_dwordx4 v189, s[80:81]
	s_add_i32 m0, s67, 0xc000
	s_nop 0
	global_load_lds_dwordx4 v190, s[80:81]
	s_add_i32 m0, s67, 0xe000
	s_nop 0
	global_load_lds_dwordx4 v191, s[80:81]
	s_add_i32 m0, s67, 0x1c000
	s_nop 0
	global_load_lds_dwordx4 v205, s[96:97]
	s_add_i32 m0, s67, 0x1e000
	s_nop 0
	global_load_lds_dwordx4 v206, s[96:97]
	s_add_u32 s80, s80, 0x80
	s_addc_u32 s81, s81, 0
	s_add_u32 s96, s96, 0x80
	s_addc_u32 s97, s97, 0
	ds_read_b128 v[82:85], v90 offset:33792
	ds_read_b128 v[86:89], v90 offset:35840
	ds_read_b128 v[208:211], v90 offset:37888
	ds_read_b128 v[212:215], v90 offset:39936
	ds_read_b128 v[66:69], v0 offset:0
	ds_read_b128 v[70:73], v0 offset:2048
	v_mfma_f32_16x16x32_bf16 v[34:37], v[216:219], v[74:77], v[34:37]
	v_mfma_f32_16x16x32_bf16 v[22:25], v[220:223], v[74:77], v[22:25]
	v_mfma_f32_16x16x32_bf16 v[18:21], v[224:227], v[74:77], v[18:21]
	v_mfma_f32_16x16x32_bf16 v[62:65], v[228:231], v[74:77], v[62:65]
	ds_read_b128 v[74:77], v0 offset:4096
	v_mfma_f32_16x16x32_bf16 v[58:61], v[216:219], v[78:81], v[58:61]
	v_mfma_f32_16x16x32_bf16 v[54:57], v[220:223], v[78:81], v[54:57]
	v_mfma_f32_16x16x32_bf16 v[50:53], v[224:227], v[78:81], v[50:53]
	v_mfma_f32_16x16x32_bf16 v[2:5], v[228:231], v[78:81], v[2:5]
	ds_read_b128 v[78:81], v0 offset:6144
	ds_read_b128 v[216:219], v91 offset:33792
	ds_read_b128 v[220:223], v91 offset:35840
	ds_read_b128 v[224:227], v91 offset:37888
	ds_read_b128 v[228:231], v91 offset:39936
	s_waitcnt lgkmcnt(7)
	v_mfma_f32_16x16x32_bf16 v[6:9], v[82:85], v[66:69], v[6:9]
	v_mfma_f32_16x16x32_bf16 v[30:33], v[86:89], v[66:69], v[30:33]
	v_mfma_f32_16x16x32_bf16 v[38:41], v[208:211], v[66:69], v[38:41]
	v_mfma_f32_16x16x32_bf16 v[42:45], v[212:215], v[66:69], v[42:45]
	ds_read_b128 v[66:69], v255 offset:0
	s_waitcnt lgkmcnt(7)
	v_mfma_f32_16x16x32_bf16 v[46:49], v[82:85], v[70:73], v[46:49]
	v_mfma_f32_16x16x32_bf16 v[26:29], v[86:89], v[70:73], v[26:29]
	v_mfma_f32_16x16x32_bf16 v[14:17], v[208:211], v[70:73], v[14:17]
	v_mfma_f32_16x16x32_bf16 v[10:13], v[212:215], v[70:73], v[10:13]
	ds_read_b128 v[70:73], v255 offset:2048
	s_waitcnt lgkmcnt(7)
	v_mfma_f32_16x16x32_bf16 v[34:37], v[82:85], v[74:77], v[34:37]
	v_mfma_f32_16x16x32_bf16 v[22:25], v[86:89], v[74:77], v[22:25]
	v_mfma_f32_16x16x32_bf16 v[18:21], v[208:211], v[74:77], v[18:21]
	v_mfma_f32_16x16x32_bf16 v[62:65], v[212:215], v[74:77], v[62:65]
	ds_read_b128 v[74:77], v255 offset:4096
	s_waitcnt lgkmcnt(7)
	v_mfma_f32_16x16x32_bf16 v[58:61], v[82:85], v[78:81], v[58:61]
	v_mfma_f32_16x16x32_bf16 v[54:57], v[86:89], v[78:81], v[54:57]
	v_mfma_f32_16x16x32_bf16 v[50:53], v[208:211], v[78:81], v[50:53]
	v_mfma_f32_16x16x32_bf16 v[2:5], v[212:215], v[78:81], v[2:5]
	ds_read_b128 v[78:81], v255 offset:6144
	s_waitcnt lgkmcnt(3)
	v_mfma_f32_16x16x32_bf16 v[6:9], v[216:219], v[66:69], v[6:9]
	v_mfma_f32_16x16x32_bf16 v[30:33], v[220:223], v[66:69], v[30:33]
	v_mfma_f32_16x16x32_bf16 v[38:41], v[224:227], v[66:69], v[38:41]
	v_mfma_f32_16x16x32_bf16 v[42:45], v[228:231], v[66:69], v[42:45]
	s_waitcnt lgkmcnt(2)
	v_mfma_f32_16x16x32_bf16 v[46:49], v[216:219], v[70:73], v[46:49]
	v_mfma_f32_16x16x32_bf16 v[26:29], v[220:223], v[70:73], v[26:29]
	v_mfma_f32_16x16x32_bf16 v[14:17], v[224:227], v[70:73], v[14:17]
	v_mfma_f32_16x16x32_bf16 v[10:13], v[228:231], v[70:73], v[10:13]
	s_waitcnt vmcnt(7)
	s_waitcnt lgkmcnt(0)
	s_barrier
	s_add_i32 m0, s67, 0x10000
	s_nop 0
	global_load_lds_dwordx4 v188, s[80:81]
	s_add_i32 m0, s67, 0x12000
	s_nop 0
	global_load_lds_dwordx4 v189, s[80:81]
	s_add_i32 m0, s67, 0x14000
	s_nop 0
	global_load_lds_dwordx4 v190, s[80:81]
	s_add_i32 m0, s67, 0x16000
	s_nop 0
	global_load_lds_dwordx4 v191, s[80:81]
	s_add_i32 m0, s67, 0x20400
	s_nop 0
	global_load_lds_dwordx4 v205, s[96:97]
	s_add_i32 m0, s67, 0x22400
	s_nop 0
	global_load_lds_dwordx4 v206, s[96:97]
	s_add_u32 s80, s80, 0x80
	s_addc_u32 s81, s81, 0
	s_add_u32 s96, s96, 0x80
	s_addc_u32 s97, s97, 0
	s_movk_i32 s10, 0x800
	s_mov_b32 s11, 0
	v_lshl_add_u64 v[248:249], v[128:129], 0, s[10:11]
	global_load_dwordx2 v[232:233], v[248:249], off
	global_load_dwordx2 v[234:235], v[248:249], off offset:32
	v_lshl_add_u64 v[248:249], v[132:133], 0, s[10:11]
	global_load_dwordx2 v[236:237], v[248:249], off
	global_load_dwordx2 v[238:239], v[248:249], off offset:32
	v_lshl_add_u64 v[248:249], v[152:153], 0, s[10:11]
	global_load_dwordx2 v[240:241], v[248:249], off
	global_load_dwordx2 v[242:243], v[248:249], off offset:32
	v_lshl_add_u64 v[248:249], v[154:155], 0, s[10:11]
	global_load_dwordx2 v[244:245], v[248:249], off
	global_load_dwordx2 v[246:247], v[248:249], off offset:32
	ds_read_b128 v[82:85], v90 offset:0
	ds_read_b128 v[86:89], v90 offset:2048
	ds_read_b128 v[208:211], v90 offset:4096
	ds_read_b128 v[212:215], v90 offset:6144
	ds_read_b128 v[66:69], v207 offset:0
	ds_read_b128 v[70:73], v207 offset:2048
	v_mfma_f32_16x16x32_bf16 v[34:37], v[216:219], v[74:77], v[34:37]
	v_mfma_f32_16x16x32_bf16 v[22:25], v[220:223], v[74:77], v[22:25]
	v_mfma_f32_16x16x32_bf16 v[18:21], v[224:227], v[74:77], v[18:21]
	v_mfma_f32_16x16x32_bf16 v[62:65], v[228:231], v[74:77], v[62:65]
	ds_read_b128 v[74:77], v207 offset:4096
	v_mfma_f32_16x16x32_bf16 v[58:61], v[216:219], v[78:81], v[58:61]
	v_mfma_f32_16x16x32_bf16 v[54:57], v[220:223], v[78:81], v[54:57]
	v_mfma_f32_16x16x32_bf16 v[50:53], v[224:227], v[78:81], v[50:53]
	v_mfma_f32_16x16x32_bf16 v[2:5], v[228:231], v[78:81], v[2:5]
	ds_read_b128 v[78:81], v207 offset:6144
	ds_read_b128 v[216:219], v91 offset:0
	ds_read_b128 v[220:223], v91 offset:2048
	ds_read_b128 v[224:227], v91 offset:4096
	ds_read_b128 v[228:231], v91 offset:6144
	s_waitcnt lgkmcnt(7)
	v_mfma_f32_16x16x32_bf16 v[6:9], v[82:85], v[66:69], v[6:9]
	v_mfma_f32_16x16x32_bf16 v[30:33], v[86:89], v[66:69], v[30:33]
	v_mfma_f32_16x16x32_bf16 v[38:41], v[208:211], v[66:69], v[38:41]
	v_mfma_f32_16x16x32_bf16 v[42:45], v[212:215], v[66:69], v[42:45]
	ds_read_b128 v[66:69], v119 offset:0
	s_waitcnt lgkmcnt(7)
	v_mfma_f32_16x16x32_bf16 v[46:49], v[82:85], v[70:73], v[46:49]
	v_mfma_f32_16x16x32_bf16 v[26:29], v[86:89], v[70:73], v[26:29]
	v_mfma_f32_16x16x32_bf16 v[14:17], v[208:211], v[70:73], v[14:17]
	v_mfma_f32_16x16x32_bf16 v[10:13], v[212:215], v[70:73], v[10:13]
	ds_read_b128 v[70:73], v119 offset:2048
	s_waitcnt lgkmcnt(7)
	v_mfma_f32_16x16x32_bf16 v[34:37], v[82:85], v[74:77], v[34:37]
	v_mfma_f32_16x16x32_bf16 v[22:25], v[86:89], v[74:77], v[22:25]
	v_mfma_f32_16x16x32_bf16 v[18:21], v[208:211], v[74:77], v[18:21]
	v_mfma_f32_16x16x32_bf16 v[62:65], v[212:215], v[74:77], v[62:65]
	ds_read_b128 v[74:77], v119 offset:4096
	s_waitcnt lgkmcnt(7)
	v_mfma_f32_16x16x32_bf16 v[58:61], v[82:85], v[78:81], v[58:61]
	v_mfma_f32_16x16x32_bf16 v[54:57], v[86:89], v[78:81], v[54:57]
	v_mfma_f32_16x16x32_bf16 v[50:53], v[208:211], v[78:81], v[50:53]
	v_mfma_f32_16x16x32_bf16 v[2:5], v[212:215], v[78:81], v[2:5]
	ds_read_b128 v[78:81], v119 offset:6144
	s_waitcnt lgkmcnt(3)
	v_mfma_f32_16x16x32_bf16 v[6:9], v[216:219], v[66:69], v[6:9]
	v_mfma_f32_16x16x32_bf16 v[30:33], v[220:223], v[66:69], v[30:33]
	v_mfma_f32_16x16x32_bf16 v[38:41], v[224:227], v[66:69], v[38:41]
	v_mfma_f32_16x16x32_bf16 v[42:45], v[228:231], v[66:69], v[42:45]
	s_waitcnt lgkmcnt(2)
	v_mfma_f32_16x16x32_bf16 v[46:49], v[216:219], v[70:73], v[46:49]
	v_mfma_f32_16x16x32_bf16 v[26:29], v[220:223], v[70:73], v[26:29]
	v_mfma_f32_16x16x32_bf16 v[14:17], v[224:227], v[70:73], v[14:17]
	v_mfma_f32_16x16x32_bf16 v[10:13], v[228:231], v[70:73], v[10:13]
	s_waitcnt vmcnt(14)
	s_waitcnt lgkmcnt(0)
	s_barrier
	s_add_i32 m0, s67, 0x0
	s_nop 0
	global_load_lds_dwordx4 v188, s[80:81]
	s_add_i32 m0, s67, 0x2000
	s_nop 0
	global_load_lds_dwordx4 v189, s[80:81]
	s_add_i32 m0, s67, 0x4000
	s_nop 0
	global_load_lds_dwordx4 v190, s[80:81]
	s_add_i32 m0, s67, 0x6000
	s_nop 0
	global_load_lds_dwordx4 v191, s[80:81]
	s_add_i32 m0, s67, 0x18000
	s_nop 0
	global_load_lds_dwordx4 v205, s[96:97]
	s_add_i32 m0, s67, 0x1a000
	s_nop 0
	global_load_lds_dwordx4 v206, s[96:97]
	s_add_u32 s80, s80, 0x80
	s_addc_u32 s81, s81, 0
	s_add_u32 s96, s96, 0x80
	s_addc_u32 s97, s97, 0
	ds_read_b128 v[82:85], v90 offset:16384
	ds_read_b128 v[86:89], v90 offset:18432
	ds_read_b128 v[208:211], v90 offset:20480
	ds_read_b128 v[212:215], v90 offset:22528
	ds_read_b128 v[66:69], v207 offset:32768
	ds_read_b128 v[70:73], v207 offset:34816
	v_mfma_f32_16x16x32_bf16 v[34:37], v[216:219], v[74:77], v[34:37]
	v_mfma_f32_16x16x32_bf16 v[22:25], v[220:223], v[74:77], v[22:25]
	v_mfma_f32_16x16x32_bf16 v[18:21], v[224:227], v[74:77], v[18:21]
	v_mfma_f32_16x16x32_bf16 v[62:65], v[228:231], v[74:77], v[62:65]
	ds_read_b128 v[74:77], v207 offset:36864
	v_mfma_f32_16x16x32_bf16 v[58:61], v[216:219], v[78:81], v[58:61]
	v_mfma_f32_16x16x32_bf16 v[54:57], v[220:223], v[78:81], v[54:57]
	v_mfma_f32_16x16x32_bf16 v[50:53], v[224:227], v[78:81], v[50:53]
	v_mfma_f32_16x16x32_bf16 v[2:5], v[228:231], v[78:81], v[2:5]
	ds_read_b128 v[78:81], v207 offset:38912
	ds_read_b128 v[216:219], v91 offset:16384
	ds_read_b128 v[220:223], v91 offset:18432
	ds_read_b128 v[224:227], v91 offset:20480
	ds_read_b128 v[228:231], v91 offset:22528
	s_waitcnt lgkmcnt(7)
	v_mfma_f32_16x16x32_bf16 v[6:9], v[82:85], v[66:69], v[6:9]
	v_mfma_f32_16x16x32_bf16 v[30:33], v[86:89], v[66:69], v[30:33]
	v_mfma_f32_16x16x32_bf16 v[38:41], v[208:211], v[66:69], v[38:41]
	v_mfma_f32_16x16x32_bf16 v[42:45], v[212:215], v[66:69], v[42:45]
	ds_read_b128 v[66:69], v119 offset:32768
	s_waitcnt lgkmcnt(7)
	v_mfma_f32_16x16x32_bf16 v[46:49], v[82:85], v[70:73], v[46:49]
	v_mfma_f32_16x16x32_bf16 v[26:29], v[86:89], v[70:73], v[26:29]
	v_mfma_f32_16x16x32_bf16 v[14:17], v[208:211], v[70:73], v[14:17]
	v_mfma_f32_16x16x32_bf16 v[10:13], v[212:215], v[70:73], v[10:13]
	ds_read_b128 v[70:73], v119 offset:34816
	s_waitcnt lgkmcnt(7)
	v_mfma_f32_16x16x32_bf16 v[34:37], v[82:85], v[74:77], v[34:37]
	v_mfma_f32_16x16x32_bf16 v[22:25], v[86:89], v[74:77], v[22:25]
	v_mfma_f32_16x16x32_bf16 v[18:21], v[208:211], v[74:77], v[18:21]
	v_mfma_f32_16x16x32_bf16 v[62:65], v[212:215], v[74:77], v[62:65]
	ds_read_b128 v[74:77], v119 offset:36864
	s_waitcnt lgkmcnt(7)
	v_mfma_f32_16x16x32_bf16 v[58:61], v[82:85], v[78:81], v[58:61]
	v_mfma_f32_16x16x32_bf16 v[54:57], v[86:89], v[78:81], v[54:57]
	v_mfma_f32_16x16x32_bf16 v[50:53], v[208:211], v[78:81], v[50:53]
	v_mfma_f32_16x16x32_bf16 v[2:5], v[212:215], v[78:81], v[2:5]
	ds_read_b128 v[78:81], v119 offset:38912
	s_waitcnt lgkmcnt(3)
	v_mfma_f32_16x16x32_bf16 v[6:9], v[216:219], v[66:69], v[6:9]
	v_mfma_f32_16x16x32_bf16 v[30:33], v[220:223], v[66:69], v[30:33]
	v_mfma_f32_16x16x32_bf16 v[38:41], v[224:227], v[66:69], v[38:41]
	v_mfma_f32_16x16x32_bf16 v[42:45], v[228:231], v[66:69], v[42:45]
	s_waitcnt lgkmcnt(2)
	v_mfma_f32_16x16x32_bf16 v[46:49], v[216:219], v[70:73], v[46:49]
	v_mfma_f32_16x16x32_bf16 v[26:29], v[220:223], v[70:73], v[26:29]
	v_mfma_f32_16x16x32_bf16 v[14:17], v[224:227], v[70:73], v[14:17]
	v_mfma_f32_16x16x32_bf16 v[10:13], v[228:231], v[70:73], v[10:13]
	s_waitcnt vmcnt(14)
	s_waitcnt lgkmcnt(0)
	s_barrier
	s_add_i32 m0, s67, 0x8000
	s_nop 0
	global_load_lds_dwordx4 v188, s[80:81]
	s_add_i32 m0, s67, 0xa000
	s_nop 0
	global_load_lds_dwordx4 v189, s[80:81]
	s_add_i32 m0, s67, 0xc000
	s_nop 0
	global_load_lds_dwordx4 v190, s[80:81]
	s_add_i32 m0, s67, 0xe000
	s_nop 0
	global_load_lds_dwordx4 v191, s[80:81]
	s_add_i32 m0, s67, 0x1c000
	s_nop 0
	global_load_lds_dwordx4 v205, s[96:97]
	s_add_i32 m0, s67, 0x1e000
	s_nop 0
	global_load_lds_dwordx4 v206, s[96:97]
	s_add_u32 s80, s80, 0x80
	s_addc_u32 s81, s81, 0
	s_add_u32 s96, s96, 0x80
	s_addc_u32 s97, s97, 0
	ds_read_b128 v[82:85], v90 offset:33792
	ds_read_b128 v[86:89], v90 offset:35840
	ds_read_b128 v[208:211], v90 offset:37888
	ds_read_b128 v[212:215], v90 offset:39936
	ds_read_b128 v[66:69], v0 offset:0
	ds_read_b128 v[70:73], v0 offset:2048
	v_mfma_f32_16x16x32_bf16 v[34:37], v[216:219], v[74:77], v[34:37]
	v_mfma_f32_16x16x32_bf16 v[22:25], v[220:223], v[74:77], v[22:25]
	v_mfma_f32_16x16x32_bf16 v[18:21], v[224:227], v[74:77], v[18:21]
	v_mfma_f32_16x16x32_bf16 v[62:65], v[228:231], v[74:77], v[62:65]
	ds_read_b128 v[74:77], v0 offset:4096
	v_mfma_f32_16x16x32_bf16 v[58:61], v[216:219], v[78:81], v[58:61]
	v_mfma_f32_16x16x32_bf16 v[54:57], v[220:223], v[78:81], v[54:57]
	v_mfma_f32_16x16x32_bf16 v[50:53], v[224:227], v[78:81], v[50:53]
	v_mfma_f32_16x16x32_bf16 v[2:5], v[228:231], v[78:81], v[2:5]
	ds_read_b128 v[78:81], v0 offset:6144
	ds_read_b128 v[216:219], v91 offset:33792
	ds_read_b128 v[220:223], v91 offset:35840
	ds_read_b128 v[224:227], v91 offset:37888
	ds_read_b128 v[228:231], v91 offset:39936
	s_waitcnt lgkmcnt(7)
	v_mfma_f32_16x16x32_bf16 v[6:9], v[82:85], v[66:69], v[6:9]
	v_mfma_f32_16x16x32_bf16 v[30:33], v[86:89], v[66:69], v[30:33]
	v_mfma_f32_16x16x32_bf16 v[38:41], v[208:211], v[66:69], v[38:41]
	v_mfma_f32_16x16x32_bf16 v[42:45], v[212:215], v[66:69], v[42:45]
	ds_read_b128 v[66:69], v255 offset:0
	s_waitcnt lgkmcnt(7)
	v_mfma_f32_16x16x32_bf16 v[46:49], v[82:85], v[70:73], v[46:49]
	v_mfma_f32_16x16x32_bf16 v[26:29], v[86:89], v[70:73], v[26:29]
	v_mfma_f32_16x16x32_bf16 v[14:17], v[208:211], v[70:73], v[14:17]
	v_mfma_f32_16x16x32_bf16 v[10:13], v[212:215], v[70:73], v[10:13]
	ds_read_b128 v[70:73], v255 offset:2048
	s_waitcnt lgkmcnt(7)
	v_mfma_f32_16x16x32_bf16 v[34:37], v[82:85], v[74:77], v[34:37]
	v_mfma_f32_16x16x32_bf16 v[22:25], v[86:89], v[74:77], v[22:25]
	v_mfma_f32_16x16x32_bf16 v[18:21], v[208:211], v[74:77], v[18:21]
	v_mfma_f32_16x16x32_bf16 v[62:65], v[212:215], v[74:77], v[62:65]
	ds_read_b128 v[74:77], v255 offset:4096
	s_waitcnt lgkmcnt(7)
	v_mfma_f32_16x16x32_bf16 v[58:61], v[82:85], v[78:81], v[58:61]
	v_mfma_f32_16x16x32_bf16 v[54:57], v[86:89], v[78:81], v[54:57]
	v_mfma_f32_16x16x32_bf16 v[50:53], v[208:211], v[78:81], v[50:53]
	v_mfma_f32_16x16x32_bf16 v[2:5], v[212:215], v[78:81], v[2:5]
	ds_read_b128 v[78:81], v255 offset:6144
	s_waitcnt lgkmcnt(3)
	v_mfma_f32_16x16x32_bf16 v[6:9], v[216:219], v[66:69], v[6:9]
	v_mfma_f32_16x16x32_bf16 v[30:33], v[220:223], v[66:69], v[30:33]
	v_mfma_f32_16x16x32_bf16 v[38:41], v[224:227], v[66:69], v[38:41]
	v_mfma_f32_16x16x32_bf16 v[42:45], v[228:231], v[66:69], v[42:45]
	s_waitcnt lgkmcnt(2)
	v_mfma_f32_16x16x32_bf16 v[46:49], v[216:219], v[70:73], v[46:49]
	v_mfma_f32_16x16x32_bf16 v[26:29], v[220:223], v[70:73], v[26:29]
	v_mfma_f32_16x16x32_bf16 v[14:17], v[224:227], v[70:73], v[14:17]
	v_mfma_f32_16x16x32_bf16 v[10:13], v[228:231], v[70:73], v[10:13]
	s_waitcnt vmcnt(6)
	s_waitcnt lgkmcnt(0)
	s_barrier
	s_add_i32 m0, s67, 0x10000
	s_nop 0
	global_load_lds_dwordx4 v188, s[80:81]
	s_add_i32 m0, s67, 0x12000
	s_nop 0
	global_load_lds_dwordx4 v189, s[80:81]
	s_add_i32 m0, s67, 0x14000
	s_nop 0
	global_load_lds_dwordx4 v190, s[80:81]
	s_add_i32 m0, s67, 0x16000
	s_nop 0
	global_load_lds_dwordx4 v191, s[80:81]
	s_add_i32 m0, s67, 0x20400
	s_nop 0
	global_load_lds_dwordx4 v205, s[96:97]
	s_add_i32 m0, s67, 0x22400
	s_nop 0
	global_load_lds_dwordx4 v206, s[96:97]
	s_add_u32 s80, s80, 0x880
	s_addc_u32 s81, s81, 0
	s_add_u32 s96, s96, 0xffc80
	s_addc_u32 s97, s97, 0
	ds_read_b128 v[82:85], v90 offset:0
	ds_read_b128 v[86:89], v90 offset:2048
	ds_read_b128 v[208:211], v90 offset:4096
	ds_read_b128 v[212:215], v90 offset:6144
	ds_read_b128 v[66:69], v207 offset:0
	ds_read_b128 v[70:73], v207 offset:2048
	v_mfma_f32_16x16x32_bf16 v[34:37], v[216:219], v[74:77], v[34:37]
	v_mfma_f32_16x16x32_bf16 v[22:25], v[220:223], v[74:77], v[22:25]
	v_mfma_f32_16x16x32_bf16 v[18:21], v[224:227], v[74:77], v[18:21]
	v_mfma_f32_16x16x32_bf16 v[62:65], v[228:231], v[74:77], v[62:65]
	ds_read_b128 v[74:77], v207 offset:4096
	v_mfma_f32_16x16x32_bf16 v[58:61], v[216:219], v[78:81], v[58:61]
	v_mfma_f32_16x16x32_bf16 v[54:57], v[220:223], v[78:81], v[54:57]
	v_mfma_f32_16x16x32_bf16 v[50:53], v[224:227], v[78:81], v[50:53]
	v_mfma_f32_16x16x32_bf16 v[2:5], v[228:231], v[78:81], v[2:5]
	ds_read_b128 v[78:81], v207 offset:6144
	ds_read_b128 v[216:219], v91 offset:0
	ds_read_b128 v[220:223], v91 offset:2048
	ds_read_b128 v[224:227], v91 offset:4096
	ds_read_b128 v[228:231], v91 offset:6144
	s_waitcnt lgkmcnt(7)
	v_mfma_f32_16x16x32_bf16 v[6:9], v[82:85], v[66:69], v[6:9]
	v_mfma_f32_16x16x32_bf16 v[30:33], v[86:89], v[66:69], v[30:33]
	v_mfma_f32_16x16x32_bf16 v[38:41], v[208:211], v[66:69], v[38:41]
	v_mfma_f32_16x16x32_bf16 v[42:45], v[212:215], v[66:69], v[42:45]
	ds_read_b128 v[66:69], v119 offset:0
	s_waitcnt lgkmcnt(7)
	v_mfma_f32_16x16x32_bf16 v[46:49], v[82:85], v[70:73], v[46:49]
	v_mfma_f32_16x16x32_bf16 v[26:29], v[86:89], v[70:73], v[26:29]
	v_mfma_f32_16x16x32_bf16 v[14:17], v[208:211], v[70:73], v[14:17]
	v_mfma_f32_16x16x32_bf16 v[10:13], v[212:215], v[70:73], v[10:13]
	ds_read_b128 v[70:73], v119 offset:2048
	s_waitcnt lgkmcnt(7)
	v_mfma_f32_16x16x32_bf16 v[34:37], v[82:85], v[74:77], v[34:37]
	v_mfma_f32_16x16x32_bf16 v[22:25], v[86:89], v[74:77], v[22:25]
	v_mfma_f32_16x16x32_bf16 v[18:21], v[208:211], v[74:77], v[18:21]
	v_mfma_f32_16x16x32_bf16 v[62:65], v[212:215], v[74:77], v[62:65]
	ds_read_b128 v[74:77], v119 offset:4096
	s_waitcnt lgkmcnt(7)
	v_mfma_f32_16x16x32_bf16 v[58:61], v[82:85], v[78:81], v[58:61]
	v_mfma_f32_16x16x32_bf16 v[54:57], v[86:89], v[78:81], v[54:57]
	v_mfma_f32_16x16x32_bf16 v[50:53], v[208:211], v[78:81], v[50:53]
	v_mfma_f32_16x16x32_bf16 v[2:5], v[212:215], v[78:81], v[2:5]
	ds_read_b128 v[78:81], v119 offset:6144
	s_waitcnt lgkmcnt(3)
	v_mfma_f32_16x16x32_bf16 v[6:9], v[216:219], v[66:69], v[6:9]
	v_mfma_f32_16x16x32_bf16 v[30:33], v[220:223], v[66:69], v[30:33]
	v_mfma_f32_16x16x32_bf16 v[38:41], v[224:227], v[66:69], v[38:41]
	v_mfma_f32_16x16x32_bf16 v[42:45], v[228:231], v[66:69], v[42:45]
	s_waitcnt lgkmcnt(2)
	v_mfma_f32_16x16x32_bf16 v[46:49], v[216:219], v[70:73], v[46:49]
	v_mfma_f32_16x16x32_bf16 v[26:29], v[220:223], v[70:73], v[26:29]
	v_mfma_f32_16x16x32_bf16 v[14:17], v[224:227], v[70:73], v[14:17]
	v_mfma_f32_16x16x32_bf16 v[10:13], v[228:231], v[70:73], v[10:13]
	s_waitcnt vmcnt(6)
	s_waitcnt lgkmcnt(0)
	s_barrier
	s_add_i32 m0, s67, 0x0
	s_nop 0
	global_load_lds_dwordx4 v188, s[80:81]
	s_add_i32 m0, s67, 0x2000
	s_nop 0
	global_load_lds_dwordx4 v189, s[80:81]
	s_add_i32 m0, s67, 0x4000
	s_nop 0
	global_load_lds_dwordx4 v190, s[80:81]
	s_add_i32 m0, s67, 0x6000
	s_nop 0
	global_load_lds_dwordx4 v191, s[80:81]
	s_add_i32 m0, s67, 0x18000
	s_nop 0
	global_load_lds_dwordx4 v205, s[96:97]
	s_add_i32 m0, s67, 0x1a000
	s_nop 0
	global_load_lds_dwordx4 v206, s[96:97]
	s_add_u32 s80, s80, 0x80
	s_addc_u32 s81, s81, 0
	s_add_u32 s96, s96, 0x80
	s_addc_u32 s97, s97, 0
	ds_read_b128 v[82:85], v90 offset:16384
	ds_read_b128 v[86:89], v90 offset:18432
	ds_read_b128 v[208:211], v90 offset:20480
	ds_read_b128 v[212:215], v90 offset:22528
	ds_read_b128 v[66:69], v207 offset:32768
	ds_read_b128 v[70:73], v207 offset:34816
	v_mfma_f32_16x16x32_bf16 v[34:37], v[216:219], v[74:77], v[34:37]
	v_mfma_f32_16x16x32_bf16 v[22:25], v[220:223], v[74:77], v[22:25]
	v_mfma_f32_16x16x32_bf16 v[18:21], v[224:227], v[74:77], v[18:21]
	v_mfma_f32_16x16x32_bf16 v[62:65], v[228:231], v[74:77], v[62:65]
	ds_read_b128 v[74:77], v207 offset:36864
	v_mfma_f32_16x16x32_bf16 v[58:61], v[216:219], v[78:81], v[58:61]
	v_mfma_f32_16x16x32_bf16 v[54:57], v[220:223], v[78:81], v[54:57]
	v_mfma_f32_16x16x32_bf16 v[50:53], v[224:227], v[78:81], v[50:53]
	v_mfma_f32_16x16x32_bf16 v[2:5], v[228:231], v[78:81], v[2:5]
	ds_read_b128 v[78:81], v207 offset:38912
	ds_read_b128 v[216:219], v91 offset:16384
	ds_read_b128 v[220:223], v91 offset:18432
	ds_read_b128 v[224:227], v91 offset:20480
	ds_read_b128 v[228:231], v91 offset:22528
	s_waitcnt lgkmcnt(7)
	v_mfma_f32_16x16x32_bf16 v[6:9], v[82:85], v[66:69], v[6:9]
	v_mfma_f32_16x16x32_bf16 v[30:33], v[86:89], v[66:69], v[30:33]
	v_mfma_f32_16x16x32_bf16 v[38:41], v[208:211], v[66:69], v[38:41]
	v_mfma_f32_16x16x32_bf16 v[42:45], v[212:215], v[66:69], v[42:45]
	ds_read_b128 v[66:69], v119 offset:32768
	s_waitcnt lgkmcnt(7)
	v_mfma_f32_16x16x32_bf16 v[46:49], v[82:85], v[70:73], v[46:49]
	v_mfma_f32_16x16x32_bf16 v[26:29], v[86:89], v[70:73], v[26:29]
	v_mfma_f32_16x16x32_bf16 v[14:17], v[208:211], v[70:73], v[14:17]
	v_mfma_f32_16x16x32_bf16 v[10:13], v[212:215], v[70:73], v[10:13]
	ds_read_b128 v[70:73], v119 offset:34816
	s_waitcnt lgkmcnt(7)
	v_mfma_f32_16x16x32_bf16 v[34:37], v[82:85], v[74:77], v[34:37]
	v_mfma_f32_16x16x32_bf16 v[22:25], v[86:89], v[74:77], v[22:25]
	v_mfma_f32_16x16x32_bf16 v[18:21], v[208:211], v[74:77], v[18:21]
	v_mfma_f32_16x16x32_bf16 v[62:65], v[212:215], v[74:77], v[62:65]
	ds_read_b128 v[74:77], v119 offset:36864
	s_waitcnt lgkmcnt(7)
	v_mfma_f32_16x16x32_bf16 v[58:61], v[82:85], v[78:81], v[58:61]
	v_mfma_f32_16x16x32_bf16 v[54:57], v[86:89], v[78:81], v[54:57]
	v_mfma_f32_16x16x32_bf16 v[50:53], v[208:211], v[78:81], v[50:53]
	v_mfma_f32_16x16x32_bf16 v[2:5], v[212:215], v[78:81], v[2:5]
	ds_read_b128 v[78:81], v119 offset:38912
	s_waitcnt lgkmcnt(3)
	v_mfma_f32_16x16x32_bf16 v[6:9], v[216:219], v[66:69], v[6:9]
	v_mfma_f32_16x16x32_bf16 v[30:33], v[220:223], v[66:69], v[30:33]
	v_mfma_f32_16x16x32_bf16 v[38:41], v[224:227], v[66:69], v[38:41]
	v_mfma_f32_16x16x32_bf16 v[42:45], v[228:231], v[66:69], v[42:45]
	s_waitcnt lgkmcnt(2)
	v_mfma_f32_16x16x32_bf16 v[46:49], v[216:219], v[70:73], v[46:49]
	v_mfma_f32_16x16x32_bf16 v[26:29], v[220:223], v[70:73], v[26:29]
	v_mfma_f32_16x16x32_bf16 v[14:17], v[224:227], v[70:73], v[14:17]
	v_mfma_f32_16x16x32_bf16 v[10:13], v[228:231], v[70:73], v[10:13]
	s_waitcnt vmcnt(6)
	s_waitcnt lgkmcnt(0)
	s_barrier
	s_add_i32 m0, s67, 0x8000
	s_nop 0
	global_load_lds_dwordx4 v188, s[80:81]
	s_add_i32 m0, s67, 0xa000
	s_nop 0
	global_load_lds_dwordx4 v189, s[80:81]
	s_add_i32 m0, s67, 0xc000
	s_nop 0
	global_load_lds_dwordx4 v190, s[80:81]
	s_add_i32 m0, s67, 0xe000
	s_nop 0
	global_load_lds_dwordx4 v191, s[80:81]
	s_add_i32 m0, s67, 0x1c000
	s_nop 0
	global_load_lds_dwordx4 v205, s[96:97]
	s_add_i32 m0, s67, 0x1e000
	s_nop 0
	global_load_lds_dwordx4 v206, s[96:97]
	s_add_u32 s80, s80, 0x80
	s_addc_u32 s81, s81, 0
	s_add_u32 s96, s96, 0x80
	s_addc_u32 s97, s97, 0
	ds_read_b128 v[82:85], v90 offset:33792
	ds_read_b128 v[86:89], v90 offset:35840
	ds_read_b128 v[208:211], v90 offset:37888
	ds_read_b128 v[212:215], v90 offset:39936
	ds_read_b128 v[66:69], v0 offset:0
	ds_read_b128 v[70:73], v0 offset:2048
	v_mfma_f32_16x16x32_bf16 v[34:37], v[216:219], v[74:77], v[34:37]
	v_mfma_f32_16x16x32_bf16 v[22:25], v[220:223], v[74:77], v[22:25]
	v_mfma_f32_16x16x32_bf16 v[18:21], v[224:227], v[74:77], v[18:21]
	v_mfma_f32_16x16x32_bf16 v[62:65], v[228:231], v[74:77], v[62:65]
	ds_read_b128 v[74:77], v0 offset:4096
	v_mfma_f32_16x16x32_bf16 v[58:61], v[216:219], v[78:81], v[58:61]
	v_mfma_f32_16x16x32_bf16 v[54:57], v[220:223], v[78:81], v[54:57]
	v_mfma_f32_16x16x32_bf16 v[50:53], v[224:227], v[78:81], v[50:53]
	v_mfma_f32_16x16x32_bf16 v[2:5], v[228:231], v[78:81], v[2:5]
	ds_read_b128 v[78:81], v0 offset:6144
	ds_read_b128 v[216:219], v91 offset:33792
	ds_read_b128 v[220:223], v91 offset:35840
	ds_read_b128 v[224:227], v91 offset:37888
	ds_read_b128 v[228:231], v91 offset:39936
	s_waitcnt lgkmcnt(7)
	v_mfma_f32_16x16x32_bf16 v[6:9], v[82:85], v[66:69], v[6:9]
	v_mfma_f32_16x16x32_bf16 v[30:33], v[86:89], v[66:69], v[30:33]
	v_mfma_f32_16x16x32_bf16 v[38:41], v[208:211], v[66:69], v[38:41]
	v_mfma_f32_16x16x32_bf16 v[42:45], v[212:215], v[66:69], v[42:45]
	ds_read_b128 v[66:69], v255 offset:0
	s_waitcnt lgkmcnt(7)
	v_mfma_f32_16x16x32_bf16 v[46:49], v[82:85], v[70:73], v[46:49]
	v_mfma_f32_16x16x32_bf16 v[26:29], v[86:89], v[70:73], v[26:29]
	v_mfma_f32_16x16x32_bf16 v[14:17], v[208:211], v[70:73], v[14:17]
	v_mfma_f32_16x16x32_bf16 v[10:13], v[212:215], v[70:73], v[10:13]
	ds_read_b128 v[70:73], v255 offset:2048
	s_waitcnt lgkmcnt(7)
	v_mfma_f32_16x16x32_bf16 v[34:37], v[82:85], v[74:77], v[34:37]
	v_mfma_f32_16x16x32_bf16 v[22:25], v[86:89], v[74:77], v[22:25]
	v_mfma_f32_16x16x32_bf16 v[18:21], v[208:211], v[74:77], v[18:21]
	v_mfma_f32_16x16x32_bf16 v[62:65], v[212:215], v[74:77], v[62:65]
	ds_read_b128 v[74:77], v255 offset:4096
	s_waitcnt lgkmcnt(7)
	v_mfma_f32_16x16x32_bf16 v[58:61], v[82:85], v[78:81], v[58:61]
	v_mfma_f32_16x16x32_bf16 v[54:57], v[86:89], v[78:81], v[54:57]
	v_mfma_f32_16x16x32_bf16 v[50:53], v[208:211], v[78:81], v[50:53]
	v_mfma_f32_16x16x32_bf16 v[2:5], v[212:215], v[78:81], v[2:5]
	ds_read_b128 v[78:81], v255 offset:6144
	s_waitcnt lgkmcnt(3)
	v_mfma_f32_16x16x32_bf16 v[6:9], v[216:219], v[66:69], v[6:9]
	s_waitcnt vmcnt(30)
	v_mfma_f32_16x16x32_bf16 v[30:33], v[220:223], v[66:69], v[30:33]
	v_mfma_f32_16x16x32_bf16 v[38:41], v[224:227], v[66:69], v[38:41]
	v_mfma_f32_16x16x32_bf16 v[42:45], v[228:231], v[66:69], v[42:45]
	v_cvt_f32_ubyte0_e32 v248, v232
	v_cvt_f32_ubyte1_e32 v249, v232
	v_cvt_f32_ubyte2_e32 v250, v232
	v_cvt_f32_ubyte3_e32 v251, v232
	v_mul_f32_e32 v248, s34, v248
	v_mul_f32_e32 v249, s34, v249
	v_mul_f32_e32 v250, s34, v250
	v_mul_f32_e32 v251, s34, v251
	v_fma_f32 v184, v6, v248, v184
	v_fma_f32 v185, v7, v249, v185
	v_fma_f32 v186, v8, v250, v186
	v_fma_f32 v187, v9, v251, v187
	s_waitcnt lgkmcnt(2)
	v_mfma_f32_16x16x32_bf16 v[46:49], v[216:219], v[70:73], v[46:49]
	v_cvt_f32_ubyte0_e32 v248, v233
	v_cvt_f32_ubyte1_e32 v249, v233
	v_cvt_f32_ubyte2_e32 v250, v233
	v_cvt_f32_ubyte3_e32 v251, v233
	v_mul_f32_e32 v248, s34, v248
	v_mul_f32_e32 v249, s34, v249
	v_mul_f32_e32 v250, s34, v250
	v_mul_f32_e32 v251, s34, v251
	v_fma_f32 v180, v30, v248, v180
	v_fma_f32 v181, v31, v249, v181
	v_fma_f32 v182, v32, v250, v182
	v_fma_f32 v183, v33, v251, v183
	v_mfma_f32_16x16x32_bf16 v[26:29], v[220:223], v[70:73], v[26:29]
	v_cvt_f32_ubyte0_e32 v248, v234
	v_cvt_f32_ubyte1_e32 v249, v234
	v_cvt_f32_ubyte2_e32 v250, v234
	v_cvt_f32_ubyte3_e32 v251, v234
	v_mul_f32_e32 v248, s34, v248
	v_mul_f32_e32 v249, s34, v249
	v_mul_f32_e32 v250, s34, v250
	v_mul_f32_e32 v251, s34, v251
	v_fma_f32 v176, v38, v248, v176
	v_fma_f32 v177, v39, v249, v177
	v_fma_f32 v178, v40, v250, v178
	v_fma_f32 v179, v41, v251, v179
	v_mfma_f32_16x16x32_bf16 v[14:17], v[224:227], v[70:73], v[14:17]
	v_cvt_f32_ubyte0_e32 v248, v235
	v_cvt_f32_ubyte1_e32 v249, v235
	v_cvt_f32_ubyte2_e32 v250, v235
	v_cvt_f32_ubyte3_e32 v251, v235
	v_mul_f32_e32 v248, s34, v248
	v_mul_f32_e32 v249, s34, v249
	v_mul_f32_e32 v250, s34, v250
	v_mul_f32_e32 v251, s34, v251
	v_fma_f32 v172, v42, v248, v172
	v_fma_f32 v173, v43, v249, v173
	v_fma_f32 v174, v44, v250, v174
	v_fma_f32 v175, v45, v251, v175
	v_mfma_f32_16x16x32_bf16 v[10:13], v[228:231], v[70:73], v[10:13]
	v_cvt_f32_ubyte0_e32 v248, v236
	v_cvt_f32_ubyte1_e32 v249, v236
	v_cvt_f32_ubyte2_e32 v250, v236
	v_cvt_f32_ubyte3_e32 v251, v236
	v_mul_f32_e32 v248, s34, v248
	v_mul_f32_e32 v249, s34, v249
	v_mul_f32_e32 v250, s34, v250
	v_mul_f32_e32 v251, s34, v251
	v_fma_f32 v168, v46, v248, v168
	v_fma_f32 v169, v47, v249, v169
	v_fma_f32 v170, v48, v250, v170
	v_fma_f32 v171, v49, v251, v171
	s_waitcnt vmcnt(6)
	s_waitcnt lgkmcnt(0)
	s_barrier
	s_add_i32 m0, s67, 0x10000
	s_nop 0
	global_load_lds_dwordx4 v188, s[80:81]
	s_add_i32 m0, s67, 0x12000
	s_nop 0
	global_load_lds_dwordx4 v189, s[80:81]
	s_add_i32 m0, s67, 0x14000
	s_nop 0
	global_load_lds_dwordx4 v190, s[80:81]
	s_add_i32 m0, s67, 0x16000
	s_nop 0
	global_load_lds_dwordx4 v191, s[80:81]
	s_add_i32 m0, s67, 0x20400
	s_nop 0
	global_load_lds_dwordx4 v205, s[96:97]
	s_add_i32 m0, s67, 0x22400
	s_nop 0
	global_load_lds_dwordx4 v206, s[96:97]
	s_add_u32 s80, s80, 0x80
	s_addc_u32 s81, s81, 0
	s_add_u32 s96, s96, 0x80
	s_addc_u32 s97, s97, 0
	ds_read_b128 v[82:85], v90 offset:0
	ds_read_b128 v[86:89], v90 offset:2048
	ds_read_b128 v[208:211], v90 offset:4096
	ds_read_b128 v[212:215], v90 offset:6144
	ds_read_b128 v[66:69], v207 offset:0
	ds_read_b128 v[70:73], v207 offset:2048
	v_mfma_f32_16x16x32_bf16 v[34:37], v[216:219], v[74:77], v[34:37]
	v_cvt_f32_ubyte0_e32 v248, v237
	v_cvt_f32_ubyte1_e32 v249, v237
	v_cvt_f32_ubyte2_e32 v250, v237
	v_cvt_f32_ubyte3_e32 v251, v237
	v_mul_f32_e32 v248, s34, v248
	v_mul_f32_e32 v249, s34, v249
	v_mul_f32_e32 v250, s34, v250
	v_mul_f32_e32 v251, s34, v251
	v_fma_f32 v164, v26, v248, v164
	v_fma_f32 v165, v27, v249, v165
	v_fma_f32 v166, v28, v250, v166
	v_fma_f32 v167, v29, v251, v167
	v_mfma_f32_16x16x32_bf16 v[22:25], v[220:223], v[74:77], v[22:25]
	v_cvt_f32_ubyte0_e32 v248, v238
	v_cvt_f32_ubyte1_e32 v249, v238
	v_cvt_f32_ubyte2_e32 v250, v238
	v_cvt_f32_ubyte3_e32 v251, v238
	v_mul_f32_e32 v248, s34, v248
	v_mul_f32_e32 v249, s34, v249
	v_mul_f32_e32 v250, s34, v250
	v_mul_f32_e32 v251, s34, v251
	v_fma_f32 v160, v14, v248, v160
	v_fma_f32 v161, v15, v249, v161
	v_fma_f32 v162, v16, v250, v162
	v_fma_f32 v163, v17, v251, v163
	v_mfma_f32_16x16x32_bf16 v[18:21], v[224:227], v[74:77], v[18:21]
	v_cvt_f32_ubyte0_e32 v248, v239
	v_cvt_f32_ubyte1_e32 v249, v239
	v_cvt_f32_ubyte2_e32 v250, v239
	v_cvt_f32_ubyte3_e32 v251, v239
	v_mul_f32_e32 v248, s34, v248
	v_mul_f32_e32 v249, s34, v249
	v_mul_f32_e32 v250, s34, v250
	v_mul_f32_e32 v251, s34, v251
	v_fma_f32 v156, v10, v248, v156
	v_fma_f32 v157, v11, v249, v157
	v_fma_f32 v158, v12, v250, v158
	v_fma_f32 v159, v13, v251, v159
	v_mfma_f32_16x16x32_bf16 v[62:65], v[228:231], v[74:77], v[62:65]
	v_cvt_f32_ubyte0_e32 v248, v240
	v_cvt_f32_ubyte1_e32 v249, v240
	v_cvt_f32_ubyte2_e32 v250, v240
	v_cvt_f32_ubyte3_e32 v251, v240
	v_mul_f32_e32 v248, s34, v248
	v_mul_f32_e32 v249, s34, v249
	v_mul_f32_e32 v250, s34, v250
	v_mul_f32_e32 v251, s34, v251
	v_fma_f32 v136, v34, v248, v136
	v_fma_f32 v137, v35, v249, v137
	v_fma_f32 v150, v36, v250, v150
	v_fma_f32 v151, v37, v251, v151
	ds_read_b128 v[74:77], v207 offset:4096
	v_mfma_f32_16x16x32_bf16 v[58:61], v[216:219], v[78:81], v[58:61]
	v_cvt_f32_ubyte0_e32 v248, v241
	v_cvt_f32_ubyte1_e32 v249, v241
	v_cvt_f32_ubyte2_e32 v250, v241
	v_cvt_f32_ubyte3_e32 v251, v241
	v_mul_f32_e32 v248, s34, v248
	v_mul_f32_e32 v249, s34, v249
	v_mul_f32_e32 v250, s34, v250
	v_mul_f32_e32 v251, s34, v251
	v_fma_f32 v130, v22, v248, v130
	v_fma_f32 v131, v23, v249, v131
	v_fma_f32 v134, v24, v250, v134
	v_fma_f32 v135, v25, v251, v135
	v_mfma_f32_16x16x32_bf16 v[54:57], v[220:223], v[78:81], v[54:57]
	v_cvt_f32_ubyte0_e32 v248, v242
	v_cvt_f32_ubyte1_e32 v249, v242
	v_cvt_f32_ubyte2_e32 v250, v242
	v_cvt_f32_ubyte3_e32 v251, v242
	v_mul_f32_e32 v248, s34, v248
	v_mul_f32_e32 v249, s34, v249
	v_mul_f32_e32 v250, s34, v250
	v_mul_f32_e32 v251, s34, v251
	v_fma_f32 v124, v18, v248, v124
	v_fma_f32 v125, v19, v249, v125
	v_fma_f32 v126, v20, v250, v126
	v_fma_f32 v127, v21, v251, v127
	v_mfma_f32_16x16x32_bf16 v[50:53], v[224:227], v[78:81], v[50:53]
	v_cvt_f32_ubyte0_e32 v248, v243
	v_cvt_f32_ubyte1_e32 v249, v243
	v_cvt_f32_ubyte2_e32 v250, v243
	v_cvt_f32_ubyte3_e32 v251, v243
	v_mul_f32_e32 v248, s34, v248
	v_mul_f32_e32 v249, s34, v249
	v_mul_f32_e32 v250, s34, v250
	v_mul_f32_e32 v251, s34, v251
	v_fma_f32 v120, v62, v248, v120
	v_fma_f32 v121, v63, v249, v121
	v_fma_f32 v122, v64, v250, v122
	v_fma_f32 v123, v65, v251, v123
	v_mfma_f32_16x16x32_bf16 v[2:5], v[228:231], v[78:81], v[2:5]
	v_cvt_f32_ubyte0_e32 v248, v244
	v_cvt_f32_ubyte1_e32 v249, v244
	v_cvt_f32_ubyte2_e32 v250, v244
	v_cvt_f32_ubyte3_e32 v251, v244
	v_mul_f32_e32 v248, s34, v248
	v_mul_f32_e32 v249, s34, v249
	v_mul_f32_e32 v250, s34, v250
	v_mul_f32_e32 v251, s34, v251
	v_fma_f32 v114, v58, v248, v114
	v_fma_f32 v115, v59, v249, v115
	v_fma_f32 v116, v60, v250, v116
	v_fma_f32 v117, v61, v251, v117
	ds_read_b128 v[78:81], v207 offset:6144
	s_nop 7
	s_nop 3
	v_cvt_f32_ubyte0_e32 v248, v245
	v_cvt_f32_ubyte1_e32 v249, v245
	v_cvt_f32_ubyte2_e32 v250, v245
	v_cvt_f32_ubyte3_e32 v251, v245
	v_mul_f32_e32 v248, s34, v248
	v_mul_f32_e32 v249, s34, v249
	v_mul_f32_e32 v250, s34, v250
	v_mul_f32_e32 v251, s34, v251
	v_fma_f32 v106, v54, v248, v106
	v_fma_f32 v107, v55, v249, v107
	v_fma_f32 v108, v56, v250, v108
	v_fma_f32 v109, v57, v251, v109
	v_cvt_f32_ubyte0_e32 v248, v246
	v_cvt_f32_ubyte1_e32 v249, v246
	v_cvt_f32_ubyte2_e32 v250, v246
	v_cvt_f32_ubyte3_e32 v251, v246
	v_mul_f32_e32 v248, s34, v248
	v_mul_f32_e32 v249, s34, v249
	v_mul_f32_e32 v250, s34, v250
	v_mul_f32_e32 v251, s34, v251
	v_fma_f32 v100, v50, v248, v100
	v_fma_f32 v101, v51, v249, v101
	v_fma_f32 v102, v52, v250, v102
	v_fma_f32 v103, v53, v251, v103
	v_cvt_f32_ubyte0_e32 v248, v247
	v_cvt_f32_ubyte1_e32 v249, v247
	v_cvt_f32_ubyte2_e32 v250, v247
	v_cvt_f32_ubyte3_e32 v251, v247
	v_mul_f32_e32 v248, s34, v248
	v_mul_f32_e32 v249, s34, v249
	v_mul_f32_e32 v250, s34, v250
	v_mul_f32_e32 v251, s34, v251
	v_fma_f32 v96, v2, v248, v96
	v_fma_f32 v97, v3, v249, v97
	v_fma_f32 v98, v4, v250, v98
	v_fma_f32 v99, v5, v251, v99
	s_cmp_eq_u32 s43, 0
	s_cselect_b32 s32, 0x7c00000, 0
	s_add_u32 s98, s86, s32
	s_addc_u32 s99, s87, 0
	s_add_u32 s98, s98, 0xc00
	s_addc_u32 s99, s99, 0
	global_load_dword v92, v93, s[98:99]
	ds_read_b128 v[216:219], v91 offset:0
	ds_read_b128 v[220:223], v91 offset:2048
	ds_read_b128 v[224:227], v91 offset:4096
	ds_read_b128 v[228:231], v91 offset:6144
	s_waitcnt lgkmcnt(7)
	v_mfma_f32_16x16x32_bf16 v[6:9], v[82:85], v[66:69], 0
	v_mfma_f32_16x16x32_bf16 v[30:33], v[86:89], v[66:69], 0
	v_mfma_f32_16x16x32_bf16 v[38:41], v[208:211], v[66:69], 0
	v_mfma_f32_16x16x32_bf16 v[42:45], v[212:215], v[66:69], 0
	ds_read_b128 v[66:69], v119 offset:0
	s_waitcnt lgkmcnt(7)
	v_mfma_f32_16x16x32_bf16 v[46:49], v[82:85], v[70:73], 0
	v_mfma_f32_16x16x32_bf16 v[26:29], v[86:89], v[70:73], 0
	v_mfma_f32_16x16x32_bf16 v[14:17], v[208:211], v[70:73], 0
	v_mfma_f32_16x16x32_bf16 v[10:13], v[212:215], v[70:73], 0
	ds_read_b128 v[70:73], v119 offset:2048
	s_waitcnt lgkmcnt(7)
	v_mfma_f32_16x16x32_bf16 v[34:37], v[82:85], v[74:77], 0
	v_mfma_f32_16x16x32_bf16 v[22:25], v[86:89], v[74:77], 0
	v_mfma_f32_16x16x32_bf16 v[18:21], v[208:211], v[74:77], 0
	v_mfma_f32_16x16x32_bf16 v[62:65], v[212:215], v[74:77], 0
	ds_read_b128 v[74:77], v119 offset:4096
	s_waitcnt lgkmcnt(7)
	v_mfma_f32_16x16x32_bf16 v[58:61], v[82:85], v[78:81], 0
	v_mfma_f32_16x16x32_bf16 v[54:57], v[86:89], v[78:81], 0
	v_mfma_f32_16x16x32_bf16 v[50:53], v[208:211], v[78:81], 0
	v_mfma_f32_16x16x32_bf16 v[2:5], v[212:215], v[78:81], 0
	ds_read_b128 v[78:81], v119 offset:6144
	s_waitcnt lgkmcnt(3)
	v_mfma_f32_16x16x32_bf16 v[6:9], v[216:219], v[66:69], v[6:9]
	v_mfma_f32_16x16x32_bf16 v[30:33], v[220:223], v[66:69], v[30:33]
	v_mfma_f32_16x16x32_bf16 v[38:41], v[224:227], v[66:69], v[38:41]
	v_mfma_f32_16x16x32_bf16 v[42:45], v[228:231], v[66:69], v[42:45]
	s_waitcnt lgkmcnt(2)
	v_mfma_f32_16x16x32_bf16 v[46:49], v[216:219], v[70:73], v[46:49]
	v_mfma_f32_16x16x32_bf16 v[26:29], v[220:223], v[70:73], v[26:29]
	v_mfma_f32_16x16x32_bf16 v[14:17], v[224:227], v[70:73], v[14:17]
	v_mfma_f32_16x16x32_bf16 v[10:13], v[228:231], v[70:73], v[10:13]
	s_waitcnt vmcnt(7)
	s_waitcnt lgkmcnt(0)
	s_barrier
	s_add_i32 m0, s67, 0x0
	s_nop 0
	global_load_lds_dwordx4 v188, s[80:81]
	s_add_i32 m0, s67, 0x2000
	s_nop 0
	global_load_lds_dwordx4 v189, s[80:81]
	s_add_i32 m0, s67, 0x4000
	s_nop 0
	global_load_lds_dwordx4 v190, s[80:81]
	s_add_i32 m0, s67, 0x6000
	s_nop 0
	global_load_lds_dwordx4 v191, s[80:81]
	s_add_i32 m0, s67, 0x18000
	s_nop 0
	global_load_lds_dwordx4 v205, s[96:97]
	s_add_i32 m0, s67, 0x1a000
	s_nop 0
	global_load_lds_dwordx4 v206, s[96:97]
	s_add_u32 s80, s80, 0x80
	s_addc_u32 s81, s81, 0
	s_add_u32 s96, s96, 0x80
	s_addc_u32 s97, s97, 0
	ds_read_b128 v[82:85], v90 offset:16384
	ds_read_b128 v[86:89], v90 offset:18432
	ds_read_b128 v[208:211], v90 offset:20480
	ds_read_b128 v[212:215], v90 offset:22528
	ds_read_b128 v[66:69], v207 offset:32768
	ds_read_b128 v[70:73], v207 offset:34816
	v_mfma_f32_16x16x32_bf16 v[34:37], v[216:219], v[74:77], v[34:37]
	v_mfma_f32_16x16x32_bf16 v[22:25], v[220:223], v[74:77], v[22:25]
	v_mfma_f32_16x16x32_bf16 v[18:21], v[224:227], v[74:77], v[18:21]
	v_mfma_f32_16x16x32_bf16 v[62:65], v[228:231], v[74:77], v[62:65]
	ds_read_b128 v[74:77], v207 offset:36864
	v_mfma_f32_16x16x32_bf16 v[58:61], v[216:219], v[78:81], v[58:61]
	v_mfma_f32_16x16x32_bf16 v[54:57], v[220:223], v[78:81], v[54:57]
	v_mfma_f32_16x16x32_bf16 v[50:53], v[224:227], v[78:81], v[50:53]
	v_mfma_f32_16x16x32_bf16 v[2:5], v[228:231], v[78:81], v[2:5]
	ds_read_b128 v[78:81], v207 offset:38912
	ds_read_b128 v[216:219], v91 offset:16384
	ds_read_b128 v[220:223], v91 offset:18432
	ds_read_b128 v[224:227], v91 offset:20480
	ds_read_b128 v[228:231], v91 offset:22528
	s_waitcnt lgkmcnt(7)
	v_mfma_f32_16x16x32_bf16 v[6:9], v[82:85], v[66:69], v[6:9]
	v_mfma_f32_16x16x32_bf16 v[30:33], v[86:89], v[66:69], v[30:33]
	v_mfma_f32_16x16x32_bf16 v[38:41], v[208:211], v[66:69], v[38:41]
	v_mfma_f32_16x16x32_bf16 v[42:45], v[212:215], v[66:69], v[42:45]
	ds_read_b128 v[66:69], v119 offset:32768
	s_waitcnt lgkmcnt(7)
	v_mfma_f32_16x16x32_bf16 v[46:49], v[82:85], v[70:73], v[46:49]
	v_mfma_f32_16x16x32_bf16 v[26:29], v[86:89], v[70:73], v[26:29]
	v_mfma_f32_16x16x32_bf16 v[14:17], v[208:211], v[70:73], v[14:17]
	v_mfma_f32_16x16x32_bf16 v[10:13], v[212:215], v[70:73], v[10:13]
	ds_read_b128 v[70:73], v119 offset:34816
	s_waitcnt lgkmcnt(7)
	v_mfma_f32_16x16x32_bf16 v[34:37], v[82:85], v[74:77], v[34:37]
	v_mfma_f32_16x16x32_bf16 v[22:25], v[86:89], v[74:77], v[22:25]
	v_mfma_f32_16x16x32_bf16 v[18:21], v[208:211], v[74:77], v[18:21]
	v_mfma_f32_16x16x32_bf16 v[62:65], v[212:215], v[74:77], v[62:65]
	ds_read_b128 v[74:77], v119 offset:36864
	s_waitcnt lgkmcnt(7)
	v_mfma_f32_16x16x32_bf16 v[58:61], v[82:85], v[78:81], v[58:61]
	v_mfma_f32_16x16x32_bf16 v[54:57], v[86:89], v[78:81], v[54:57]
	v_mfma_f32_16x16x32_bf16 v[50:53], v[208:211], v[78:81], v[50:53]
	v_mfma_f32_16x16x32_bf16 v[2:5], v[212:215], v[78:81], v[2:5]
	ds_read_b128 v[78:81], v119 offset:38912
	s_waitcnt lgkmcnt(3)
	v_mfma_f32_16x16x32_bf16 v[6:9], v[216:219], v[66:69], v[6:9]
	v_mfma_f32_16x16x32_bf16 v[30:33], v[220:223], v[66:69], v[30:33]
	v_mfma_f32_16x16x32_bf16 v[38:41], v[224:227], v[66:69], v[38:41]
	v_mfma_f32_16x16x32_bf16 v[42:45], v[228:231], v[66:69], v[42:45]
	s_waitcnt lgkmcnt(2)
	v_mfma_f32_16x16x32_bf16 v[46:49], v[216:219], v[70:73], v[46:49]
	v_mfma_f32_16x16x32_bf16 v[26:29], v[220:223], v[70:73], v[26:29]
	v_mfma_f32_16x16x32_bf16 v[14:17], v[224:227], v[70:73], v[14:17]
	v_mfma_f32_16x16x32_bf16 v[10:13], v[228:231], v[70:73], v[10:13]
	s_waitcnt vmcnt(7)
	s_waitcnt lgkmcnt(0)
	s_barrier
	s_add_i32 m0, s67, 0x8000
	s_nop 0
	global_load_lds_dwordx4 v188, s[80:81]
	s_add_i32 m0, s67, 0xa000
	s_nop 0
	global_load_lds_dwordx4 v189, s[80:81]
	s_add_i32 m0, s67, 0xc000
	s_nop 0
	global_load_lds_dwordx4 v190, s[80:81]
	s_add_i32 m0, s67, 0xe000
	s_nop 0
	global_load_lds_dwordx4 v191, s[80:81]
	s_add_i32 m0, s67, 0x1c000
	s_nop 0
	global_load_lds_dwordx4 v205, s[96:97]
	s_add_i32 m0, s67, 0x1e000
	s_nop 0
	global_load_lds_dwordx4 v206, s[96:97]
	s_add_u32 s80, s80, 0x80
	s_addc_u32 s81, s81, 0
	s_add_u32 s96, s96, 0x80
	s_addc_u32 s97, s97, 0
	s_movk_i32 s10, 0xc00
	s_mov_b32 s11, 0
	v_lshl_add_u64 v[248:249], v[128:129], 0, s[10:11]
	global_load_dwordx2 v[232:233], v[248:249], off
	global_load_dwordx2 v[234:235], v[248:249], off offset:32
	v_lshl_add_u64 v[248:249], v[132:133], 0, s[10:11]
	global_load_dwordx2 v[236:237], v[248:249], off
	global_load_dwordx2 v[238:239], v[248:249], off offset:32
	v_lshl_add_u64 v[248:249], v[152:153], 0, s[10:11]
	global_load_dwordx2 v[240:241], v[248:249], off
	global_load_dwordx2 v[242:243], v[248:249], off offset:32
	v_lshl_add_u64 v[248:249], v[154:155], 0, s[10:11]
	global_load_dwordx2 v[244:245], v[248:249], off
	global_load_dwordx2 v[246:247], v[248:249], off offset:32
	ds_read_b128 v[82:85], v90 offset:33792
	ds_read_b128 v[86:89], v90 offset:35840
	ds_read_b128 v[208:211], v90 offset:37888
	ds_read_b128 v[212:215], v90 offset:39936
	ds_read_b128 v[66:69], v0 offset:0
	ds_read_b128 v[70:73], v0 offset:2048
	v_mfma_f32_16x16x32_bf16 v[34:37], v[216:219], v[74:77], v[34:37]
	v_mfma_f32_16x16x32_bf16 v[22:25], v[220:223], v[74:77], v[22:25]
	v_mfma_f32_16x16x32_bf16 v[18:21], v[224:227], v[74:77], v[18:21]
	v_mfma_f32_16x16x32_bf16 v[62:65], v[228:231], v[74:77], v[62:65]
	ds_read_b128 v[74:77], v0 offset:4096
	v_mfma_f32_16x16x32_bf16 v[58:61], v[216:219], v[78:81], v[58:61]
	v_mfma_f32_16x16x32_bf16 v[54:57], v[220:223], v[78:81], v[54:57]
	v_mfma_f32_16x16x32_bf16 v[50:53], v[224:227], v[78:81], v[50:53]
	v_mfma_f32_16x16x32_bf16 v[2:5], v[228:231], v[78:81], v[2:5]
	ds_read_b128 v[78:81], v0 offset:6144
	ds_read_b128 v[216:219], v91 offset:33792
	ds_read_b128 v[220:223], v91 offset:35840
	ds_read_b128 v[224:227], v91 offset:37888
	ds_read_b128 v[228:231], v91 offset:39936
	s_waitcnt lgkmcnt(7)
	v_mfma_f32_16x16x32_bf16 v[6:9], v[82:85], v[66:69], v[6:9]
	v_mfma_f32_16x16x32_bf16 v[30:33], v[86:89], v[66:69], v[30:33]
	v_mfma_f32_16x16x32_bf16 v[38:41], v[208:211], v[66:69], v[38:41]
	v_mfma_f32_16x16x32_bf16 v[42:45], v[212:215], v[66:69], v[42:45]
	ds_read_b128 v[66:69], v255 offset:0
	s_waitcnt lgkmcnt(7)
	v_mfma_f32_16x16x32_bf16 v[46:49], v[82:85], v[70:73], v[46:49]
	v_mfma_f32_16x16x32_bf16 v[26:29], v[86:89], v[70:73], v[26:29]
	v_mfma_f32_16x16x32_bf16 v[14:17], v[208:211], v[70:73], v[14:17]
	v_mfma_f32_16x16x32_bf16 v[10:13], v[212:215], v[70:73], v[10:13]
	ds_read_b128 v[70:73], v255 offset:2048
	s_waitcnt lgkmcnt(7)
	v_mfma_f32_16x16x32_bf16 v[34:37], v[82:85], v[74:77], v[34:37]
	v_mfma_f32_16x16x32_bf16 v[22:25], v[86:89], v[74:77], v[22:25]
	v_mfma_f32_16x16x32_bf16 v[18:21], v[208:211], v[74:77], v[18:21]
	v_mfma_f32_16x16x32_bf16 v[62:65], v[212:215], v[74:77], v[62:65]
	ds_read_b128 v[74:77], v255 offset:4096
	s_waitcnt lgkmcnt(7)
	v_mfma_f32_16x16x32_bf16 v[58:61], v[82:85], v[78:81], v[58:61]
	v_mfma_f32_16x16x32_bf16 v[54:57], v[86:89], v[78:81], v[54:57]
	v_mfma_f32_16x16x32_bf16 v[50:53], v[208:211], v[78:81], v[50:53]
	v_mfma_f32_16x16x32_bf16 v[2:5], v[212:215], v[78:81], v[2:5]
	ds_read_b128 v[78:81], v255 offset:6144
	s_waitcnt lgkmcnt(3)
	v_mfma_f32_16x16x32_bf16 v[6:9], v[216:219], v[66:69], v[6:9]
	v_mfma_f32_16x16x32_bf16 v[30:33], v[220:223], v[66:69], v[30:33]
	v_mfma_f32_16x16x32_bf16 v[38:41], v[224:227], v[66:69], v[38:41]
	v_mfma_f32_16x16x32_bf16 v[42:45], v[228:231], v[66:69], v[42:45]
	s_waitcnt lgkmcnt(2)
	v_mfma_f32_16x16x32_bf16 v[46:49], v[216:219], v[70:73], v[46:49]
	v_mfma_f32_16x16x32_bf16 v[26:29], v[220:223], v[70:73], v[26:29]
	v_mfma_f32_16x16x32_bf16 v[14:17], v[224:227], v[70:73], v[14:17]
	v_mfma_f32_16x16x32_bf16 v[10:13], v[228:231], v[70:73], v[10:13]
	s_waitcnt vmcnt(14)
	s_waitcnt lgkmcnt(0)
	s_barrier
	s_add_i32 m0, s67, 0x10000
	s_nop 0
	global_load_lds_dwordx4 v188, s[80:81]
	s_add_i32 m0, s67, 0x12000
	s_nop 0
	global_load_lds_dwordx4 v189, s[80:81]
	s_add_i32 m0, s67, 0x14000
	s_nop 0
	global_load_lds_dwordx4 v190, s[80:81]
	s_add_i32 m0, s67, 0x16000
	s_nop 0
	global_load_lds_dwordx4 v191, s[80:81]
	s_add_i32 m0, s67, 0x20400
	s_nop 0
	global_load_lds_dwordx4 v205, s[96:97]
	s_add_i32 m0, s67, 0x22400
	s_nop 0
	global_load_lds_dwordx4 v206, s[96:97]
	s_add_u32 s80, s80, 0x80
	s_addc_u32 s81, s81, 0
	s_add_u32 s96, s96, 0x80
	s_addc_u32 s97, s97, 0
	ds_read_b128 v[82:85], v90 offset:0
	ds_read_b128 v[86:89], v90 offset:2048
	ds_read_b128 v[208:211], v90 offset:4096
	ds_read_b128 v[212:215], v90 offset:6144
	ds_read_b128 v[66:69], v207 offset:0
	ds_read_b128 v[70:73], v207 offset:2048
	v_mfma_f32_16x16x32_bf16 v[34:37], v[216:219], v[74:77], v[34:37]
	v_mfma_f32_16x16x32_bf16 v[22:25], v[220:223], v[74:77], v[22:25]
	v_mfma_f32_16x16x32_bf16 v[18:21], v[224:227], v[74:77], v[18:21]
	v_mfma_f32_16x16x32_bf16 v[62:65], v[228:231], v[74:77], v[62:65]
	ds_read_b128 v[74:77], v207 offset:4096
	v_mfma_f32_16x16x32_bf16 v[58:61], v[216:219], v[78:81], v[58:61]
	v_mfma_f32_16x16x32_bf16 v[54:57], v[220:223], v[78:81], v[54:57]
	v_mfma_f32_16x16x32_bf16 v[50:53], v[224:227], v[78:81], v[50:53]
	v_mfma_f32_16x16x32_bf16 v[2:5], v[228:231], v[78:81], v[2:5]
	ds_read_b128 v[78:81], v207 offset:6144
	ds_read_b128 v[216:219], v91 offset:0
	ds_read_b128 v[220:223], v91 offset:2048
	ds_read_b128 v[224:227], v91 offset:4096
	ds_read_b128 v[228:231], v91 offset:6144
	s_waitcnt lgkmcnt(7)
	v_mfma_f32_16x16x32_bf16 v[6:9], v[82:85], v[66:69], v[6:9]
	v_mfma_f32_16x16x32_bf16 v[30:33], v[86:89], v[66:69], v[30:33]
	v_mfma_f32_16x16x32_bf16 v[38:41], v[208:211], v[66:69], v[38:41]
	v_mfma_f32_16x16x32_bf16 v[42:45], v[212:215], v[66:69], v[42:45]
	ds_read_b128 v[66:69], v119 offset:0
	s_waitcnt lgkmcnt(7)
	v_mfma_f32_16x16x32_bf16 v[46:49], v[82:85], v[70:73], v[46:49]
	v_mfma_f32_16x16x32_bf16 v[26:29], v[86:89], v[70:73], v[26:29]
	v_mfma_f32_16x16x32_bf16 v[14:17], v[208:211], v[70:73], v[14:17]
	v_mfma_f32_16x16x32_bf16 v[10:13], v[212:215], v[70:73], v[10:13]
	ds_read_b128 v[70:73], v119 offset:2048
	s_waitcnt lgkmcnt(7)
	v_mfma_f32_16x16x32_bf16 v[34:37], v[82:85], v[74:77], v[34:37]
	v_mfma_f32_16x16x32_bf16 v[22:25], v[86:89], v[74:77], v[22:25]
	v_mfma_f32_16x16x32_bf16 v[18:21], v[208:211], v[74:77], v[18:21]
	v_mfma_f32_16x16x32_bf16 v[62:65], v[212:215], v[74:77], v[62:65]
	ds_read_b128 v[74:77], v119 offset:4096
	s_waitcnt lgkmcnt(7)
	v_mfma_f32_16x16x32_bf16 v[58:61], v[82:85], v[78:81], v[58:61]
	v_mfma_f32_16x16x32_bf16 v[54:57], v[86:89], v[78:81], v[54:57]
	v_mfma_f32_16x16x32_bf16 v[50:53], v[208:211], v[78:81], v[50:53]
	v_mfma_f32_16x16x32_bf16 v[2:5], v[212:215], v[78:81], v[2:5]
	ds_read_b128 v[78:81], v119 offset:6144
	s_waitcnt lgkmcnt(3)
	v_mfma_f32_16x16x32_bf16 v[6:9], v[216:219], v[66:69], v[6:9]
	v_mfma_f32_16x16x32_bf16 v[30:33], v[220:223], v[66:69], v[30:33]
	v_mfma_f32_16x16x32_bf16 v[38:41], v[224:227], v[66:69], v[38:41]
	v_mfma_f32_16x16x32_bf16 v[42:45], v[228:231], v[66:69], v[42:45]
	s_waitcnt lgkmcnt(2)
	v_mfma_f32_16x16x32_bf16 v[46:49], v[216:219], v[70:73], v[46:49]
	v_mfma_f32_16x16x32_bf16 v[26:29], v[220:223], v[70:73], v[26:29]
	v_mfma_f32_16x16x32_bf16 v[14:17], v[224:227], v[70:73], v[14:17]
	v_mfma_f32_16x16x32_bf16 v[10:13], v[228:231], v[70:73], v[10:13]
	s_waitcnt vmcnt(14)
	s_waitcnt lgkmcnt(0)
	s_barrier
	s_add_i32 m0, s67, 0x0
	s_nop 0
	global_load_lds_dwordx4 v188, s[80:81]
	s_add_i32 m0, s67, 0x2000
	s_nop 0
	global_load_lds_dwordx4 v189, s[80:81]
	s_add_i32 m0, s67, 0x4000
	s_nop 0
	global_load_lds_dwordx4 v190, s[80:81]
	s_add_i32 m0, s67, 0x6000
	s_nop 0
	global_load_lds_dwordx4 v191, s[80:81]
	s_add_i32 m0, s67, 0x18000
	s_nop 0
	global_load_lds_dwordx4 v205, s[96:97]
	s_add_i32 m0, s67, 0x1a000
	s_nop 0
	global_load_lds_dwordx4 v206, s[96:97]
	s_add_u32 s80, s80, 0x80
	s_addc_u32 s81, s81, 0
	s_add_u32 s96, s96, 0x80
	s_addc_u32 s97, s97, 0
	ds_read_b128 v[82:85], v90 offset:16384
	ds_read_b128 v[86:89], v90 offset:18432
	ds_read_b128 v[208:211], v90 offset:20480
	ds_read_b128 v[212:215], v90 offset:22528
	ds_read_b128 v[66:69], v207 offset:32768
	ds_read_b128 v[70:73], v207 offset:34816
	v_mfma_f32_16x16x32_bf16 v[34:37], v[216:219], v[74:77], v[34:37]
	v_mfma_f32_16x16x32_bf16 v[22:25], v[220:223], v[74:77], v[22:25]
	v_mfma_f32_16x16x32_bf16 v[18:21], v[224:227], v[74:77], v[18:21]
	v_mfma_f32_16x16x32_bf16 v[62:65], v[228:231], v[74:77], v[62:65]
	ds_read_b128 v[74:77], v207 offset:36864
	v_mfma_f32_16x16x32_bf16 v[58:61], v[216:219], v[78:81], v[58:61]
	v_mfma_f32_16x16x32_bf16 v[54:57], v[220:223], v[78:81], v[54:57]
	v_mfma_f32_16x16x32_bf16 v[50:53], v[224:227], v[78:81], v[50:53]
	v_mfma_f32_16x16x32_bf16 v[2:5], v[228:231], v[78:81], v[2:5]
	ds_read_b128 v[78:81], v207 offset:38912
	ds_read_b128 v[216:219], v91 offset:16384
	ds_read_b128 v[220:223], v91 offset:18432
	ds_read_b128 v[224:227], v91 offset:20480
	ds_read_b128 v[228:231], v91 offset:22528
	s_waitcnt lgkmcnt(7)
	v_mfma_f32_16x16x32_bf16 v[6:9], v[82:85], v[66:69], v[6:9]
	v_mfma_f32_16x16x32_bf16 v[30:33], v[86:89], v[66:69], v[30:33]
	v_mfma_f32_16x16x32_bf16 v[38:41], v[208:211], v[66:69], v[38:41]
	v_mfma_f32_16x16x32_bf16 v[42:45], v[212:215], v[66:69], v[42:45]
	ds_read_b128 v[66:69], v119 offset:32768
	s_waitcnt lgkmcnt(7)
	v_mfma_f32_16x16x32_bf16 v[46:49], v[82:85], v[70:73], v[46:49]
	v_mfma_f32_16x16x32_bf16 v[26:29], v[86:89], v[70:73], v[26:29]
	v_mfma_f32_16x16x32_bf16 v[14:17], v[208:211], v[70:73], v[14:17]
	v_mfma_f32_16x16x32_bf16 v[10:13], v[212:215], v[70:73], v[10:13]
	ds_read_b128 v[70:73], v119 offset:34816
	s_waitcnt lgkmcnt(7)
	v_mfma_f32_16x16x32_bf16 v[34:37], v[82:85], v[74:77], v[34:37]
	v_mfma_f32_16x16x32_bf16 v[22:25], v[86:89], v[74:77], v[22:25]
	v_mfma_f32_16x16x32_bf16 v[18:21], v[208:211], v[74:77], v[18:21]
	v_mfma_f32_16x16x32_bf16 v[62:65], v[212:215], v[74:77], v[62:65]
	ds_read_b128 v[74:77], v119 offset:36864
	s_waitcnt lgkmcnt(7)
	v_mfma_f32_16x16x32_bf16 v[58:61], v[82:85], v[78:81], v[58:61]
	v_mfma_f32_16x16x32_bf16 v[54:57], v[86:89], v[78:81], v[54:57]
	v_mfma_f32_16x16x32_bf16 v[50:53], v[208:211], v[78:81], v[50:53]
	v_mfma_f32_16x16x32_bf16 v[2:5], v[212:215], v[78:81], v[2:5]
	ds_read_b128 v[78:81], v119 offset:38912
	s_waitcnt lgkmcnt(3)
	v_mfma_f32_16x16x32_bf16 v[6:9], v[216:219], v[66:69], v[6:9]
	v_mfma_f32_16x16x32_bf16 v[30:33], v[220:223], v[66:69], v[30:33]
	v_mfma_f32_16x16x32_bf16 v[38:41], v[224:227], v[66:69], v[38:41]
	v_mfma_f32_16x16x32_bf16 v[42:45], v[228:231], v[66:69], v[42:45]
	s_waitcnt lgkmcnt(2)
	v_mfma_f32_16x16x32_bf16 v[46:49], v[216:219], v[70:73], v[46:49]
	v_mfma_f32_16x16x32_bf16 v[26:29], v[220:223], v[70:73], v[26:29]
	v_mfma_f32_16x16x32_bf16 v[14:17], v[224:227], v[70:73], v[14:17]
	v_mfma_f32_16x16x32_bf16 v[10:13], v[228:231], v[70:73], v[10:13]
	s_waitcnt vmcnt(6)
	s_waitcnt lgkmcnt(0)
	s_barrier
	s_add_i32 m0, s67, 0x8000
	s_nop 0
	global_load_lds_dwordx4 v188, s[80:81]
	s_add_i32 m0, s67, 0xa000
	s_nop 0
	global_load_lds_dwordx4 v189, s[80:81]
	s_add_i32 m0, s67, 0xc000
	s_nop 0
	global_load_lds_dwordx4 v190, s[80:81]
	s_add_i32 m0, s67, 0xe000
	s_nop 0
	global_load_lds_dwordx4 v191, s[80:81]
	s_add_i32 m0, s67, 0x1c000
	s_nop 0
	global_load_lds_dwordx4 v205, s[96:97]
	s_add_i32 m0, s67, 0x1e000
	s_nop 0
	global_load_lds_dwordx4 v206, s[96:97]
	ds_read_b128 v[82:85], v90 offset:33792
	ds_read_b128 v[86:89], v90 offset:35840
	ds_read_b128 v[208:211], v90 offset:37888
	ds_read_b128 v[212:215], v90 offset:39936
	ds_read_b128 v[66:69], v0 offset:0
	ds_read_b128 v[70:73], v0 offset:2048
	v_mfma_f32_16x16x32_bf16 v[34:37], v[216:219], v[74:77], v[34:37]
	v_mfma_f32_16x16x32_bf16 v[22:25], v[220:223], v[74:77], v[22:25]
	v_mfma_f32_16x16x32_bf16 v[18:21], v[224:227], v[74:77], v[18:21]
	v_mfma_f32_16x16x32_bf16 v[62:65], v[228:231], v[74:77], v[62:65]
	ds_read_b128 v[74:77], v0 offset:4096
	v_mfma_f32_16x16x32_bf16 v[58:61], v[216:219], v[78:81], v[58:61]
	v_mfma_f32_16x16x32_bf16 v[54:57], v[220:223], v[78:81], v[54:57]
	v_mfma_f32_16x16x32_bf16 v[50:53], v[224:227], v[78:81], v[50:53]
	v_mfma_f32_16x16x32_bf16 v[2:5], v[228:231], v[78:81], v[2:5]
	ds_read_b128 v[78:81], v0 offset:6144
	ds_read_b128 v[216:219], v91 offset:33792
	ds_read_b128 v[220:223], v91 offset:35840
	ds_read_b128 v[224:227], v91 offset:37888
	ds_read_b128 v[228:231], v91 offset:39936
	s_waitcnt lgkmcnt(7)
	v_mfma_f32_16x16x32_bf16 v[6:9], v[82:85], v[66:69], v[6:9]
	v_mfma_f32_16x16x32_bf16 v[30:33], v[86:89], v[66:69], v[30:33]
	v_mfma_f32_16x16x32_bf16 v[38:41], v[208:211], v[66:69], v[38:41]
	v_mfma_f32_16x16x32_bf16 v[42:45], v[212:215], v[66:69], v[42:45]
	ds_read_b128 v[66:69], v255 offset:0
	s_waitcnt lgkmcnt(7)
	v_mfma_f32_16x16x32_bf16 v[46:49], v[82:85], v[70:73], v[46:49]
	v_mfma_f32_16x16x32_bf16 v[26:29], v[86:89], v[70:73], v[26:29]
	v_mfma_f32_16x16x32_bf16 v[14:17], v[208:211], v[70:73], v[14:17]
	v_mfma_f32_16x16x32_bf16 v[10:13], v[212:215], v[70:73], v[10:13]
	ds_read_b128 v[70:73], v255 offset:2048
	s_waitcnt lgkmcnt(7)
	v_mfma_f32_16x16x32_bf16 v[34:37], v[82:85], v[74:77], v[34:37]
	v_mfma_f32_16x16x32_bf16 v[22:25], v[86:89], v[74:77], v[22:25]
	v_mfma_f32_16x16x32_bf16 v[18:21], v[208:211], v[74:77], v[18:21]
	v_mfma_f32_16x16x32_bf16 v[62:65], v[212:215], v[74:77], v[62:65]
	ds_read_b128 v[74:77], v255 offset:4096
	s_waitcnt lgkmcnt(7)
	v_mfma_f32_16x16x32_bf16 v[58:61], v[82:85], v[78:81], v[58:61]
	v_mfma_f32_16x16x32_bf16 v[54:57], v[86:89], v[78:81], v[54:57]
	v_mfma_f32_16x16x32_bf16 v[50:53], v[208:211], v[78:81], v[50:53]
	v_mfma_f32_16x16x32_bf16 v[2:5], v[212:215], v[78:81], v[2:5]
	ds_read_b128 v[78:81], v255 offset:6144
	s_waitcnt lgkmcnt(3)
	v_mfma_f32_16x16x32_bf16 v[6:9], v[216:219], v[66:69], v[6:9]
	v_mfma_f32_16x16x32_bf16 v[30:33], v[220:223], v[66:69], v[30:33]
	v_mfma_f32_16x16x32_bf16 v[38:41], v[224:227], v[66:69], v[38:41]
	v_mfma_f32_16x16x32_bf16 v[42:45], v[228:231], v[66:69], v[42:45]
	s_waitcnt lgkmcnt(2)
	v_mfma_f32_16x16x32_bf16 v[46:49], v[216:219], v[70:73], v[46:49]
	v_mfma_f32_16x16x32_bf16 v[26:29], v[220:223], v[70:73], v[26:29]
	v_mfma_f32_16x16x32_bf16 v[14:17], v[224:227], v[70:73], v[14:17]
	v_mfma_f32_16x16x32_bf16 v[10:13], v[228:231], v[70:73], v[10:13]
	s_waitcnt vmcnt(6)
	s_waitcnt lgkmcnt(0)
	s_barrier
	ds_read_b128 v[82:85], v90 offset:0
	ds_read_b128 v[86:89], v90 offset:2048
	ds_read_b128 v[208:211], v90 offset:4096
	ds_read_b128 v[212:215], v90 offset:6144
	ds_read_b128 v[66:69], v207 offset:0
	ds_read_b128 v[70:73], v207 offset:2048
	v_mfma_f32_16x16x32_bf16 v[34:37], v[216:219], v[74:77], v[34:37]
	v_mfma_f32_16x16x32_bf16 v[22:25], v[220:223], v[74:77], v[22:25]
	v_mfma_f32_16x16x32_bf16 v[18:21], v[224:227], v[74:77], v[18:21]
	v_mfma_f32_16x16x32_bf16 v[62:65], v[228:231], v[74:77], v[62:65]
	ds_read_b128 v[74:77], v207 offset:4096
	v_mfma_f32_16x16x32_bf16 v[58:61], v[216:219], v[78:81], v[58:61]
	v_mfma_f32_16x16x32_bf16 v[54:57], v[220:223], v[78:81], v[54:57]
	v_mfma_f32_16x16x32_bf16 v[50:53], v[224:227], v[78:81], v[50:53]
	v_mfma_f32_16x16x32_bf16 v[2:5], v[228:231], v[78:81], v[2:5]
	ds_read_b128 v[78:81], v207 offset:6144
	ds_read_b128 v[216:219], v91 offset:0
	ds_read_b128 v[220:223], v91 offset:2048
	ds_read_b128 v[224:227], v91 offset:4096
	ds_read_b128 v[228:231], v91 offset:6144
	s_waitcnt lgkmcnt(7)
	v_mfma_f32_16x16x32_bf16 v[6:9], v[82:85], v[66:69], v[6:9]
	v_mfma_f32_16x16x32_bf16 v[30:33], v[86:89], v[66:69], v[30:33]
	v_mfma_f32_16x16x32_bf16 v[38:41], v[208:211], v[66:69], v[38:41]
	v_mfma_f32_16x16x32_bf16 v[42:45], v[212:215], v[66:69], v[42:45]
	ds_read_b128 v[66:69], v119 offset:0
	s_waitcnt lgkmcnt(7)
	v_mfma_f32_16x16x32_bf16 v[46:49], v[82:85], v[70:73], v[46:49]
	v_mfma_f32_16x16x32_bf16 v[26:29], v[86:89], v[70:73], v[26:29]
	v_mfma_f32_16x16x32_bf16 v[14:17], v[208:211], v[70:73], v[14:17]
	v_mfma_f32_16x16x32_bf16 v[10:13], v[212:215], v[70:73], v[10:13]
	ds_read_b128 v[70:73], v119 offset:2048
	s_waitcnt lgkmcnt(7)
	v_mfma_f32_16x16x32_bf16 v[34:37], v[82:85], v[74:77], v[34:37]
	v_mfma_f32_16x16x32_bf16 v[22:25], v[86:89], v[74:77], v[22:25]
	v_mfma_f32_16x16x32_bf16 v[18:21], v[208:211], v[74:77], v[18:21]
	v_mfma_f32_16x16x32_bf16 v[62:65], v[212:215], v[74:77], v[62:65]
	ds_read_b128 v[74:77], v119 offset:4096
	s_waitcnt lgkmcnt(7)
	v_mfma_f32_16x16x32_bf16 v[58:61], v[82:85], v[78:81], v[58:61]
	v_mfma_f32_16x16x32_bf16 v[54:57], v[86:89], v[78:81], v[54:57]
	v_mfma_f32_16x16x32_bf16 v[50:53], v[208:211], v[78:81], v[50:53]
	v_mfma_f32_16x16x32_bf16 v[2:5], v[212:215], v[78:81], v[2:5]
	ds_read_b128 v[78:81], v119 offset:6144
	s_waitcnt lgkmcnt(3)
	v_mfma_f32_16x16x32_bf16 v[6:9], v[216:219], v[66:69], v[6:9]
	v_mfma_f32_16x16x32_bf16 v[30:33], v[220:223], v[66:69], v[30:33]
	v_mfma_f32_16x16x32_bf16 v[38:41], v[224:227], v[66:69], v[38:41]
	v_mfma_f32_16x16x32_bf16 v[42:45], v[228:231], v[66:69], v[42:45]
	s_waitcnt lgkmcnt(2)
	v_mfma_f32_16x16x32_bf16 v[46:49], v[216:219], v[70:73], v[46:49]
	v_mfma_f32_16x16x32_bf16 v[26:29], v[220:223], v[70:73], v[26:29]
	v_mfma_f32_16x16x32_bf16 v[14:17], v[224:227], v[70:73], v[14:17]
	v_mfma_f32_16x16x32_bf16 v[10:13], v[228:231], v[70:73], v[10:13]
	s_waitcnt vmcnt(0)
	s_waitcnt lgkmcnt(0)
	s_barrier
	ds_read_b128 v[82:85], v90 offset:16384
	ds_read_b128 v[86:89], v90 offset:18432
	ds_read_b128 v[208:211], v90 offset:20480
	ds_read_b128 v[212:215], v90 offset:22528
	ds_read_b128 v[66:69], v207 offset:32768
	ds_read_b128 v[70:73], v207 offset:34816
	v_mfma_f32_16x16x32_bf16 v[34:37], v[216:219], v[74:77], v[34:37]
	v_mfma_f32_16x16x32_bf16 v[22:25], v[220:223], v[74:77], v[22:25]
	v_mfma_f32_16x16x32_bf16 v[18:21], v[224:227], v[74:77], v[18:21]
	v_mfma_f32_16x16x32_bf16 v[62:65], v[228:231], v[74:77], v[62:65]
	ds_read_b128 v[74:77], v207 offset:36864
	v_mfma_f32_16x16x32_bf16 v[58:61], v[216:219], v[78:81], v[58:61]
	v_mfma_f32_16x16x32_bf16 v[54:57], v[220:223], v[78:81], v[54:57]
	v_mfma_f32_16x16x32_bf16 v[50:53], v[224:227], v[78:81], v[50:53]
	v_mfma_f32_16x16x32_bf16 v[2:5], v[228:231], v[78:81], v[2:5]
	ds_read_b128 v[78:81], v207 offset:38912
	ds_read_b128 v[216:219], v91 offset:16384
	ds_read_b128 v[220:223], v91 offset:18432
	ds_read_b128 v[224:227], v91 offset:20480
	ds_read_b128 v[228:231], v91 offset:22528
	s_waitcnt lgkmcnt(7)
	v_mfma_f32_16x16x32_bf16 v[6:9], v[82:85], v[66:69], v[6:9]
	v_mfma_f32_16x16x32_bf16 v[30:33], v[86:89], v[66:69], v[30:33]
	v_mfma_f32_16x16x32_bf16 v[38:41], v[208:211], v[66:69], v[38:41]
	v_mfma_f32_16x16x32_bf16 v[42:45], v[212:215], v[66:69], v[42:45]
	ds_read_b128 v[66:69], v119 offset:32768
	s_waitcnt lgkmcnt(7)
	v_mfma_f32_16x16x32_bf16 v[46:49], v[82:85], v[70:73], v[46:49]
	v_mfma_f32_16x16x32_bf16 v[26:29], v[86:89], v[70:73], v[26:29]
	v_mfma_f32_16x16x32_bf16 v[14:17], v[208:211], v[70:73], v[14:17]
	v_mfma_f32_16x16x32_bf16 v[10:13], v[212:215], v[70:73], v[10:13]
	ds_read_b128 v[70:73], v119 offset:34816
	s_waitcnt lgkmcnt(7)
	v_mfma_f32_16x16x32_bf16 v[34:37], v[82:85], v[74:77], v[34:37]
	v_mfma_f32_16x16x32_bf16 v[22:25], v[86:89], v[74:77], v[22:25]
	v_mfma_f32_16x16x32_bf16 v[18:21], v[208:211], v[74:77], v[18:21]
	v_mfma_f32_16x16x32_bf16 v[62:65], v[212:215], v[74:77], v[62:65]
	ds_read_b128 v[74:77], v119 offset:36864
	s_waitcnt lgkmcnt(7)
	v_mfma_f32_16x16x32_bf16 v[58:61], v[82:85], v[78:81], v[58:61]
	v_mfma_f32_16x16x32_bf16 v[54:57], v[86:89], v[78:81], v[54:57]
	v_mfma_f32_16x16x32_bf16 v[50:53], v[208:211], v[78:81], v[50:53]
	v_mfma_f32_16x16x32_bf16 v[2:5], v[212:215], v[78:81], v[2:5]
	ds_read_b128 v[78:81], v119 offset:38912
	s_waitcnt lgkmcnt(3)
	v_mfma_f32_16x16x32_bf16 v[6:9], v[216:219], v[66:69], v[6:9]
	s_waitcnt vmcnt(18)
	v_mfma_f32_16x16x32_bf16 v[30:33], v[220:223], v[66:69], v[30:33]
	v_mfma_f32_16x16x32_bf16 v[38:41], v[224:227], v[66:69], v[38:41]
	v_mfma_f32_16x16x32_bf16 v[42:45], v[228:231], v[66:69], v[42:45]
	v_cvt_f32_ubyte0_e32 v248, v232
	v_cvt_f32_ubyte1_e32 v249, v232
	v_cvt_f32_ubyte2_e32 v250, v232
	v_cvt_f32_ubyte3_e32 v251, v232
	v_mul_f32_e32 v248, s34, v248
	v_mul_f32_e32 v249, s34, v249
	v_mul_f32_e32 v250, s34, v250
	v_mul_f32_e32 v251, s34, v251
	v_fma_f32 v184, v6, v248, v184
	v_fma_f32 v185, v7, v249, v185
	v_fma_f32 v186, v8, v250, v186
	v_fma_f32 v187, v9, v251, v187
	s_waitcnt lgkmcnt(2)
	v_mfma_f32_16x16x32_bf16 v[46:49], v[216:219], v[70:73], v[46:49]
	v_cvt_f32_ubyte0_e32 v248, v233
	v_cvt_f32_ubyte1_e32 v249, v233
	v_cvt_f32_ubyte2_e32 v250, v233
	v_cvt_f32_ubyte3_e32 v251, v233
	v_mul_f32_e32 v248, s34, v248
	v_mul_f32_e32 v249, s34, v249
	v_mul_f32_e32 v250, s34, v250
	v_mul_f32_e32 v251, s34, v251
	v_fma_f32 v180, v30, v248, v180
	v_fma_f32 v181, v31, v249, v181
	v_fma_f32 v182, v32, v250, v182
	v_fma_f32 v183, v33, v251, v183
	v_mfma_f32_16x16x32_bf16 v[26:29], v[220:223], v[70:73], v[26:29]
	v_cvt_f32_ubyte0_e32 v248, v234
	v_cvt_f32_ubyte1_e32 v249, v234
	v_cvt_f32_ubyte2_e32 v250, v234
	v_cvt_f32_ubyte3_e32 v251, v234
	v_mul_f32_e32 v248, s34, v248
	v_mul_f32_e32 v249, s34, v249
	v_mul_f32_e32 v250, s34, v250
	v_mul_f32_e32 v251, s34, v251
	v_fma_f32 v176, v38, v248, v176
	v_fma_f32 v177, v39, v249, v177
	v_fma_f32 v178, v40, v250, v178
	v_fma_f32 v179, v41, v251, v179
	v_mfma_f32_16x16x32_bf16 v[14:17], v[224:227], v[70:73], v[14:17]
	v_cvt_f32_ubyte0_e32 v248, v235
	v_cvt_f32_ubyte1_e32 v249, v235
	v_cvt_f32_ubyte2_e32 v250, v235
	v_cvt_f32_ubyte3_e32 v251, v235
	v_mul_f32_e32 v248, s34, v248
	v_mul_f32_e32 v249, s34, v249
	v_mul_f32_e32 v250, s34, v250
	v_mul_f32_e32 v251, s34, v251
	v_fma_f32 v172, v42, v248, v172
	v_fma_f32 v173, v43, v249, v173
	v_fma_f32 v174, v44, v250, v174
	v_fma_f32 v175, v45, v251, v175
	v_mfma_f32_16x16x32_bf16 v[10:13], v[228:231], v[70:73], v[10:13]
	v_cvt_f32_ubyte0_e32 v248, v236
	v_cvt_f32_ubyte1_e32 v249, v236
	v_cvt_f32_ubyte2_e32 v250, v236
	v_cvt_f32_ubyte3_e32 v251, v236
	v_mul_f32_e32 v248, s34, v248
	v_mul_f32_e32 v249, s34, v249
	v_mul_f32_e32 v250, s34, v250
	v_mul_f32_e32 v251, s34, v251
	v_fma_f32 v168, v46, v248, v168
	v_fma_f32 v169, v47, v249, v169
	v_fma_f32 v170, v48, v250, v170
	v_fma_f32 v171, v49, v251, v171
	s_waitcnt lgkmcnt(0)
	s_barrier
	v_mfma_f32_16x16x32_bf16 v[34:37], v[216:219], v[74:77], v[34:37]
	v_cvt_f32_ubyte0_e32 v248, v237
	v_cvt_f32_ubyte1_e32 v249, v237
	v_cvt_f32_ubyte2_e32 v250, v237
	v_cvt_f32_ubyte3_e32 v251, v237
	v_mul_f32_e32 v248, s34, v248
	v_mul_f32_e32 v249, s34, v249
	v_mul_f32_e32 v250, s34, v250
	v_mul_f32_e32 v251, s34, v251
	v_fma_f32 v164, v26, v248, v164
	v_fma_f32 v165, v27, v249, v165
	v_fma_f32 v166, v28, v250, v166
	v_fma_f32 v167, v29, v251, v167
	v_mfma_f32_16x16x32_bf16 v[22:25], v[220:223], v[74:77], v[22:25]
	v_cvt_f32_ubyte0_e32 v248, v238
	v_cvt_f32_ubyte1_e32 v249, v238
	v_cvt_f32_ubyte2_e32 v250, v238
	v_cvt_f32_ubyte3_e32 v251, v238
	v_mul_f32_e32 v248, s34, v248
	v_mul_f32_e32 v249, s34, v249
	v_mul_f32_e32 v250, s34, v250
	v_mul_f32_e32 v251, s34, v251
	v_fma_f32 v160, v14, v248, v160
	v_fma_f32 v161, v15, v249, v161
	v_fma_f32 v162, v16, v250, v162
	v_fma_f32 v163, v17, v251, v163
	v_mfma_f32_16x16x32_bf16 v[18:21], v[224:227], v[74:77], v[18:21]
	v_cvt_f32_ubyte0_e32 v248, v239
	v_cvt_f32_ubyte1_e32 v249, v239
	v_cvt_f32_ubyte2_e32 v250, v239
	v_cvt_f32_ubyte3_e32 v251, v239
	v_mul_f32_e32 v248, s34, v248
	v_mul_f32_e32 v249, s34, v249
	v_mul_f32_e32 v250, s34, v250
	v_mul_f32_e32 v251, s34, v251
	v_fma_f32 v156, v10, v248, v156
	v_fma_f32 v157, v11, v249, v157
	v_fma_f32 v158, v12, v250, v158
	v_fma_f32 v159, v13, v251, v159
	v_mfma_f32_16x16x32_bf16 v[62:65], v[228:231], v[74:77], v[62:65]
	v_cvt_f32_ubyte0_e32 v248, v240
	v_cvt_f32_ubyte1_e32 v249, v240
	v_cvt_f32_ubyte2_e32 v250, v240
	v_cvt_f32_ubyte3_e32 v251, v240
	v_mul_f32_e32 v248, s34, v248
	v_mul_f32_e32 v249, s34, v249
	v_mul_f32_e32 v250, s34, v250
	v_mul_f32_e32 v251, s34, v251
	v_fma_f32 v136, v34, v248, v136
	v_fma_f32 v137, v35, v249, v137
	v_fma_f32 v150, v36, v250, v150
	v_fma_f32 v151, v37, v251, v151
	v_mfma_f32_16x16x32_bf16 v[58:61], v[216:219], v[78:81], v[58:61]
	v_cvt_f32_ubyte0_e32 v248, v241
	v_cvt_f32_ubyte1_e32 v249, v241
	v_cvt_f32_ubyte2_e32 v250, v241
	v_cvt_f32_ubyte3_e32 v251, v241
	v_mul_f32_e32 v248, s34, v248
	v_mul_f32_e32 v249, s34, v249
	v_mul_f32_e32 v250, s34, v250
	v_mul_f32_e32 v251, s34, v251
	v_fma_f32 v130, v22, v248, v130
	v_fma_f32 v131, v23, v249, v131
	v_fma_f32 v134, v24, v250, v134
	v_fma_f32 v135, v25, v251, v135
	v_mfma_f32_16x16x32_bf16 v[54:57], v[220:223], v[78:81], v[54:57]
	v_cvt_f32_ubyte0_e32 v248, v242
	v_cvt_f32_ubyte1_e32 v249, v242
	v_cvt_f32_ubyte2_e32 v250, v242
	v_cvt_f32_ubyte3_e32 v251, v242
	v_mul_f32_e32 v248, s34, v248
	v_mul_f32_e32 v249, s34, v249
	v_mul_f32_e32 v250, s34, v250
	v_mul_f32_e32 v251, s34, v251
	v_fma_f32 v124, v18, v248, v124
	v_fma_f32 v125, v19, v249, v125
	v_fma_f32 v126, v20, v250, v126
	v_fma_f32 v127, v21, v251, v127
	v_mfma_f32_16x16x32_bf16 v[50:53], v[224:227], v[78:81], v[50:53]
	v_cvt_f32_ubyte0_e32 v248, v243
	v_cvt_f32_ubyte1_e32 v249, v243
	v_cvt_f32_ubyte2_e32 v250, v243
	v_cvt_f32_ubyte3_e32 v251, v243
	v_mul_f32_e32 v248, s34, v248
	v_mul_f32_e32 v249, s34, v249
	v_mul_f32_e32 v250, s34, v250
	v_mul_f32_e32 v251, s34, v251
	v_fma_f32 v120, v62, v248, v120
	v_fma_f32 v121, v63, v249, v121
	v_fma_f32 v122, v64, v250, v122
	v_fma_f32 v123, v65, v251, v123
	v_mfma_f32_16x16x32_bf16 v[2:5], v[228:231], v[78:81], v[2:5]
	v_cvt_f32_ubyte0_e32 v248, v244
	v_cvt_f32_ubyte1_e32 v249, v244
	v_cvt_f32_ubyte2_e32 v250, v244
	v_cvt_f32_ubyte3_e32 v251, v244
	v_mul_f32_e32 v248, s34, v248
	v_mul_f32_e32 v249, s34, v249
	v_mul_f32_e32 v250, s34, v250
	v_mul_f32_e32 v251, s34, v251
	v_fma_f32 v114, v58, v248, v114
	v_fma_f32 v115, v59, v249, v115
	v_fma_f32 v116, v60, v250, v116
	v_fma_f32 v117, v61, v251, v117
	s_nop 7
	s_nop 3
	v_cvt_f32_ubyte0_e32 v248, v245
	v_cvt_f32_ubyte1_e32 v249, v245
	v_cvt_f32_ubyte2_e32 v250, v245
	v_cvt_f32_ubyte3_e32 v251, v245
	v_mul_f32_e32 v248, s34, v248
	v_mul_f32_e32 v249, s34, v249
	v_mul_f32_e32 v250, s34, v250
	v_mul_f32_e32 v251, s34, v251
	v_fma_f32 v106, v54, v248, v106
	v_fma_f32 v107, v55, v249, v107
	v_fma_f32 v108, v56, v250, v108
	v_fma_f32 v109, v57, v251, v109
	v_cvt_f32_ubyte0_e32 v248, v246
	v_cvt_f32_ubyte1_e32 v249, v246
	v_cvt_f32_ubyte2_e32 v250, v246
	v_cvt_f32_ubyte3_e32 v251, v246
	v_mul_f32_e32 v248, s34, v248
	v_mul_f32_e32 v249, s34, v249
	v_mul_f32_e32 v250, s34, v250
	v_mul_f32_e32 v251, s34, v251
	v_fma_f32 v100, v50, v248, v100
	v_fma_f32 v101, v51, v249, v101
	v_fma_f32 v102, v52, v250, v102
	v_fma_f32 v103, v53, v251, v103
	v_cvt_f32_ubyte0_e32 v248, v247
	v_cvt_f32_ubyte1_e32 v249, v247
	v_cvt_f32_ubyte2_e32 v250, v247
	v_cvt_f32_ubyte3_e32 v251, v247
	v_mul_f32_e32 v248, s34, v248
	v_mul_f32_e32 v249, s34, v249
	v_mul_f32_e32 v250, s34, v250
	v_mul_f32_e32 v251, s34, v251
	v_fma_f32 v96, v2, v248, v96
	v_fma_f32 v97, v3, v249, v97
	v_fma_f32 v98, v4, v250, v98
	v_fma_f32 v99, v5, v251, v99
	s_cmp_eq_u32 0, 0
	s_cbranch_scc0 .LBB0_1004
	v_lshlrev_b32_e32 v0, 1, v118
	v_lshl_add_u64 v[6:7], s[4:5], 0, v[0:1]
	v_lshlrev_b64 v[2:3], 11, v[112:113]
	v_lshl_add_u64 v[8:9], v[6:7], 0, v[2:3]
	v_cvt_pk_bf16_f32 v2, v184, v185
	v_cvt_pk_bf16_f32 v3, v186, v187
	v_cvt_pk_bf16_f32 v4, v180, v181
	v_cvt_pk_bf16_f32 v5, v182, v183
	global_store_dwordx4 v[8:9], v[2:5], off
	v_readlane_b32 s46, v254, 29
	s_mov_b32 s38, 0
	v_cvt_pk_bf16_f32 v2, v176, v177
	v_cvt_pk_bf16_f32 v3, v178, v179
	v_cvt_pk_bf16_f32 v4, v172, v173
	v_cvt_pk_bf16_f32 v5, v174, v175
	global_store_dwordx4 v[8:9], v[2:5], off offset:64
	v_readlane_b32 s47, v254, 30
	s_nop 0
	v_lshlrev_b64 v[2:3], 11, v[110:111]
	v_lshl_add_u64 v[8:9], v[6:7], 0, v[2:3]
	v_cvt_pk_bf16_f32 v2, v168, v169
	v_cvt_pk_bf16_f32 v3, v170, v171
	v_cvt_pk_bf16_f32 v4, v164, v165
	v_cvt_pk_bf16_f32 v5, v166, v167
	global_store_dwordx4 v[8:9], v[2:5], off
	s_nop 1
	v_cvt_pk_bf16_f32 v2, v160, v161
	v_cvt_pk_bf16_f32 v3, v162, v163
	v_cvt_pk_bf16_f32 v4, v156, v157
	v_cvt_pk_bf16_f32 v5, v158, v159
	global_store_dwordx4 v[8:9], v[2:5], off offset:64
	s_nop 1
	v_lshlrev_b64 v[2:3], 11, v[104:105]
	v_lshl_add_u64 v[8:9], v[6:7], 0, v[2:3]
	v_cvt_pk_bf16_f32 v2, v136, v137
	v_cvt_pk_bf16_f32 v3, v150, v151
	v_cvt_pk_bf16_f32 v4, v130, v131
	v_cvt_pk_bf16_f32 v5, v134, v135
	global_store_dwordx4 v[8:9], v[2:5], off
	s_nop 1
	v_cvt_pk_bf16_f32 v2, v124, v125
	v_cvt_pk_bf16_f32 v3, v126, v127
	v_cvt_pk_bf16_f32 v4, v120, v121
	v_cvt_pk_bf16_f32 v5, v122, v123
	global_store_dwordx4 v[8:9], v[2:5], off offset:64
	s_nop 1
	v_lshlrev_b64 v[2:3], 11, v[94:95]
	v_lshl_add_u64 v[6:7], v[6:7], 0, v[2:3]
	v_cvt_pk_bf16_f32 v2, v114, v115
	v_cvt_pk_bf16_f32 v3, v116, v117
	v_cvt_pk_bf16_f32 v4, v106, v107
	v_cvt_pk_bf16_f32 v5, v108, v109
	global_store_dwordx4 v[6:7], v[2:5], off
	s_nop 1
	v_cvt_pk_bf16_f32 v2, v100, v101
	v_cvt_pk_bf16_f32 v3, v102, v103
	v_cvt_pk_bf16_f32 v4, v96, v97
	v_cvt_pk_bf16_f32 v5, v98, v99
	global_store_dwordx4 v[6:7], v[2:5], off offset:64
